# SwiGLU epilogue rewritten with packed f32 + 8-wide interleave (same per-element arithmetic), dup lgkmcnt waits removed in K-loops, packed acc zeroing, retention gate loads batched
# speedup vs baseline: 1.0150x; 1.0150x over previous
; #define PG8_STAGE(bufoff, gbase, voff) do { _Pragma("unroll") for (int _i = 0; _i < 2; ++_i) \
;         __builtin_amdgcn_global_load_lds((const unsigned*)((const char*)(gbase) + (voff)[_i]), (LAS unsigned*)(lds + (bufoff) + ldsw + _i * 8192), 16, 0, 0); } while (0)
; #define PG8_LDA(dst, b, h) do { _Pragma("unroll") for (int m = 0; m < 4; ++m) _Pragma("unroll") for (int k = 0; k < 2; ++k) dst[m][k] = *(const LAS bf16x8*)(lds + PG8_SA(b, h) + aoff + m * 2048 + k * 1024); } while (0)
; #define PG8_LDB(dst, b, h) do { _Pragma("unroll") for (int n = 0; n < 2; ++n) _Pragma("unroll") for (int k = 0; k < 2; ++k) dst[n][k] = *(const LAS bf16x8*)(lds + PG8_SB(b, h) + boff + n * 2048 + k * 1024); } while (0)
; #define PG8_WAIT_L(n) asm volatile("s_waitcnt lgkmcnt(" #n ")" ::: "memory")
; #define PG8_BAR __builtin_amdgcn_s_barrier()
; #define PG8_SCHED __builtin_amdgcn_sched_barrier(0)
; template <class Epi, class Sched>
; __device__ __forceinline__ void gemm_phase(LAS unsigned char* lds, const Gemm g, const Sched& S, const Epi& E) {
;     ...
;         const bool has_next = S.next(ui + 1, nxt);
;         const char* nA = has_next ? (const char*)g.A + (size_t)nxt.pm * tstep : cA; const char* nB = has_next ? (const char*)g.Bt + (size_t)nxt.pn * tstep : cB;
;         for (int t = 0; t < nt; t += 2) {
;             const bool last = (t == nt - 2);
;             const char* a1 = cA + (size_t)(t + 1) * kstep;
;             const char* a2 = last ? nA : cA + (size_t)(t + 2) * kstep; const char* b2 = last ? nB : cB + (size_t)(t + 2) * kstep;
;             const char* a3 = a2 + kstep; const char* b3 = b2 + kstep;
;             PG8_LDB(B0, 0, 0); PG8_SCHED; PG8_LDA(At, 0, 0); PG8_STAGE(PG8_SA(1, 1), a1 + hstep, voffA);
;             PG8_WAIT_L(8); PG8_BAR; PG8_WAIT_L(0); PG8_MMA(0, 0, At, B0); PG8_BAR; PG8_SCHED;
;             PG8_LDB(B1, 0, 1); PG8_STAGE(PG8_SB(0, 0), b2, voffB);
;             PG8_BAR; PG8_WAIT_L(0); PG8_MMA(0, 1, At, B1); PG8_BAR;
;     ...
; #pragma unroll
;         for (int a = 0; a < 2; ++a)
; #pragma unroll
;             for (int b = 0; b < 2; ++b)
; #pragma unroll
;                 for (int m = 0; m < 4; ++m)
; #pragma unroll
;                     for (int n = 0; n < 2; ++n) acc[a][b][m][n] = (f32x4){0.f, 0.f, 0.f, 0.f};
.LBB0_296:
	v_mov_b64_e32 v[0:1], s[80:81]
	s_ashr_i32 s9, s8, 31
	v_cmp_lt_i64_e32 vcc, s[10:11], v[0:1]
	s_lshl_b64 s[10:11], s[8:9], 19
	s_add_u32 s10, s24, s10
	s_addc_u32 s11, s25, s11
	s_and_b64 s[12:13], vcc, exec
	s_cselect_b32 s9, s11, s19
	s_cselect_b32 s39, s10, s18
	s_ashr_i32 s7, s6, 31
	s_lshl_b64 s[12:13], s[6:7], 19
	s_add_u32 s12, s26, s12
	s_addc_u32 s13, s27, s13
	s_and_b64 s[20:21], vcc, exec
	s_cselect_b32 s7, s13, s17
	s_cselect_b32 s48, s12, s16
	s_add_u32 s49, s16, 0x100
	s_addc_u32 s50, s17, 0
	s_add_u32 s16, s18, 0x40080
	v_mov_b32_e32 v0, 0
	s_addc_u32 s17, s19, 0
	s_mov_b32 s51, -2
	v_mov_b32_e32 v1, v0
	v_pk_mov_b32 v[2:3], v[0:1], v[0:1]
	v_pk_mov_b32 v[4:5], v[0:1], v[0:1]
	v_pk_mov_b32 v[6:7], v[0:1], v[0:1]
	v_pk_mov_b32 v[8:9], v[0:1], v[0:1]
	v_pk_mov_b32 v[10:11], v[0:1], v[0:1]
	v_pk_mov_b32 v[12:13], v[0:1], v[0:1]
	v_pk_mov_b32 v[14:15], v[0:1], v[0:1]
	v_pk_mov_b32 v[16:17], v[0:1], v[0:1]
	v_pk_mov_b32 v[18:19], v[0:1], v[0:1]
	v_pk_mov_b32 v[20:21], v[0:1], v[0:1]
	v_pk_mov_b32 v[22:23], v[0:1], v[0:1]
	v_pk_mov_b32 v[24:25], v[0:1], v[0:1]
	v_pk_mov_b32 v[26:27], v[0:1], v[0:1]
	v_pk_mov_b32 v[28:29], v[0:1], v[0:1]
	v_pk_mov_b32 v[30:31], v[0:1], v[0:1]
	v_pk_mov_b32 v[32:33], v[0:1], v[0:1]
	v_pk_mov_b32 v[34:35], v[0:1], v[0:1]
	v_pk_mov_b32 v[36:37], v[0:1], v[0:1]
	v_pk_mov_b32 v[38:39], v[0:1], v[0:1]
	v_pk_mov_b32 v[40:41], v[0:1], v[0:1]
	v_pk_mov_b32 v[42:43], v[0:1], v[0:1]
	v_pk_mov_b32 v[44:45], v[0:1], v[0:1]
	v_pk_mov_b32 v[46:47], v[0:1], v[0:1]
	v_pk_mov_b32 v[48:49], v[0:1], v[0:1]
	v_pk_mov_b32 v[50:51], v[0:1], v[0:1]
	v_pk_mov_b32 v[52:53], v[0:1], v[0:1]
	v_pk_mov_b32 v[54:55], v[0:1], v[0:1]
	v_pk_mov_b32 v[56:57], v[0:1], v[0:1]
	v_pk_mov_b32 v[58:59], v[0:1], v[0:1]
	v_pk_mov_b32 v[60:61], v[0:1], v[0:1]
	v_pk_mov_b32 v[62:63], v[0:1], v[0:1]
	v_pk_mov_b32 v[64:65], v[0:1], v[0:1]
	v_pk_mov_b32 v[66:67], v[0:1], v[0:1]
	v_pk_mov_b32 v[68:69], v[0:1], v[0:1]
	v_pk_mov_b32 v[70:71], v[0:1], v[0:1]
	v_pk_mov_b32 v[72:73], v[0:1], v[0:1]
	v_pk_mov_b32 v[74:75], v[0:1], v[0:1]
	v_pk_mov_b32 v[76:77], v[0:1], v[0:1]
	v_pk_mov_b32 v[78:79], v[0:1], v[0:1]
	v_pk_mov_b32 v[80:81], v[0:1], v[0:1]
	v_pk_mov_b32 v[82:83], v[0:1], v[0:1]
	v_pk_mov_b32 v[84:85], v[0:1], v[0:1]
	v_pk_mov_b32 v[86:87], v[0:1], v[0:1]
	v_pk_mov_b32 v[88:89], v[0:1], v[0:1]
	v_pk_mov_b32 v[90:91], v[0:1], v[0:1]
	v_pk_mov_b32 v[92:93], v[0:1], v[0:1]
	v_pk_mov_b32 v[94:95], v[0:1], v[0:1]
	v_pk_mov_b32 v[96:97], v[0:1], v[0:1]
	v_pk_mov_b32 v[98:99], v[0:1], v[0:1]
	v_pk_mov_b32 v[100:101], v[0:1], v[0:1]
	v_pk_mov_b32 v[102:103], v[0:1], v[0:1]
	v_pk_mov_b32 v[104:105], v[0:1], v[0:1]
	v_pk_mov_b32 v[106:107], v[0:1], v[0:1]
	v_pk_mov_b32 v[108:109], v[0:1], v[0:1]
	v_pk_mov_b32 v[110:111], v[0:1], v[0:1]
	v_pk_mov_b32 v[112:113], v[0:1], v[0:1]
	v_pk_mov_b32 v[114:115], v[0:1], v[0:1]
	v_pk_mov_b32 v[116:117], v[0:1], v[0:1]
	v_pk_mov_b32 v[118:119], v[0:1], v[0:1]
	v_pk_mov_b32 v[120:121], v[0:1], v[0:1]
	v_pk_mov_b32 v[122:123], v[0:1], v[0:1]
	v_pk_mov_b32 v[124:125], v[0:1], v[0:1]
	v_pk_mov_b32 v[126:127], v[0:1], v[0:1]
.LBB0_297:
	s_add_u32 s18, s16, 0xfffc0080
	s_addc_u32 s19, s17, -1
	s_add_i32 s52, 0, 0x10000
	v_add_u32_e32 v138, s52, v141
	ds_read_b128 v[154:157], v138
	ds_read_b128 v[158:161], v138 offset:1024
	ds_read_b128 v[162:165], v138 offset:2048
	ds_read_b128 v[166:169], v138 offset:3072
	s_cmp_eq_u32 s51, 12
	s_cselect_b32 s21, s9, s19
	s_cselect_b32 s20, s39, s18
	s_cselect_b32 s19, s7, s50
	s_cselect_b32 s18, s48, s49
	v_lshl_add_u64 v[138:139], s[16:17], 0, v[136:137]
	s_add_i32 m0, s15, 0xc000
	ds_read_b128 v[170:173], v143
	ds_read_b128 v[174:177], v143 offset:1024
	ds_read_b128 v[178:181], v143 offset:2048
	ds_read_b128 v[182:185], v143 offset:3072
	ds_read_b128 v[208:211], v143 offset:4096
	ds_read_b128 v[212:215], v143 offset:5120
	ds_read_b128 v[216:219], v143 offset:6144
	ds_read_b128 v[220:223], v143 offset:7168
	global_load_lds_dwordx4 v[138:139], off
	v_lshl_add_u64 v[138:139], s[16:17], 0, v[134:135]
	s_add_i32 m0, s15, 0xe000
	s_nop 0
	global_load_lds_dwordx4 v[138:139], off
	s_waitcnt lgkmcnt(8)
	s_barrier
	s_waitcnt lgkmcnt(0)
	s_setprio 1
	v_mfma_f32_16x16x32_bf16 v[124:127], v[154:157], v[170:173], v[124:127]
	v_mfma_f32_16x16x32_bf16 v[116:119], v[162:165], v[170:173], v[116:119]
	v_mfma_f32_16x16x32_bf16 v[108:111], v[154:157], v[178:181], v[108:111]
	v_mfma_f32_16x16x32_bf16 v[100:103], v[162:165], v[178:181], v[100:103]
	v_mfma_f32_16x16x32_bf16 v[92:95], v[154:157], v[208:211], v[92:95]
	v_mfma_f32_16x16x32_bf16 v[84:87], v[162:165], v[208:211], v[84:87]
	v_mfma_f32_16x16x32_bf16 v[76:79], v[154:157], v[216:219], v[76:79]
	v_mfma_f32_16x16x32_bf16 v[68:71], v[162:165], v[216:219], v[68:71]
	v_mfma_f32_16x16x32_bf16 v[124:127], v[158:161], v[174:177], v[124:127]
	v_mfma_f32_16x16x32_bf16 v[116:119], v[166:169], v[174:177], v[116:119]
	v_mfma_f32_16x16x32_bf16 v[108:111], v[158:161], v[182:185], v[108:111]
	v_mfma_f32_16x16x32_bf16 v[100:103], v[166:169], v[182:185], v[100:103]
	v_mfma_f32_16x16x32_bf16 v[92:95], v[158:161], v[212:215], v[92:95]
	v_mfma_f32_16x16x32_bf16 v[84:87], v[166:169], v[212:215], v[84:87]
	v_mfma_f32_16x16x32_bf16 v[76:79], v[158:161], v[220:223], v[76:79]
	v_mfma_f32_16x16x32_bf16 v[68:71], v[166:169], v[220:223], v[68:71]
	s_setprio 0
	s_barrier
	s_add_i32 s62, 0, 0x14000
	v_add_u32_e32 v138, s62, v141
	s_add_i32 s52, s52, s28
	ds_read_b128 v[224:227], v138
	ds_read_b128 v[228:231], v138 offset:1024
	ds_read_b128 v[232:235], v138 offset:2048
	ds_read_b128 v[236:239], v138 offset:3072
	v_lshl_add_u64 v[138:139], s[18:19], 0, v[144:145]
	s_mov_b32 m0, s52
	v_lshl_add_u64 v[186:187], s[18:19], 0, v[128:129]
	global_load_lds_dwordx4 v[138:139], off
	s_add_i32 m0, s52, 0x2000
	s_nop 0
	global_load_lds_dwordx4 v[186:187], off
	s_barrier
; #define PG8_STAGE(bufoff, gbase, voff) do { _Pragma("unroll") for (int _i = 0; _i < 2; ++_i) \
;         __builtin_amdgcn_global_load_lds((const unsigned*)((const char*)(gbase) + (voff)[_i]), (LAS unsigned*)(lds + (bufoff) + ldsw + _i * 8192), 16, 0, 0); } while (0)
; #define PG8_LDA(dst, b, h) do { _Pragma("unroll") for (int m = 0; m < 4; ++m) _Pragma("unroll") for (int k = 0; k < 2; ++k) dst[m][k] = *(const LAS bf16x8*)(lds + PG8_SA(b, h) + aoff + m * 2048 + k * 1024); } while (0)
; #define PG8_LDB(dst, b, h) do { _Pragma("unroll") for (int n = 0; n < 2; ++n) _Pragma("unroll") for (int k = 0; k < 2; ++k) dst[n][k] = *(const LAS bf16x8*)(lds + PG8_SB(b, h) + boff + n * 2048 + k * 1024); } while (0)
; #define PG8_MMA(ai, bj, At, Bt) do { __builtin_amdgcn_s_setprio(1); _Pragma("unroll") for (int m = 0; m < 4; ++m) _Pragma("unroll") for (int n = 0; n < 2; ++n) _Pragma("unroll") for (int k = 0; k < 2; ++k) \
;         acc[ai][bj][m][n] = __builtin_amdgcn_mfma_f32_16x16x32_bf16(Bt[n][k], At[m][k], acc[ai][bj][m][n], 0, 0, 0); __builtin_amdgcn_s_setprio(0); } while (0)
; #define PG8_WAIT_V(n) asm volatile("s_waitcnt vmcnt(" #n ")" ::: "memory")
; #define PG8_WAIT_L(n) asm volatile("s_waitcnt lgkmcnt(" #n ")" ::: "memory")
; #define PG8_BAR __builtin_amdgcn_s_barrier()
; #define PG8_SCHED __builtin_amdgcn_sched_barrier(0)
; template <class Epi, class Sched>
; __device__ __forceinline__ void gemm_phase(LAS unsigned char* lds, const Gemm g, const Sched& S, const Epi& E) {
;     ...
;             PG8_BAR; PG8_WAIT_L(0); PG8_MMA(0, 1, At, B1); PG8_BAR;
;             PG8_LDA(At, 0, 1); PG8_STAGE(PG8_SA(0, 0), a2, voffA);
;             PG8_BAR; PG8_WAIT_L(0); PG8_MMA(1, 0, At, B0); PG8_BAR; PG8_SCHED;
;             PG8_STAGE(PG8_SB(0, 1), b2 + hstep, voffB);
;             PG8_WAIT_V(6); PG8_BAR; PG8_MMA(1, 1, At, B1); PG8_BAR;
;             PG8_LDB(B0, 1, 0); PG8_SCHED; PG8_LDA(At, 1, 0); PG8_STAGE(PG8_SA(0, 1), a2 + hstep, voffA);
;             PG8_WAIT_L(8); PG8_BAR; PG8_WAIT_L(0); PG8_MMA(0, 0, At, B0); PG8_BAR; PG8_SCHED;
	s_waitcnt lgkmcnt(0)
	s_setprio 1
	v_mfma_f32_16x16x32_bf16 v[120:123], v[224:227], v[170:173], v[120:123]
	v_mfma_f32_16x16x32_bf16 v[112:115], v[232:235], v[170:173], v[112:115]
	v_mfma_f32_16x16x32_bf16 v[104:107], v[224:227], v[178:181], v[104:107]
	v_mfma_f32_16x16x32_bf16 v[96:99], v[232:235], v[178:181], v[96:99]
	v_mfma_f32_16x16x32_bf16 v[88:91], v[224:227], v[208:211], v[88:91]
	v_mfma_f32_16x16x32_bf16 v[80:83], v[232:235], v[208:211], v[80:83]
	v_mfma_f32_16x16x32_bf16 v[72:75], v[224:227], v[216:219], v[72:75]
	v_mfma_f32_16x16x32_bf16 v[64:67], v[232:235], v[216:219], v[64:67]
	v_mfma_f32_16x16x32_bf16 v[120:123], v[228:231], v[174:177], v[120:123]
	v_mfma_f32_16x16x32_bf16 v[112:115], v[236:239], v[174:177], v[112:115]
	v_mfma_f32_16x16x32_bf16 v[104:107], v[228:231], v[182:185], v[104:107]
	v_mfma_f32_16x16x32_bf16 v[96:99], v[236:239], v[182:185], v[96:99]
	v_mfma_f32_16x16x32_bf16 v[88:91], v[228:231], v[212:215], v[88:91]
	v_mfma_f32_16x16x32_bf16 v[80:83], v[236:239], v[212:215], v[80:83]
	v_mfma_f32_16x16x32_bf16 v[72:75], v[228:231], v[220:223], v[72:75]
	v_mfma_f32_16x16x32_bf16 v[64:67], v[236:239], v[220:223], v[64:67]
	s_setprio 0
	s_mov_b32 m0, s15
	v_lshl_add_u64 v[240:241], s[20:21], 0, v[132:133]
	s_barrier
	ds_read_b128 v[170:173], v143 offset:16384
	ds_read_b128 v[174:177], v143 offset:17408
	ds_read_b128 v[178:181], v143 offset:18432
	ds_read_b128 v[182:185], v143 offset:19456
	ds_read_b128 v[208:211], v143 offset:20480
	ds_read_b128 v[212:215], v143 offset:21504
	ds_read_b128 v[216:219], v143 offset:22528
	ds_read_b128 v[220:223], v143 offset:23552
	global_load_lds_dwordx4 v[240:241], off
	v_lshl_add_u64 v[242:243], s[20:21], 0, v[130:131]
	s_mov_b32 m0, s31
	s_nop 0
	global_load_lds_dwordx4 v[242:243], off
	s_barrier
	s_waitcnt lgkmcnt(0)
	s_setprio 1
	v_mfma_f32_16x16x32_bf16 v[60:63], v[154:157], v[170:173], v[60:63]
	v_mfma_f32_16x16x32_bf16 v[52:55], v[162:165], v[170:173], v[52:55]
	v_mfma_f32_16x16x32_bf16 v[44:47], v[154:157], v[178:181], v[44:47]
	v_mfma_f32_16x16x32_bf16 v[36:39], v[162:165], v[178:181], v[36:39]
	v_mfma_f32_16x16x32_bf16 v[28:31], v[154:157], v[208:211], v[28:31]
	v_mfma_f32_16x16x32_bf16 v[20:23], v[162:165], v[208:211], v[20:23]
	v_mfma_f32_16x16x32_bf16 v[12:15], v[154:157], v[216:219], v[12:15]
	v_mfma_f32_16x16x32_bf16 v[4:7], v[162:165], v[216:219], v[4:7]
	v_mfma_f32_16x16x32_bf16 v[60:63], v[158:161], v[174:177], v[60:63]
	v_mfma_f32_16x16x32_bf16 v[52:55], v[166:169], v[174:177], v[52:55]
	v_mfma_f32_16x16x32_bf16 v[44:47], v[158:161], v[182:185], v[44:47]
	v_mfma_f32_16x16x32_bf16 v[36:39], v[166:169], v[182:185], v[36:39]
	v_mfma_f32_16x16x32_bf16 v[28:31], v[158:161], v[212:215], v[28:31]
	v_mfma_f32_16x16x32_bf16 v[20:23], v[166:169], v[212:215], v[20:23]
	v_mfma_f32_16x16x32_bf16 v[12:15], v[158:161], v[220:223], v[12:15]
	v_mfma_f32_16x16x32_bf16 v[4:7], v[166:169], v[220:223], v[4:7]
	s_setprio 0
	s_barrier
	s_add_u32 s52, s18, 0x40000
	s_addc_u32 s53, s19, 0
	s_add_i32 s62, s62, s28
	v_lshl_add_u64 v[154:155], s[52:53], 0, v[144:145]
	s_mov_b32 m0, s62
	s_nop 0
	global_load_lds_dwordx4 v[154:155], off
	v_lshl_add_u64 v[154:155], s[52:53], 0, v[128:129]
	s_add_i32 m0, s62, 0x2000
	s_nop 0
	global_load_lds_dwordx4 v[154:155], off
	s_waitcnt vmcnt(6)
	s_barrier
	s_setprio 1
	v_mfma_f32_16x16x32_bf16 v[56:59], v[224:227], v[170:173], v[56:59]
	v_mfma_f32_16x16x32_bf16 v[48:51], v[232:235], v[170:173], v[48:51]
	v_mfma_f32_16x16x32_bf16 v[40:43], v[224:227], v[178:181], v[40:43]
	v_mfma_f32_16x16x32_bf16 v[32:35], v[232:235], v[178:181], v[32:35]
	v_mfma_f32_16x16x32_bf16 v[24:27], v[224:227], v[208:211], v[24:27]
	v_mfma_f32_16x16x32_bf16 v[16:19], v[232:235], v[208:211], v[16:19]
	v_mfma_f32_16x16x32_bf16 v[8:11], v[224:227], v[216:219], v[8:11]
	v_mfma_f32_16x16x32_bf16 v[0:3], v[232:235], v[216:219], v[0:3]
	v_mfma_f32_16x16x32_bf16 v[56:59], v[228:231], v[174:177], v[56:59]
	v_mfma_f32_16x16x32_bf16 v[48:51], v[236:239], v[174:177], v[48:51]
	v_mfma_f32_16x16x32_bf16 v[40:43], v[228:231], v[182:185], v[40:43]
	v_mfma_f32_16x16x32_bf16 v[32:35], v[236:239], v[182:185], v[32:35]
	v_mfma_f32_16x16x32_bf16 v[24:27], v[228:231], v[212:215], v[24:27]
	v_mfma_f32_16x16x32_bf16 v[16:19], v[236:239], v[212:215], v[16:19]
	v_mfma_f32_16x16x32_bf16 v[8:11], v[228:231], v[220:223], v[8:11]
	v_mfma_f32_16x16x32_bf16 v[0:3], v[236:239], v[220:223], v[0:3]
	s_setprio 0
	s_add_i32 s52, 0, 0x18000
	v_add_u32_e32 v149, s52, v141
	s_barrier
	ds_read_b128 v[154:157], v149
	ds_read_b128 v[158:161], v149 offset:1024
	ds_read_b128 v[162:165], v149 offset:2048
	ds_read_b128 v[166:169], v149 offset:3072
	s_add_u32 s20, s20, 0x40000
	s_addc_u32 s21, s21, 0
	s_mov_b32 m0, s34
	v_lshl_add_u64 v[224:225], s[20:21], 0, v[132:133]
	ds_read_b128 v[170:173], v143 offset:32768
	ds_read_b128 v[174:177], v143 offset:33792
	ds_read_b128 v[178:181], v143 offset:34816
	ds_read_b128 v[182:185], v143 offset:35840
	ds_read_b128 v[208:211], v143 offset:36864
	ds_read_b128 v[212:215], v143 offset:37888
	ds_read_b128 v[216:219], v143 offset:38912
	ds_read_b128 v[220:223], v143 offset:39936
	global_load_lds_dwordx4 v[224:225], off
	v_lshl_add_u64 v[224:225], s[20:21], 0, v[130:131]
	s_mov_b32 m0, s35
	s_nop 0
	global_load_lds_dwordx4 v[224:225], off
	s_waitcnt lgkmcnt(8)
	s_barrier
; #define PG8_STAGE(bufoff, gbase, voff) do { _Pragma("unroll") for (int _i = 0; _i < 2; ++_i) \
;         __builtin_amdgcn_global_load_lds((const unsigned*)((const char*)(gbase) + (voff)[_i]), (LAS unsigned*)(lds + (bufoff) + ldsw + _i * 8192), 16, 0, 0); } while (0)
; #define PG8_LDA(dst, b, h) do { _Pragma("unroll") for (int m = 0; m < 4; ++m) _Pragma("unroll") for (int k = 0; k < 2; ++k) dst[m][k] = *(const LAS bf16x8*)(lds + PG8_SA(b, h) + aoff + m * 2048 + k * 1024); } while (0)
; #define PG8_LDB(dst, b, h) do { _Pragma("unroll") for (int n = 0; n < 2; ++n) _Pragma("unroll") for (int k = 0; k < 2; ++k) dst[n][k] = *(const LAS bf16x8*)(lds + PG8_SB(b, h) + boff + n * 2048 + k * 1024); } while (0)
; #define PG8_MMA(ai, bj, At, Bt) do { __builtin_amdgcn_s_setprio(1); _Pragma("unroll") for (int m = 0; m < 4; ++m) _Pragma("unroll") for (int n = 0; n < 2; ++n) _Pragma("unroll") for (int k = 0; k < 2; ++k) \
;         acc[ai][bj][m][n] = __builtin_amdgcn_mfma_f32_16x16x32_bf16(Bt[n][k], At[m][k], acc[ai][bj][m][n], 0, 0, 0); __builtin_amdgcn_s_setprio(0); } while (0)
; #define PG8_WAIT_V(n) asm volatile("s_waitcnt vmcnt(" #n ")" ::: "memory")
; #define PG8_WAIT_L(n) asm volatile("s_waitcnt lgkmcnt(" #n ")" ::: "memory")
; #define PG8_BAR __builtin_amdgcn_s_barrier()
; #define PG8_SCHED __builtin_amdgcn_sched_barrier(0)
; template <class Epi, class Sched>
; __device__ __forceinline__ void gemm_phase(LAS unsigned char* lds, const Gemm g, const Sched& S, const Epi& E) {
;     ...
;             PG8_WAIT_L(8); PG8_BAR; PG8_WAIT_L(0); PG8_MMA(0, 0, At, B0); PG8_BAR; PG8_SCHED;
;             PG8_LDB(B1, 1, 1); PG8_STAGE(PG8_SB(1, 0), b3, voffB);
;             PG8_BAR; PG8_WAIT_L(0); PG8_MMA(0, 1, At, B1); PG8_BAR;
;             PG8_LDA(At, 1, 1); PG8_STAGE(PG8_SA(1, 0), a3, voffA);
;             PG8_BAR; PG8_WAIT_L(0); PG8_MMA(1, 0, At, B0); PG8_BAR; PG8_SCHED;
;             PG8_STAGE(PG8_SB(1, 1), b3 + hstep, voffB);
;             PG8_WAIT_V(6); PG8_BAR; PG8_MMA(1, 1, At, B1); PG8_BAR;
	s_waitcnt lgkmcnt(0)
	s_setprio 1
	v_mfma_f32_16x16x32_bf16 v[124:127], v[154:157], v[170:173], v[124:127]
	v_mfma_f32_16x16x32_bf16 v[116:119], v[162:165], v[170:173], v[116:119]
	v_mfma_f32_16x16x32_bf16 v[108:111], v[154:157], v[178:181], v[108:111]
	v_mfma_f32_16x16x32_bf16 v[100:103], v[162:165], v[178:181], v[100:103]
	v_mfma_f32_16x16x32_bf16 v[92:95], v[154:157], v[208:211], v[92:95]
	v_mfma_f32_16x16x32_bf16 v[84:87], v[162:165], v[208:211], v[84:87]
	v_mfma_f32_16x16x32_bf16 v[76:79], v[154:157], v[216:219], v[76:79]
	v_mfma_f32_16x16x32_bf16 v[68:71], v[162:165], v[216:219], v[68:71]
	v_mfma_f32_16x16x32_bf16 v[124:127], v[158:161], v[174:177], v[124:127]
	v_mfma_f32_16x16x32_bf16 v[116:119], v[166:169], v[174:177], v[116:119]
	v_mfma_f32_16x16x32_bf16 v[108:111], v[158:161], v[182:185], v[108:111]
	v_mfma_f32_16x16x32_bf16 v[100:103], v[166:169], v[182:185], v[100:103]
	v_mfma_f32_16x16x32_bf16 v[92:95], v[158:161], v[212:215], v[92:95]
	v_mfma_f32_16x16x32_bf16 v[84:87], v[166:169], v[212:215], v[84:87]
	v_mfma_f32_16x16x32_bf16 v[76:79], v[158:161], v[220:223], v[76:79]
	v_mfma_f32_16x16x32_bf16 v[68:71], v[166:169], v[220:223], v[68:71]
	s_setprio 0
	s_barrier
	s_add_i32 s20, 0, 0x1c000
	s_add_i32 s21, s52, s28
	v_add_u32_e32 v149, s20, v141
	v_lshl_add_u64 v[138:139], v[138:139], 0, s[82:83]
	s_mov_b32 m0, s21
	ds_read_b128 v[224:227], v149
	ds_read_b128 v[228:231], v149 offset:1024
	ds_read_b128 v[232:235], v149 offset:2048
	ds_read_b128 v[236:239], v149 offset:3072
	global_load_lds_dwordx4 v[138:139], off
	v_lshl_add_u64 v[138:139], v[186:187], 0, s[82:83]
	s_add_i32 m0, s21, 0x2000
	s_nop 0
	global_load_lds_dwordx4 v[138:139], off
	s_barrier
	s_waitcnt lgkmcnt(0)
	s_setprio 1
	v_mfma_f32_16x16x32_bf16 v[120:123], v[224:227], v[170:173], v[120:123]
	v_mfma_f32_16x16x32_bf16 v[112:115], v[232:235], v[170:173], v[112:115]
	v_mfma_f32_16x16x32_bf16 v[104:107], v[224:227], v[178:181], v[104:107]
	v_mfma_f32_16x16x32_bf16 v[96:99], v[232:235], v[178:181], v[96:99]
	v_mfma_f32_16x16x32_bf16 v[88:91], v[224:227], v[208:211], v[88:91]
	v_mfma_f32_16x16x32_bf16 v[80:83], v[232:235], v[208:211], v[80:83]
	v_mfma_f32_16x16x32_bf16 v[72:75], v[224:227], v[216:219], v[72:75]
	v_mfma_f32_16x16x32_bf16 v[64:67], v[232:235], v[216:219], v[64:67]
	v_mfma_f32_16x16x32_bf16 v[120:123], v[228:231], v[174:177], v[120:123]
	v_mfma_f32_16x16x32_bf16 v[112:115], v[236:239], v[174:177], v[112:115]
	v_mfma_f32_16x16x32_bf16 v[104:107], v[228:231], v[182:185], v[104:107]
	v_mfma_f32_16x16x32_bf16 v[96:99], v[236:239], v[182:185], v[96:99]
	v_mfma_f32_16x16x32_bf16 v[88:91], v[228:231], v[212:215], v[88:91]
	v_mfma_f32_16x16x32_bf16 v[80:83], v[236:239], v[212:215], v[80:83]
	v_mfma_f32_16x16x32_bf16 v[72:75], v[228:231], v[220:223], v[72:75]
	v_mfma_f32_16x16x32_bf16 v[64:67], v[236:239], v[220:223], v[64:67]
	s_setprio 0
	s_mov_b32 m0, s36
	v_lshl_add_u64 v[138:139], v[240:241], 0, s[82:83]
	s_barrier
	ds_read_b128 v[170:173], v143 offset:49152
	ds_read_b128 v[174:177], v143 offset:50176
	ds_read_b128 v[178:181], v143 offset:51200
	ds_read_b128 v[182:185], v143 offset:52224
	ds_read_b128 v[208:211], v143 offset:53248
	ds_read_b128 v[212:215], v143 offset:54272
	ds_read_b128 v[216:219], v143 offset:55296
	ds_read_b128 v[220:223], v143 offset:56320
	global_load_lds_dwordx4 v[138:139], off
	v_lshl_add_u64 v[138:139], v[242:243], 0, s[82:83]
	s_mov_b32 m0, s37
	s_nop 0
	global_load_lds_dwordx4 v[138:139], off
	s_barrier
	s_waitcnt lgkmcnt(0)
	s_setprio 1
	v_mfma_f32_16x16x32_bf16 v[60:63], v[154:157], v[170:173], v[60:63]
	v_mfma_f32_16x16x32_bf16 v[52:55], v[162:165], v[170:173], v[52:55]
	v_mfma_f32_16x16x32_bf16 v[44:47], v[154:157], v[178:181], v[44:47]
	v_mfma_f32_16x16x32_bf16 v[36:39], v[162:165], v[178:181], v[36:39]
	v_mfma_f32_16x16x32_bf16 v[28:31], v[154:157], v[208:211], v[28:31]
	v_mfma_f32_16x16x32_bf16 v[20:23], v[162:165], v[208:211], v[20:23]
	v_mfma_f32_16x16x32_bf16 v[12:15], v[154:157], v[216:219], v[12:15]
	v_mfma_f32_16x16x32_bf16 v[4:7], v[162:165], v[216:219], v[4:7]
	v_mfma_f32_16x16x32_bf16 v[60:63], v[158:161], v[174:177], v[60:63]
	v_mfma_f32_16x16x32_bf16 v[52:55], v[166:169], v[174:177], v[52:55]
	v_mfma_f32_16x16x32_bf16 v[44:47], v[158:161], v[182:185], v[44:47]
	v_mfma_f32_16x16x32_bf16 v[36:39], v[166:169], v[182:185], v[36:39]
	v_mfma_f32_16x16x32_bf16 v[28:31], v[158:161], v[212:215], v[28:31]
	v_mfma_f32_16x16x32_bf16 v[20:23], v[166:169], v[212:215], v[20:23]
	v_mfma_f32_16x16x32_bf16 v[12:15], v[158:161], v[220:223], v[12:15]
	v_mfma_f32_16x16x32_bf16 v[4:7], v[166:169], v[220:223], v[4:7]
	s_setprio 0
	s_barrier
	s_add_u32 s18, s18, 0x40080
	s_addc_u32 s19, s19, 0
	s_add_i32 s20, s20, s28
	v_lshl_add_u64 v[138:139], s[18:19], 0, v[144:145]
	s_mov_b32 m0, s20
	s_nop 0
	global_load_lds_dwordx4 v[138:139], off
	v_lshl_add_u64 v[138:139], s[18:19], 0, v[128:129]
	s_add_i32 m0, s20, 0x2000
	s_nop 0
	global_load_lds_dwordx4 v[138:139], off
	s_waitcnt vmcnt(6)
	s_barrier
	s_setprio 1
	v_mfma_f32_16x16x32_bf16 v[56:59], v[224:227], v[170:173], v[56:59]
	v_mfma_f32_16x16x32_bf16 v[48:51], v[232:235], v[170:173], v[48:51]
	v_mfma_f32_16x16x32_bf16 v[40:43], v[224:227], v[178:181], v[40:43]
	v_mfma_f32_16x16x32_bf16 v[32:35], v[232:235], v[178:181], v[32:35]
	v_mfma_f32_16x16x32_bf16 v[24:27], v[224:227], v[208:211], v[24:27]
	v_mfma_f32_16x16x32_bf16 v[16:19], v[232:235], v[208:211], v[16:19]
	v_mfma_f32_16x16x32_bf16 v[8:11], v[224:227], v[216:219], v[8:11]
	v_mfma_f32_16x16x32_bf16 v[0:3], v[232:235], v[216:219], v[0:3]
	v_mfma_f32_16x16x32_bf16 v[56:59], v[228:231], v[174:177], v[56:59]
	v_mfma_f32_16x16x32_bf16 v[48:51], v[236:239], v[174:177], v[48:51]
	v_mfma_f32_16x16x32_bf16 v[40:43], v[228:231], v[182:185], v[40:43]
	v_mfma_f32_16x16x32_bf16 v[32:35], v[236:239], v[182:185], v[32:35]
	v_mfma_f32_16x16x32_bf16 v[24:27], v[228:231], v[212:215], v[24:27]
	v_mfma_f32_16x16x32_bf16 v[16:19], v[236:239], v[212:215], v[16:19]
	v_mfma_f32_16x16x32_bf16 v[8:11], v[228:231], v[220:223], v[8:11]
	v_mfma_f32_16x16x32_bf16 v[0:3], v[236:239], v[220:223], v[0:3]
	s_setprio 0
	s_add_i32 s51, s51, 2
	s_add_u32 s49, s49, 0x100
	s_addc_u32 s50, s50, 0
	s_add_u32 s16, s16, 0x100
	s_addc_u32 s17, s17, 0
	s_cmp_gt_u32 s51, 13
	s_barrier
; __device__ __forceinline__ float silu_f(float x) { return x * __builtin_amdgcn_rcpf(1.0f + __expf(-x)); }
; __device__ __forceinline__ unsigned cvt_pk_bf16(float lo, float hi) { unsigned r; asm volatile("v_cvt_pk_bf16_f32 %0, %1, %2" : "=v"(r) : "v"(lo), "v"(hi)); return r; }
;     __device__ __forceinline__ void operator()(const f32x4 (&acc)[2][2][4][2], const Unit& u, int wr, int wc, int fr, int fq) const {
;         const int row0 = u.pm * BM + wr * 64 + fr; const int col0 = u.pn * HALF + wc * 32 + 8 * fq;
; #pragma unroll
;         for (int ai = 0; ai < 2; ++ai)
; #pragma unroll
;             for (int m = 0; m < 4; ++m) { bf16_t* rowp = O + (size_t)(row0 + ai * HALF + m * 16) * ldc + col0;
;                 float v[8];
; #pragma unroll
;                 for (int n = 0; n < 2; ++n)
; #pragma unroll
;                     for (int j = 0; j < 4; ++j) { const float g = acc[ai][0][m][n][j], up = acc[ai][1][m][n][j]; v[n * 4 + j] = silu_f(g) * up; }
;                 u32x4 w; w.x = cvt_pk_bf16(v[0], v[1]); w.y = cvt_pk_bf16(v[2], v[3]); w.z = cvt_pk_bf16(v[4], v[5]); w.w = cvt_pk_bf16(v[6], v[7]);
;                 *(u32x4*)rowp = w; }
	s_cbranch_scc0 .LBB0_297
	v_lshl_or_b32 v154, s33, 7, v142
	v_lshl_add_u32 v149, s14, 8, v140
	v_ashrrev_i32_e32 v155, 31, v154
	v_mov_b64_e32 v[138:139], s[4:5]
	v_lshlrev_b64 v[176:177], 1, v[154:155]
	v_lshl_add_u64 v[178:179], v[138:139], 0, v[176:177]
	v_mov_b32_e32 v172, 0xbfb8aa3b
	v_mov_b32_e32 v174, 1.0
	s_and_b64 vcc, exec, s[0:1]
	v_pk_mul_f32 v[160:161], v[124:125], v[172:173] op_sel_hi:[1,0]
	v_pk_mul_f32 v[162:163], v[126:127], v[172:173] op_sel_hi:[1,0]
	v_pk_mul_f32 v[164:165], v[116:117], v[172:173] op_sel_hi:[1,0]
	v_pk_mul_f32 v[166:167], v[118:119], v[172:173] op_sel_hi:[1,0]
	v_exp_f32_e32 v160, v160
	v_exp_f32_e32 v161, v161
	v_exp_f32_e32 v162, v162
	v_exp_f32_e32 v163, v163
	v_exp_f32_e32 v164, v164
	v_exp_f32_e32 v165, v165
	v_exp_f32_e32 v166, v166
	v_exp_f32_e32 v167, v167
	v_pk_add_f32 v[160:161], v[160:161], v[174:175] op_sel_hi:[1,0]
	v_pk_add_f32 v[162:163], v[162:163], v[174:175] op_sel_hi:[1,0]
	v_pk_add_f32 v[164:165], v[164:165], v[174:175] op_sel_hi:[1,0]
	v_pk_add_f32 v[166:167], v[166:167], v[174:175] op_sel_hi:[1,0]
	v_rcp_f32_e32 v160, v160
	v_rcp_f32_e32 v161, v161
	v_rcp_f32_e32 v162, v162
	v_rcp_f32_e32 v163, v163
	v_rcp_f32_e32 v164, v164
	v_rcp_f32_e32 v165, v165
	v_rcp_f32_e32 v166, v166
	v_rcp_f32_e32 v167, v167
	v_pk_mul_f32 v[160:161], v[124:125], v[160:161]
	v_pk_mul_f32 v[162:163], v[126:127], v[162:163]
	v_pk_mul_f32 v[164:165], v[116:117], v[164:165]
	v_pk_mul_f32 v[166:167], v[118:119], v[166:167]
	v_pk_mul_f32 v[160:161], v[160:161], v[120:121]
	v_pk_mul_f32 v[162:163], v[162:163], v[122:123]
	v_pk_mul_f32 v[164:165], v[164:165], v[112:113]
	v_pk_mul_f32 v[166:167], v[166:167], v[114:115]
	v_mov_b32_e32 v180, v149
	v_mad_i64_i32 v[182:183], s[16:17], v180, s54, v[178:179]
	v_cvt_pk_bf16_f32 v168, v160, v161
	v_cvt_pk_bf16_f32 v169, v162, v163
	v_cvt_pk_bf16_f32 v170, v164, v165
	v_cvt_pk_bf16_f32 v171, v166, v167
	global_store_dwordx4 v[182:183], v[168:171], off
	v_pk_mul_f32 v[160:161], v[108:109], v[172:173] op_sel_hi:[1,0]
	v_pk_mul_f32 v[162:163], v[110:111], v[172:173] op_sel_hi:[1,0]
	v_pk_mul_f32 v[164:165], v[100:101], v[172:173] op_sel_hi:[1,0]
	v_pk_mul_f32 v[166:167], v[102:103], v[172:173] op_sel_hi:[1,0]
	v_exp_f32_e32 v160, v160
	v_exp_f32_e32 v161, v161
	v_exp_f32_e32 v162, v162
	v_exp_f32_e32 v163, v163
	v_exp_f32_e32 v164, v164
	v_exp_f32_e32 v165, v165
	v_exp_f32_e32 v166, v166
	v_exp_f32_e32 v167, v167
	v_pk_add_f32 v[160:161], v[160:161], v[174:175] op_sel_hi:[1,0]
	v_pk_add_f32 v[162:163], v[162:163], v[174:175] op_sel_hi:[1,0]
	v_pk_add_f32 v[164:165], v[164:165], v[174:175] op_sel_hi:[1,0]
	v_pk_add_f32 v[166:167], v[166:167], v[174:175] op_sel_hi:[1,0]
	v_rcp_f32_e32 v160, v160
	v_rcp_f32_e32 v161, v161
	v_rcp_f32_e32 v162, v162
	v_rcp_f32_e32 v163, v163
	v_rcp_f32_e32 v164, v164
	v_rcp_f32_e32 v165, v165
	v_rcp_f32_e32 v166, v166
	v_rcp_f32_e32 v167, v167
	v_pk_mul_f32 v[160:161], v[108:109], v[160:161]
	v_pk_mul_f32 v[162:163], v[110:111], v[162:163]
	v_pk_mul_f32 v[164:165], v[100:101], v[164:165]
	v_pk_mul_f32 v[166:167], v[102:103], v[166:167]
	v_pk_mul_f32 v[160:161], v[160:161], v[104:105]
	v_pk_mul_f32 v[162:163], v[162:163], v[106:107]
	v_pk_mul_f32 v[164:165], v[164:165], v[96:97]
	v_pk_mul_f32 v[166:167], v[166:167], v[98:99]
	v_add_u32_e32 v180, 16, v149
	v_mad_i64_i32 v[182:183], s[16:17], v180, s54, v[178:179]
	v_cvt_pk_bf16_f32 v168, v160, v161
	v_cvt_pk_bf16_f32 v169, v162, v163
	v_cvt_pk_bf16_f32 v170, v164, v165
	v_cvt_pk_bf16_f32 v171, v166, v167
	global_store_dwordx4 v[182:183], v[168:171], off
	v_pk_mul_f32 v[160:161], v[92:93], v[172:173] op_sel_hi:[1,0]
	v_pk_mul_f32 v[162:163], v[94:95], v[172:173] op_sel_hi:[1,0]
	v_pk_mul_f32 v[164:165], v[84:85], v[172:173] op_sel_hi:[1,0]
	v_pk_mul_f32 v[166:167], v[86:87], v[172:173] op_sel_hi:[1,0]
	v_exp_f32_e32 v160, v160
	v_exp_f32_e32 v161, v161
	v_exp_f32_e32 v162, v162
	v_exp_f32_e32 v163, v163
	v_exp_f32_e32 v164, v164
	v_exp_f32_e32 v165, v165
	v_exp_f32_e32 v166, v166
	v_exp_f32_e32 v167, v167
	v_pk_add_f32 v[160:161], v[160:161], v[174:175] op_sel_hi:[1,0]
	v_pk_add_f32 v[162:163], v[162:163], v[174:175] op_sel_hi:[1,0]
	v_pk_add_f32 v[164:165], v[164:165], v[174:175] op_sel_hi:[1,0]
	v_pk_add_f32 v[166:167], v[166:167], v[174:175] op_sel_hi:[1,0]
	v_rcp_f32_e32 v160, v160
	v_rcp_f32_e32 v161, v161
	v_rcp_f32_e32 v162, v162
	v_rcp_f32_e32 v163, v163
	v_rcp_f32_e32 v164, v164
	v_rcp_f32_e32 v165, v165
	v_rcp_f32_e32 v166, v166
	v_rcp_f32_e32 v167, v167
	v_pk_mul_f32 v[160:161], v[92:93], v[160:161]
	v_pk_mul_f32 v[162:163], v[94:95], v[162:163]
	v_pk_mul_f32 v[164:165], v[84:85], v[164:165]
	v_pk_mul_f32 v[166:167], v[86:87], v[166:167]
	v_pk_mul_f32 v[160:161], v[160:161], v[88:89]
	v_pk_mul_f32 v[162:163], v[162:163], v[90:91]
	v_pk_mul_f32 v[164:165], v[164:165], v[80:81]
	v_pk_mul_f32 v[166:167], v[166:167], v[82:83]
	v_add_u32_e32 v180, 32, v149
	v_mad_i64_i32 v[182:183], s[16:17], v180, s54, v[178:179]
	v_cvt_pk_bf16_f32 v168, v160, v161
	v_cvt_pk_bf16_f32 v169, v162, v163
	v_cvt_pk_bf16_f32 v170, v164, v165
	v_cvt_pk_bf16_f32 v171, v166, v167
	global_store_dwordx4 v[182:183], v[168:171], off
	v_pk_mul_f32 v[160:161], v[76:77], v[172:173] op_sel_hi:[1,0]
	v_pk_mul_f32 v[162:163], v[78:79], v[172:173] op_sel_hi:[1,0]
	v_pk_mul_f32 v[164:165], v[68:69], v[172:173] op_sel_hi:[1,0]
	v_pk_mul_f32 v[166:167], v[70:71], v[172:173] op_sel_hi:[1,0]
	v_exp_f32_e32 v160, v160
	v_exp_f32_e32 v161, v161
	v_exp_f32_e32 v162, v162
	v_exp_f32_e32 v163, v163
	v_exp_f32_e32 v164, v164
	v_exp_f32_e32 v165, v165
	v_exp_f32_e32 v166, v166
	v_exp_f32_e32 v167, v167
	v_pk_add_f32 v[160:161], v[160:161], v[174:175] op_sel_hi:[1,0]
; __device__ __forceinline__ float silu_f(float x) { return x * __builtin_amdgcn_rcpf(1.0f + __expf(-x)); }
; __device__ __forceinline__ unsigned cvt_pk_bf16(float lo, float hi) { unsigned r; asm volatile("v_cvt_pk_bf16_f32 %0, %1, %2" : "=v"(r) : "v"(lo), "v"(hi)); return r; }
;     __device__ __forceinline__ void operator()(const f32x4 (&acc)[2][2][4][2], const Unit& u, int wr, int wc, int fr, int fq) const {
;     ...
;         for (int ai = 0; ai < 2; ++ai)
; #pragma unroll
;             for (int m = 0; m < 4; ++m) { bf16_t* rowp = O + (size_t)(row0 + ai * HALF + m * 16) * ldc + col0;
;                 float v[8];
; #pragma unroll
;                 for (int n = 0; n < 2; ++n)
; #pragma unroll
;                     for (int j = 0; j < 4; ++j) { const float g = acc[ai][0][m][n][j], up = acc[ai][1][m][n][j]; v[n * 4 + j] = silu_f(g) * up; }
;                 u32x4 w; w.x = cvt_pk_bf16(v[0], v[1]); w.y = cvt_pk_bf16(v[2], v[3]); w.z = cvt_pk_bf16(v[4], v[5]); w.w = cvt_pk_bf16(v[6], v[7]);
;                 *(u32x4*)rowp = w; }
	v_pk_add_f32 v[162:163], v[162:163], v[174:175] op_sel_hi:[1,0]
	v_pk_add_f32 v[164:165], v[164:165], v[174:175] op_sel_hi:[1,0]
	v_pk_add_f32 v[166:167], v[166:167], v[174:175] op_sel_hi:[1,0]
	v_rcp_f32_e32 v160, v160
	v_rcp_f32_e32 v161, v161
	v_rcp_f32_e32 v162, v162
	v_rcp_f32_e32 v163, v163
	v_rcp_f32_e32 v164, v164
	v_rcp_f32_e32 v165, v165
	v_rcp_f32_e32 v166, v166
	v_rcp_f32_e32 v167, v167
	v_pk_mul_f32 v[160:161], v[76:77], v[160:161]
	v_pk_mul_f32 v[162:163], v[78:79], v[162:163]
	v_pk_mul_f32 v[164:165], v[68:69], v[164:165]
	v_pk_mul_f32 v[166:167], v[70:71], v[166:167]
	v_pk_mul_f32 v[160:161], v[160:161], v[72:73]
	v_pk_mul_f32 v[162:163], v[162:163], v[74:75]
	v_pk_mul_f32 v[164:165], v[164:165], v[64:65]
	v_pk_mul_f32 v[166:167], v[166:167], v[66:67]
	v_add_u32_e32 v180, 48, v149
	v_mad_i64_i32 v[182:183], s[16:17], v180, s54, v[178:179]
	v_cvt_pk_bf16_f32 v168, v160, v161
	v_cvt_pk_bf16_f32 v169, v162, v163
	v_cvt_pk_bf16_f32 v170, v164, v165
	v_cvt_pk_bf16_f32 v171, v166, v167
	global_store_dwordx4 v[182:183], v[168:171], off
	v_pk_mul_f32 v[160:161], v[60:61], v[172:173] op_sel_hi:[1,0]
	v_pk_mul_f32 v[162:163], v[62:63], v[172:173] op_sel_hi:[1,0]
	v_pk_mul_f32 v[164:165], v[52:53], v[172:173] op_sel_hi:[1,0]
	v_pk_mul_f32 v[166:167], v[54:55], v[172:173] op_sel_hi:[1,0]
	v_exp_f32_e32 v160, v160
	v_exp_f32_e32 v161, v161
	v_exp_f32_e32 v162, v162
	v_exp_f32_e32 v163, v163
	v_exp_f32_e32 v164, v164
	v_exp_f32_e32 v165, v165
	v_exp_f32_e32 v166, v166
	v_exp_f32_e32 v167, v167
	v_pk_add_f32 v[160:161], v[160:161], v[174:175] op_sel_hi:[1,0]
	v_pk_add_f32 v[162:163], v[162:163], v[174:175] op_sel_hi:[1,0]
	v_pk_add_f32 v[164:165], v[164:165], v[174:175] op_sel_hi:[1,0]
	v_pk_add_f32 v[166:167], v[166:167], v[174:175] op_sel_hi:[1,0]
	v_rcp_f32_e32 v160, v160
	v_rcp_f32_e32 v161, v161
	v_rcp_f32_e32 v162, v162
	v_rcp_f32_e32 v163, v163
	v_rcp_f32_e32 v164, v164
	v_rcp_f32_e32 v165, v165
	v_rcp_f32_e32 v166, v166
	v_rcp_f32_e32 v167, v167
	v_pk_mul_f32 v[160:161], v[60:61], v[160:161]
	v_pk_mul_f32 v[162:163], v[62:63], v[162:163]
	v_pk_mul_f32 v[164:165], v[52:53], v[164:165]
	v_pk_mul_f32 v[166:167], v[54:55], v[166:167]
	v_pk_mul_f32 v[160:161], v[160:161], v[56:57]
	v_pk_mul_f32 v[162:163], v[162:163], v[58:59]
	v_pk_mul_f32 v[164:165], v[164:165], v[48:49]
	v_pk_mul_f32 v[166:167], v[166:167], v[50:51]
	v_add_u32_e32 v180, 0x80, v149
	v_mad_i64_i32 v[182:183], s[16:17], v180, s54, v[178:179]
	v_cvt_pk_bf16_f32 v168, v160, v161
	v_cvt_pk_bf16_f32 v169, v162, v163
	v_cvt_pk_bf16_f32 v170, v164, v165
	v_cvt_pk_bf16_f32 v171, v166, v167
	global_store_dwordx4 v[182:183], v[168:171], off
	v_pk_mul_f32 v[160:161], v[44:45], v[172:173] op_sel_hi:[1,0]
	v_pk_mul_f32 v[162:163], v[46:47], v[172:173] op_sel_hi:[1,0]
	v_pk_mul_f32 v[164:165], v[36:37], v[172:173] op_sel_hi:[1,0]
	v_pk_mul_f32 v[166:167], v[38:39], v[172:173] op_sel_hi:[1,0]
	v_exp_f32_e32 v160, v160
	v_exp_f32_e32 v161, v161
	v_exp_f32_e32 v162, v162
	v_exp_f32_e32 v163, v163
	v_exp_f32_e32 v164, v164
	v_exp_f32_e32 v165, v165
	v_exp_f32_e32 v166, v166
	v_exp_f32_e32 v167, v167
	v_pk_add_f32 v[160:161], v[160:161], v[174:175] op_sel_hi:[1,0]
	v_pk_add_f32 v[162:163], v[162:163], v[174:175] op_sel_hi:[1,0]
	v_pk_add_f32 v[164:165], v[164:165], v[174:175] op_sel_hi:[1,0]
	v_pk_add_f32 v[166:167], v[166:167], v[174:175] op_sel_hi:[1,0]
	v_rcp_f32_e32 v160, v160
	v_rcp_f32_e32 v161, v161
	v_rcp_f32_e32 v162, v162
	v_rcp_f32_e32 v163, v163
	v_rcp_f32_e32 v164, v164
	v_rcp_f32_e32 v165, v165
	v_rcp_f32_e32 v166, v166
	v_rcp_f32_e32 v167, v167
	v_pk_mul_f32 v[160:161], v[44:45], v[160:161]
	v_pk_mul_f32 v[162:163], v[46:47], v[162:163]
	v_pk_mul_f32 v[164:165], v[36:37], v[164:165]
	v_pk_mul_f32 v[166:167], v[38:39], v[166:167]
	v_pk_mul_f32 v[160:161], v[160:161], v[40:41]
; __device__ __forceinline__ float silu_f(float x) { return x * __builtin_amdgcn_rcpf(1.0f + __expf(-x)); }
; __device__ __forceinline__ unsigned cvt_pk_bf16(float lo, float hi) { unsigned r; asm volatile("v_cvt_pk_bf16_f32 %0, %1, %2" : "=v"(r) : "v"(lo), "v"(hi)); return r; }
;     __device__ __forceinline__ void operator()(const f32x4 (&acc)[2][2][4][2], const Unit& u, int wr, int wc, int fr, int fq) const {
;     ...
;         for (int ai = 0; ai < 2; ++ai)
; #pragma unroll
;             for (int m = 0; m < 4; ++m) { bf16_t* rowp = O + (size_t)(row0 + ai * HALF + m * 16) * ldc + col0;
;                 float v[8];
; #pragma unroll
;                 for (int n = 0; n < 2; ++n)
; #pragma unroll
;                     for (int j = 0; j < 4; ++j) { const float g = acc[ai][0][m][n][j], up = acc[ai][1][m][n][j]; v[n * 4 + j] = silu_f(g) * up; }
;                 u32x4 w; w.x = cvt_pk_bf16(v[0], v[1]); w.y = cvt_pk_bf16(v[2], v[3]); w.z = cvt_pk_bf16(v[4], v[5]); w.w = cvt_pk_bf16(v[6], v[7]);
;                 *(u32x4*)rowp = w; }
; template <class Epi, class Sched>
; __device__ __forceinline__ void gemm_phase(LAS unsigned char* lds, const Gemm g, const Sched& S, const Epi& E) {
;     ...
;         if constexpr (!Epi::AFTER_DRAIN) E(acc, cur, wr, wc, fr, fq);
;         if (!has_next) break;
; #pragma unroll
;         for (int a = 0; a < 2; ++a)
; #pragma unroll
;             for (int b = 0; b < 2; ++b)
; #pragma unroll
;                 for (int m = 0; m < 4; ++m)
; #pragma unroll
;                     for (int n = 0; n < 2; ++n) acc[a][b][m][n] = (f32x4){0.f, 0.f, 0.f, 0.f};
;         cur = nxt; cA = nA; cB = nB; ++ui;
;     }
	v_pk_mul_f32 v[162:163], v[162:163], v[42:43]
	v_pk_mul_f32 v[164:165], v[164:165], v[32:33]
	v_pk_mul_f32 v[166:167], v[166:167], v[34:35]
	v_add_u32_e32 v180, 0x90, v149
	v_mad_i64_i32 v[182:183], s[16:17], v180, s54, v[178:179]
	v_cvt_pk_bf16_f32 v168, v160, v161
	v_cvt_pk_bf16_f32 v169, v162, v163
	v_cvt_pk_bf16_f32 v170, v164, v165
	v_cvt_pk_bf16_f32 v171, v166, v167
	global_store_dwordx4 v[182:183], v[168:171], off
	v_pk_mul_f32 v[160:161], v[28:29], v[172:173] op_sel_hi:[1,0]
	v_pk_mul_f32 v[162:163], v[30:31], v[172:173] op_sel_hi:[1,0]
	v_pk_mul_f32 v[164:165], v[20:21], v[172:173] op_sel_hi:[1,0]
	v_pk_mul_f32 v[166:167], v[22:23], v[172:173] op_sel_hi:[1,0]
	v_exp_f32_e32 v160, v160
	v_exp_f32_e32 v161, v161
	v_exp_f32_e32 v162, v162
	v_exp_f32_e32 v163, v163
	v_exp_f32_e32 v164, v164
	v_exp_f32_e32 v165, v165
	v_exp_f32_e32 v166, v166
	v_exp_f32_e32 v167, v167
	v_pk_add_f32 v[160:161], v[160:161], v[174:175] op_sel_hi:[1,0]
	v_pk_add_f32 v[162:163], v[162:163], v[174:175] op_sel_hi:[1,0]
	v_pk_add_f32 v[164:165], v[164:165], v[174:175] op_sel_hi:[1,0]
	v_pk_add_f32 v[166:167], v[166:167], v[174:175] op_sel_hi:[1,0]
	v_rcp_f32_e32 v160, v160
	v_rcp_f32_e32 v161, v161
	v_rcp_f32_e32 v162, v162
	v_rcp_f32_e32 v163, v163
	v_rcp_f32_e32 v164, v164
	v_rcp_f32_e32 v165, v165
	v_rcp_f32_e32 v166, v166
	v_rcp_f32_e32 v167, v167
	v_pk_mul_f32 v[160:161], v[28:29], v[160:161]
	v_pk_mul_f32 v[162:163], v[30:31], v[162:163]
	v_pk_mul_f32 v[164:165], v[20:21], v[164:165]
	v_pk_mul_f32 v[166:167], v[22:23], v[166:167]
	v_pk_mul_f32 v[160:161], v[160:161], v[24:25]
	v_pk_mul_f32 v[162:163], v[162:163], v[26:27]
	v_pk_mul_f32 v[164:165], v[164:165], v[16:17]
	v_pk_mul_f32 v[166:167], v[166:167], v[18:19]
	v_add_u32_e32 v180, 0xa0, v149
	v_mad_i64_i32 v[182:183], s[16:17], v180, s54, v[178:179]
	v_cvt_pk_bf16_f32 v168, v160, v161
	v_cvt_pk_bf16_f32 v169, v162, v163
	v_cvt_pk_bf16_f32 v170, v164, v165
	v_cvt_pk_bf16_f32 v171, v166, v167
	global_store_dwordx4 v[182:183], v[168:171], off
	v_pk_mul_f32 v[160:161], v[12:13], v[172:173] op_sel_hi:[1,0]
	v_pk_mul_f32 v[162:163], v[14:15], v[172:173] op_sel_hi:[1,0]
	v_pk_mul_f32 v[164:165], v[4:5], v[172:173] op_sel_hi:[1,0]
	v_pk_mul_f32 v[166:167], v[6:7], v[172:173] op_sel_hi:[1,0]
	v_exp_f32_e32 v160, v160
	v_exp_f32_e32 v161, v161
	v_exp_f32_e32 v162, v162
	v_exp_f32_e32 v163, v163
	v_exp_f32_e32 v164, v164
	v_exp_f32_e32 v165, v165
	v_exp_f32_e32 v166, v166
	v_exp_f32_e32 v167, v167
	v_pk_add_f32 v[160:161], v[160:161], v[174:175] op_sel_hi:[1,0]
	v_pk_add_f32 v[162:163], v[162:163], v[174:175] op_sel_hi:[1,0]
	v_pk_add_f32 v[164:165], v[164:165], v[174:175] op_sel_hi:[1,0]
	v_pk_add_f32 v[166:167], v[166:167], v[174:175] op_sel_hi:[1,0]
	v_rcp_f32_e32 v160, v160
	v_rcp_f32_e32 v161, v161
	v_rcp_f32_e32 v162, v162
	v_rcp_f32_e32 v163, v163
	v_rcp_f32_e32 v164, v164
	v_rcp_f32_e32 v165, v165
	v_rcp_f32_e32 v166, v166
	v_rcp_f32_e32 v167, v167
	v_pk_mul_f32 v[160:161], v[12:13], v[160:161]
	v_pk_mul_f32 v[162:163], v[14:15], v[162:163]
	v_pk_mul_f32 v[164:165], v[4:5], v[164:165]
	v_pk_mul_f32 v[166:167], v[6:7], v[166:167]
	v_pk_mul_f32 v[160:161], v[160:161], v[8:9]
	v_pk_mul_f32 v[162:163], v[162:163], v[10:11]
	v_pk_mul_f32 v[164:165], v[164:165], v[0:1]
	v_pk_mul_f32 v[166:167], v[166:167], v[2:3]
	v_add_u32_e32 v180, 0xb0, v149
	v_mad_i64_i32 v[182:183], s[16:17], v180, s54, v[178:179]
	v_cvt_pk_bf16_f32 v168, v160, v161
	v_cvt_pk_bf16_f32 v169, v162, v163
	v_cvt_pk_bf16_f32 v170, v164, v165
	v_cvt_pk_bf16_f32 v171, v166, v167
	global_store_dwordx4 v[182:183], v[168:171], off
	s_mov_b32 s33, s6
	s_mov_b32 s14, s8
	s_mov_b64 s[18:19], s[10:11]
	s_mov_b64 s[16:17], s[12:13]
	s_cbranch_vccz .LBB0_294
	s_waitcnt vmcnt(0)
	s_cmpk_gt_u32 s23, 0xff
	s_cbranch_scc1 .LBB0_301
	s_barrier

; #define PG8_STAGE(bufoff, gbase, voff) do { _Pragma("unroll") for (int _i = 0; _i < 2; ++_i) \
;         __builtin_amdgcn_global_load_lds((const unsigned*)((const char*)(gbase) + (voff)[_i]), (LAS unsigned*)(lds + (bufoff) + ldsw + _i * 8192), 16, 0, 0); } while (0)
; #define PG8_LDA(dst, b, h) do { _Pragma("unroll") for (int m = 0; m < 4; ++m) _Pragma("unroll") for (int k = 0; k < 2; ++k) dst[m][k] = *(const LAS bf16x8*)(lds + PG8_SA(b, h) + aoff + m * 2048 + k * 1024); } while (0)
; #define PG8_LDB(dst, b, h) do { _Pragma("unroll") for (int n = 0; n < 2; ++n) _Pragma("unroll") for (int k = 0; k < 2; ++k) dst[n][k] = *(const LAS bf16x8*)(lds + PG8_SB(b, h) + boff + n * 2048 + k * 1024); } while (0)
; #define PG8_WAIT_L(n) asm volatile("s_waitcnt lgkmcnt(" #n ")" ::: "memory")
; #define PG8_BAR __builtin_amdgcn_s_barrier()
; #define PG8_SCHED __builtin_amdgcn_sched_barrier(0)
; template <class Epi, class Sched>
; __device__ __forceinline__ void gemm_phase(LAS unsigned char* lds, const Gemm g, const Sched& S, const Epi& E) {
;     ...
;         const bool has_next = S.next(ui + 1, nxt);
;         const char* nA = has_next ? (const char*)g.A + (size_t)nxt.pm * tstep : cA; const char* nB = has_next ? (const char*)g.Bt + (size_t)nxt.pn * tstep : cB;
;         for (int t = 0; t < nt; t += 2) {
;             const bool last = (t == nt - 2);
;             const char* a1 = cA + (size_t)(t + 1) * kstep;
;             const char* a2 = last ? nA : cA + (size_t)(t + 2) * kstep; const char* b2 = last ? nB : cB + (size_t)(t + 2) * kstep;
;             const char* a3 = a2 + kstep; const char* b3 = b2 + kstep;
;             PG8_LDB(B0, 0, 0); PG8_SCHED; PG8_LDA(At, 0, 0); PG8_STAGE(PG8_SA(1, 1), a1 + hstep, voffA);
;             PG8_WAIT_L(8); PG8_BAR; PG8_WAIT_L(0); PG8_MMA(0, 0, At, B0); PG8_BAR; PG8_SCHED;
;             PG8_LDB(B1, 0, 1); PG8_STAGE(PG8_SB(0, 0), b2, voffB);
;             PG8_BAR; PG8_WAIT_L(0); PG8_MMA(0, 1, At, B1); PG8_BAR;
;     ...
; #pragma unroll
;         for (int a = 0; a < 2; ++a)
; #pragma unroll
;             for (int b = 0; b < 2; ++b)
; #pragma unroll
;                 for (int m = 0; m < 4; ++m)
; #pragma unroll
;                     for (int n = 0; n < 2; ++n) acc[a][b][m][n] = (f32x4){0.f, 0.f, 0.f, 0.f};
.LBB0_364:
	v_readlane_b32 s18, v252, 47
	v_readlane_b32 s19, v252, 48
	s_ashr_i32 s15, s14, 31
	s_mov_b32 s51, -2
	v_mov_b64_e32 v[0:1], s[18:19]
	v_cmp_lt_i64_e32 vcc, s[16:17], v[0:1]
	s_lshl_b64 s[16:17], s[14:15], 19
	s_add_u32 s16, s24, s16
	s_addc_u32 s17, s25, s17
	s_and_b64 s[18:19], vcc, exec
	s_cselect_b32 s15, s17, s21
	s_cselect_b32 s39, s16, s20
	s_ashr_i32 s13, s12, 31
	s_lshl_b64 s[18:19], s[12:13], 19
	s_add_u32 s18, s26, s18
	s_addc_u32 s19, s27, s19
	s_and_b64 s[22:23], vcc, exec
	s_cselect_b32 s13, s19, s5
	s_cselect_b32 s48, s18, s4
	s_add_u32 s49, s4, 0x100
	s_addc_u32 s50, s5, 0
	s_add_u32 s4, s20, 0x40080
	v_mov_b32_e32 v0, 0
	s_addc_u32 s5, s21, 0
	v_mov_b32_e32 v1, v0
	v_pk_mov_b32 v[2:3], v[0:1], v[0:1]
	v_pk_mov_b32 v[4:5], v[0:1], v[0:1]
	v_pk_mov_b32 v[6:7], v[0:1], v[0:1]
	v_pk_mov_b32 v[8:9], v[0:1], v[0:1]
	v_pk_mov_b32 v[10:11], v[0:1], v[0:1]
	v_pk_mov_b32 v[12:13], v[0:1], v[0:1]
	v_pk_mov_b32 v[14:15], v[0:1], v[0:1]
	v_pk_mov_b32 v[16:17], v[0:1], v[0:1]
	v_pk_mov_b32 v[18:19], v[0:1], v[0:1]
	v_pk_mov_b32 v[20:21], v[0:1], v[0:1]
	v_pk_mov_b32 v[22:23], v[0:1], v[0:1]
	v_pk_mov_b32 v[24:25], v[0:1], v[0:1]
	v_pk_mov_b32 v[26:27], v[0:1], v[0:1]
	v_pk_mov_b32 v[28:29], v[0:1], v[0:1]
	v_pk_mov_b32 v[30:31], v[0:1], v[0:1]
	v_pk_mov_b32 v[32:33], v[0:1], v[0:1]
	v_pk_mov_b32 v[34:35], v[0:1], v[0:1]
	v_pk_mov_b32 v[36:37], v[0:1], v[0:1]
	v_pk_mov_b32 v[38:39], v[0:1], v[0:1]
	v_pk_mov_b32 v[40:41], v[0:1], v[0:1]
	v_pk_mov_b32 v[42:43], v[0:1], v[0:1]
	v_pk_mov_b32 v[44:45], v[0:1], v[0:1]
	v_pk_mov_b32 v[46:47], v[0:1], v[0:1]
	v_pk_mov_b32 v[48:49], v[0:1], v[0:1]
	v_pk_mov_b32 v[50:51], v[0:1], v[0:1]
	v_pk_mov_b32 v[52:53], v[0:1], v[0:1]
	v_pk_mov_b32 v[54:55], v[0:1], v[0:1]
	v_pk_mov_b32 v[56:57], v[0:1], v[0:1]
	v_pk_mov_b32 v[58:59], v[0:1], v[0:1]
	v_pk_mov_b32 v[60:61], v[0:1], v[0:1]
	v_pk_mov_b32 v[62:63], v[0:1], v[0:1]
	v_pk_mov_b32 v[64:65], v[0:1], v[0:1]
	v_pk_mov_b32 v[66:67], v[0:1], v[0:1]
	v_pk_mov_b32 v[68:69], v[0:1], v[0:1]
	v_pk_mov_b32 v[70:71], v[0:1], v[0:1]
	v_pk_mov_b32 v[72:73], v[0:1], v[0:1]
	v_pk_mov_b32 v[74:75], v[0:1], v[0:1]
	v_pk_mov_b32 v[76:77], v[0:1], v[0:1]
	v_pk_mov_b32 v[78:79], v[0:1], v[0:1]
	v_pk_mov_b32 v[80:81], v[0:1], v[0:1]
	v_pk_mov_b32 v[82:83], v[0:1], v[0:1]
	v_pk_mov_b32 v[84:85], v[0:1], v[0:1]
	v_pk_mov_b32 v[86:87], v[0:1], v[0:1]
	v_pk_mov_b32 v[88:89], v[0:1], v[0:1]
	v_pk_mov_b32 v[90:91], v[0:1], v[0:1]
	v_pk_mov_b32 v[92:93], v[0:1], v[0:1]
	v_pk_mov_b32 v[94:95], v[0:1], v[0:1]
	v_pk_mov_b32 v[96:97], v[0:1], v[0:1]
	v_pk_mov_b32 v[98:99], v[0:1], v[0:1]
	v_pk_mov_b32 v[100:101], v[0:1], v[0:1]
	v_pk_mov_b32 v[102:103], v[0:1], v[0:1]
	v_pk_mov_b32 v[104:105], v[0:1], v[0:1]
	v_pk_mov_b32 v[106:107], v[0:1], v[0:1]
	v_pk_mov_b32 v[108:109], v[0:1], v[0:1]
	v_pk_mov_b32 v[110:111], v[0:1], v[0:1]
	v_pk_mov_b32 v[112:113], v[0:1], v[0:1]
	v_pk_mov_b32 v[114:115], v[0:1], v[0:1]
	v_pk_mov_b32 v[116:117], v[0:1], v[0:1]
	v_pk_mov_b32 v[118:119], v[0:1], v[0:1]
	v_pk_mov_b32 v[120:121], v[0:1], v[0:1]
	v_pk_mov_b32 v[122:123], v[0:1], v[0:1]
	v_pk_mov_b32 v[124:125], v[0:1], v[0:1]
	v_pk_mov_b32 v[126:127], v[0:1], v[0:1]
.LBB0_365:
	s_add_u32 s20, s4, 0xfffc0080
	s_addc_u32 s21, s5, -1
	s_add_i32 s52, 0, 0x10000
	v_add_u32_e32 v140, s52, v168
	ds_read_b128 v[128:131], v140
	ds_read_b128 v[132:135], v140 offset:1024
	ds_read_b128 v[136:139], v140 offset:2048
	ds_read_b128 v[140:143], v140 offset:3072
	s_cmp_eq_u32 s51, 12
	s_cselect_b32 s23, s15, s21
	s_cselect_b32 s22, s39, s20
	s_cselect_b32 s21, s13, s50
	s_cselect_b32 s20, s48, s49
	v_lshl_add_u64 v[220:221], s[4:5], 0, v[162:163]
	s_add_i32 m0, s29, 0xc000
	ds_read_b128 v[164:167], v170
	ds_read_b128 v[172:175], v170 offset:1024
	ds_read_b128 v[176:179], v170 offset:2048
	ds_read_b128 v[180:183], v170 offset:3072
	ds_read_b128 v[184:187], v170 offset:4096
	ds_read_b128 v[208:211], v170 offset:5120
	ds_read_b128 v[212:215], v170 offset:6144
	ds_read_b128 v[216:219], v170 offset:7168
	global_load_lds_dwordx4 v[220:221], off
	v_lshl_add_u64 v[220:221], s[4:5], 0, v[160:161]
	s_add_i32 m0, s29, 0xe000
	s_nop 0
	global_load_lds_dwordx4 v[220:221], off
	s_waitcnt lgkmcnt(8)
	s_barrier
	s_waitcnt lgkmcnt(0)
	s_setprio 1
	v_mfma_f32_16x16x32_bf16 v[124:127], v[128:131], v[164:167], v[124:127]
	v_mfma_f32_16x16x32_bf16 v[120:123], v[136:139], v[164:167], v[120:123]
	v_mfma_f32_16x16x32_bf16 v[112:115], v[128:131], v[176:179], v[112:115]
	v_mfma_f32_16x16x32_bf16 v[104:107], v[136:139], v[176:179], v[104:107]
	v_mfma_f32_16x16x32_bf16 v[96:99], v[128:131], v[184:187], v[96:99]
	v_mfma_f32_16x16x32_bf16 v[88:91], v[136:139], v[184:187], v[88:91]
	v_mfma_f32_16x16x32_bf16 v[80:83], v[128:131], v[212:215], v[80:83]
	v_mfma_f32_16x16x32_bf16 v[72:75], v[136:139], v[212:215], v[72:75]
	v_mfma_f32_16x16x32_bf16 v[124:127], v[132:135], v[172:175], v[124:127]
	v_mfma_f32_16x16x32_bf16 v[120:123], v[140:143], v[172:175], v[120:123]
	v_mfma_f32_16x16x32_bf16 v[112:115], v[132:135], v[180:183], v[112:115]
	v_mfma_f32_16x16x32_bf16 v[104:107], v[140:143], v[180:183], v[104:107]
	v_mfma_f32_16x16x32_bf16 v[96:99], v[132:135], v[208:211], v[96:99]
	v_mfma_f32_16x16x32_bf16 v[88:91], v[140:143], v[208:211], v[88:91]
	v_mfma_f32_16x16x32_bf16 v[80:83], v[132:135], v[216:219], v[80:83]
	v_mfma_f32_16x16x32_bf16 v[72:75], v[140:143], v[216:219], v[72:75]
	s_setprio 0
	s_barrier
; #define PG8_STAGE(bufoff, gbase, voff) do { _Pragma("unroll") for (int _i = 0; _i < 2; ++_i) \
;         __builtin_amdgcn_global_load_lds((const unsigned*)((const char*)(gbase) + (voff)[_i]), (LAS unsigned*)(lds + (bufoff) + ldsw + _i * 8192), 16, 0, 0); } while (0)
; #define PG8_LDA(dst, b, h) do { _Pragma("unroll") for (int m = 0; m < 4; ++m) _Pragma("unroll") for (int k = 0; k < 2; ++k) dst[m][k] = *(const LAS bf16x8*)(lds + PG8_SA(b, h) + aoff + m * 2048 + k * 1024); } while (0)
; #define PG8_LDB(dst, b, h) do { _Pragma("unroll") for (int n = 0; n < 2; ++n) _Pragma("unroll") for (int k = 0; k < 2; ++k) dst[n][k] = *(const LAS bf16x8*)(lds + PG8_SB(b, h) + boff + n * 2048 + k * 1024); } while (0)
; #define PG8_MMA(ai, bj, At, Bt) do { __builtin_amdgcn_s_setprio(1); _Pragma("unroll") for (int m = 0; m < 4; ++m) _Pragma("unroll") for (int n = 0; n < 2; ++n) _Pragma("unroll") for (int k = 0; k < 2; ++k) \
;         acc[ai][bj][m][n] = __builtin_amdgcn_mfma_f32_16x16x32_bf16(Bt[n][k], At[m][k], acc[ai][bj][m][n], 0, 0, 0); __builtin_amdgcn_s_setprio(0); } while (0)
; #define PG8_WAIT_V(n) asm volatile("s_waitcnt vmcnt(" #n ")" ::: "memory")
; #define PG8_WAIT_L(n) asm volatile("s_waitcnt lgkmcnt(" #n ")" ::: "memory")
; #define PG8_BAR __builtin_amdgcn_s_barrier()
; #define PG8_SCHED __builtin_amdgcn_sched_barrier(0)
; template <class Epi, class Sched>
; __device__ __forceinline__ void gemm_phase(LAS unsigned char* lds, const Gemm g, const Sched& S, const Epi& E) {
;     ...
;             PG8_BAR; PG8_WAIT_L(0); PG8_MMA(0, 1, At, B1); PG8_BAR;
;             PG8_LDA(At, 0, 1); PG8_STAGE(PG8_SA(0, 0), a2, voffA);
;             PG8_BAR; PG8_WAIT_L(0); PG8_MMA(1, 0, At, B0); PG8_BAR; PG8_SCHED;
;             PG8_STAGE(PG8_SB(0, 1), b2 + hstep, voffB);
;             PG8_WAIT_V(6); PG8_BAR; PG8_MMA(1, 1, At, B1); PG8_BAR;
;             PG8_LDB(B0, 1, 0); PG8_SCHED; PG8_LDA(At, 1, 0); PG8_STAGE(PG8_SA(0, 1), a2 + hstep, voffA);
;             PG8_WAIT_L(8); PG8_BAR; PG8_WAIT_L(0); PG8_MMA(0, 0, At, B0); PG8_BAR; PG8_SCHED;
	s_add_i32 s62, 0, 0x14000
	s_add_i32 s52, s52, s28
	v_add_u32_e32 v171, s62, v168
	v_lshl_add_u64 v[236:237], s[20:21], 0, v[144:145]
	s_mov_b32 m0, s52
	ds_read_b128 v[220:223], v171
	ds_read_b128 v[224:227], v171 offset:1024
	ds_read_b128 v[228:231], v171 offset:2048
	ds_read_b128 v[232:235], v171 offset:3072
	global_load_lds_dwordx4 v[236:237], off
	v_lshl_add_u64 v[238:239], s[20:21], 0, v[154:155]
	s_add_i32 m0, s52, 0x2000
	s_nop 0
	global_load_lds_dwordx4 v[238:239], off
	s_barrier
	s_waitcnt lgkmcnt(0)
	s_setprio 1
	v_mfma_f32_16x16x32_bf16 v[116:119], v[220:223], v[164:167], v[116:119]
	v_mfma_f32_16x16x32_bf16 v[108:111], v[228:231], v[164:167], v[108:111]
	v_mfma_f32_16x16x32_bf16 v[100:103], v[220:223], v[176:179], v[100:103]
	v_mfma_f32_16x16x32_bf16 v[92:95], v[228:231], v[176:179], v[92:95]
	v_mfma_f32_16x16x32_bf16 v[84:87], v[220:223], v[184:187], v[84:87]
	v_mfma_f32_16x16x32_bf16 v[76:79], v[228:231], v[184:187], v[76:79]
	v_mfma_f32_16x16x32_bf16 v[68:71], v[220:223], v[212:215], v[68:71]
	v_mfma_f32_16x16x32_bf16 v[64:67], v[228:231], v[212:215], v[64:67]
	v_mfma_f32_16x16x32_bf16 v[116:119], v[224:227], v[172:175], v[116:119]
	v_mfma_f32_16x16x32_bf16 v[108:111], v[232:235], v[172:175], v[108:111]
	v_mfma_f32_16x16x32_bf16 v[100:103], v[224:227], v[180:183], v[100:103]
	v_mfma_f32_16x16x32_bf16 v[92:95], v[232:235], v[180:183], v[92:95]
	v_mfma_f32_16x16x32_bf16 v[84:87], v[224:227], v[208:211], v[84:87]
	v_mfma_f32_16x16x32_bf16 v[76:79], v[232:235], v[208:211], v[76:79]
	v_mfma_f32_16x16x32_bf16 v[68:71], v[224:227], v[216:219], v[68:71]
	v_mfma_f32_16x16x32_bf16 v[64:67], v[232:235], v[216:219], v[64:67]
	s_setprio 0
	s_mov_b32 m0, s29
	v_lshl_add_u64 v[240:241], s[22:23], 0, v[158:159]
	s_barrier
	ds_read_b128 v[164:167], v170 offset:16384
	ds_read_b128 v[172:175], v170 offset:17408
	ds_read_b128 v[176:179], v170 offset:18432
	ds_read_b128 v[180:183], v170 offset:19456
	ds_read_b128 v[184:187], v170 offset:20480
	ds_read_b128 v[208:211], v170 offset:21504
	ds_read_b128 v[212:215], v170 offset:22528
	ds_read_b128 v[216:219], v170 offset:23552
	global_load_lds_dwordx4 v[240:241], off
	v_lshl_add_u64 v[242:243], s[22:23], 0, v[156:157]
	s_mov_b32 m0, s30
	s_nop 0
	global_load_lds_dwordx4 v[242:243], off
	s_barrier
	s_waitcnt lgkmcnt(0)
	s_setprio 1
	v_mfma_f32_16x16x32_bf16 v[60:63], v[128:131], v[164:167], v[60:63]
	v_mfma_f32_16x16x32_bf16 v[56:59], v[136:139], v[164:167], v[56:59]
	v_mfma_f32_16x16x32_bf16 v[48:51], v[128:131], v[176:179], v[48:51]
	v_mfma_f32_16x16x32_bf16 v[40:43], v[136:139], v[176:179], v[40:43]
	v_mfma_f32_16x16x32_bf16 v[32:35], v[128:131], v[184:187], v[32:35]
	v_mfma_f32_16x16x32_bf16 v[24:27], v[136:139], v[184:187], v[24:27]
	v_mfma_f32_16x16x32_bf16 v[16:19], v[128:131], v[212:215], v[16:19]
	v_mfma_f32_16x16x32_bf16 v[8:11], v[136:139], v[212:215], v[8:11]
	v_mfma_f32_16x16x32_bf16 v[60:63], v[132:135], v[172:175], v[60:63]
	v_mfma_f32_16x16x32_bf16 v[56:59], v[140:143], v[172:175], v[56:59]
	v_mfma_f32_16x16x32_bf16 v[48:51], v[132:135], v[180:183], v[48:51]
	v_mfma_f32_16x16x32_bf16 v[40:43], v[140:143], v[180:183], v[40:43]
	v_mfma_f32_16x16x32_bf16 v[32:35], v[132:135], v[208:211], v[32:35]
	v_mfma_f32_16x16x32_bf16 v[24:27], v[140:143], v[208:211], v[24:27]
	v_mfma_f32_16x16x32_bf16 v[16:19], v[132:135], v[216:219], v[16:19]
	v_mfma_f32_16x16x32_bf16 v[8:11], v[140:143], v[216:219], v[8:11]
	s_setprio 0
	s_barrier
	s_add_u32 s52, s20, 0x40000
	s_addc_u32 s53, s21, 0
	s_add_i32 s62, s62, s28
	v_lshl_add_u64 v[128:129], s[52:53], 0, v[144:145]
	s_mov_b32 m0, s62
	s_nop 0
	global_load_lds_dwordx4 v[128:129], off
	v_lshl_add_u64 v[128:129], s[52:53], 0, v[154:155]
	s_add_i32 m0, s62, 0x2000
	s_nop 0
	global_load_lds_dwordx4 v[128:129], off
	s_waitcnt vmcnt(6)
	s_barrier
	s_setprio 1
	v_mfma_f32_16x16x32_bf16 v[52:55], v[220:223], v[164:167], v[52:55]
	v_mfma_f32_16x16x32_bf16 v[44:47], v[228:231], v[164:167], v[44:47]
	v_mfma_f32_16x16x32_bf16 v[36:39], v[220:223], v[176:179], v[36:39]
	v_mfma_f32_16x16x32_bf16 v[28:31], v[228:231], v[176:179], v[28:31]
	v_mfma_f32_16x16x32_bf16 v[20:23], v[220:223], v[184:187], v[20:23]
	v_mfma_f32_16x16x32_bf16 v[12:15], v[228:231], v[184:187], v[12:15]
	v_mfma_f32_16x16x32_bf16 v[4:7], v[220:223], v[212:215], v[4:7]
	v_mfma_f32_16x16x32_bf16 v[0:3], v[228:231], v[212:215], v[0:3]
	v_mfma_f32_16x16x32_bf16 v[52:55], v[224:227], v[172:175], v[52:55]
	v_mfma_f32_16x16x32_bf16 v[44:47], v[232:235], v[172:175], v[44:47]
	v_mfma_f32_16x16x32_bf16 v[36:39], v[224:227], v[180:183], v[36:39]
	v_mfma_f32_16x16x32_bf16 v[28:31], v[232:235], v[180:183], v[28:31]
	v_mfma_f32_16x16x32_bf16 v[20:23], v[224:227], v[208:211], v[20:23]
	v_mfma_f32_16x16x32_bf16 v[12:15], v[232:235], v[208:211], v[12:15]
	v_mfma_f32_16x16x32_bf16 v[4:7], v[224:227], v[216:219], v[4:7]
	v_mfma_f32_16x16x32_bf16 v[0:3], v[232:235], v[216:219], v[0:3]
	s_setprio 0
	s_add_i32 s52, 0, 0x18000
	v_add_u32_e32 v140, s52, v168
	s_barrier
	ds_read_b128 v[128:131], v140
	ds_read_b128 v[132:135], v140 offset:1024
	ds_read_b128 v[136:139], v140 offset:2048
	ds_read_b128 v[140:143], v140 offset:3072
	s_add_u32 s22, s22, 0x40000
	s_addc_u32 s23, s23, 0
	s_mov_b32 m0, s31
	v_lshl_add_u64 v[220:221], s[22:23], 0, v[158:159]
	ds_read_b128 v[164:167], v170 offset:32768
	ds_read_b128 v[172:175], v170 offset:33792
	ds_read_b128 v[176:179], v170 offset:34816
	ds_read_b128 v[180:183], v170 offset:35840
	ds_read_b128 v[184:187], v170 offset:36864
	ds_read_b128 v[208:211], v170 offset:37888
	ds_read_b128 v[212:215], v170 offset:38912
	ds_read_b128 v[216:219], v170 offset:39936
	global_load_lds_dwordx4 v[220:221], off
	v_lshl_add_u64 v[220:221], s[22:23], 0, v[156:157]
	s_mov_b32 m0, s34
	s_nop 0
	global_load_lds_dwordx4 v[220:221], off
	s_waitcnt lgkmcnt(8)
	s_barrier
; #define PG8_STAGE(bufoff, gbase, voff) do { _Pragma("unroll") for (int _i = 0; _i < 2; ++_i) \
;         __builtin_amdgcn_global_load_lds((const unsigned*)((const char*)(gbase) + (voff)[_i]), (LAS unsigned*)(lds + (bufoff) + ldsw + _i * 8192), 16, 0, 0); } while (0)
; #define PG8_LDA(dst, b, h) do { _Pragma("unroll") for (int m = 0; m < 4; ++m) _Pragma("unroll") for (int k = 0; k < 2; ++k) dst[m][k] = *(const LAS bf16x8*)(lds + PG8_SA(b, h) + aoff + m * 2048 + k * 1024); } while (0)
; #define PG8_LDB(dst, b, h) do { _Pragma("unroll") for (int n = 0; n < 2; ++n) _Pragma("unroll") for (int k = 0; k < 2; ++k) dst[n][k] = *(const LAS bf16x8*)(lds + PG8_SB(b, h) + boff + n * 2048 + k * 1024); } while (0)
; #define PG8_MMA(ai, bj, At, Bt) do { __builtin_amdgcn_s_setprio(1); _Pragma("unroll") for (int m = 0; m < 4; ++m) _Pragma("unroll") for (int n = 0; n < 2; ++n) _Pragma("unroll") for (int k = 0; k < 2; ++k) \
;         acc[ai][bj][m][n] = __builtin_amdgcn_mfma_f32_16x16x32_bf16(Bt[n][k], At[m][k], acc[ai][bj][m][n], 0, 0, 0); __builtin_amdgcn_s_setprio(0); } while (0)
; #define PG8_WAIT_V(n) asm volatile("s_waitcnt vmcnt(" #n ")" ::: "memory")
; #define PG8_WAIT_L(n) asm volatile("s_waitcnt lgkmcnt(" #n ")" ::: "memory")
;     __device__ __forceinline__ void operator()(const f32x4 (&acc)[2][2][4][2], const Unit& u, int wr, int wc, int fr, int fq) const {
;         const int row0 = u.pm * BM + wr * 64 + fr; const int col0 = u.pn * BM + wc * 32 + 8 * fq;
;         f32x4 bv[2][2];
; #pragma unroll
;         for (int bj = 0; bj < 2; ++bj)
; #pragma unroll
;             for (int n = 0; n < 2; ++n) bv[bj][n] = bias ? *(const f32x4*)(bias + col0 + bj * HALF + 4 * n) : (f32x4){0.f, 0.f, 0.f, 0.f};
; template <class Epi, class Sched>
; __device__ __forceinline__ void gemm_phase(LAS unsigned char* lds, const Gemm g, const Sched& S, const Epi& E) {
;     ...
;             PG8_WAIT_L(8); PG8_BAR; PG8_WAIT_L(0); PG8_MMA(0, 0, At, B0); PG8_BAR; PG8_SCHED;
;             PG8_LDB(B1, 1, 1); PG8_STAGE(PG8_SB(1, 0), b3, voffB);
;             PG8_BAR; PG8_WAIT_L(0); PG8_MMA(0, 1, At, B1); PG8_BAR;
;             PG8_LDA(At, 1, 1); PG8_STAGE(PG8_SA(1, 0), a3, voffA);
;             PG8_BAR; PG8_WAIT_L(0); PG8_MMA(1, 0, At, B0); PG8_BAR; PG8_SCHED;
;             PG8_STAGE(PG8_SB(1, 1), b3 + hstep, voffB);
;             PG8_WAIT_V(6); PG8_BAR; PG8_MMA(1, 1, At, B1); PG8_BAR;
	s_waitcnt lgkmcnt(0)
	s_setprio 1
	v_mfma_f32_16x16x32_bf16 v[124:127], v[128:131], v[164:167], v[124:127]
	v_mfma_f32_16x16x32_bf16 v[120:123], v[136:139], v[164:167], v[120:123]
	v_mfma_f32_16x16x32_bf16 v[112:115], v[128:131], v[176:179], v[112:115]
	v_mfma_f32_16x16x32_bf16 v[104:107], v[136:139], v[176:179], v[104:107]
	v_mfma_f32_16x16x32_bf16 v[96:99], v[128:131], v[184:187], v[96:99]
	v_mfma_f32_16x16x32_bf16 v[88:91], v[136:139], v[184:187], v[88:91]
	v_mfma_f32_16x16x32_bf16 v[80:83], v[128:131], v[212:215], v[80:83]
	v_mfma_f32_16x16x32_bf16 v[72:75], v[136:139], v[212:215], v[72:75]
	v_mfma_f32_16x16x32_bf16 v[124:127], v[132:135], v[172:175], v[124:127]
	v_mfma_f32_16x16x32_bf16 v[120:123], v[140:143], v[172:175], v[120:123]
	v_mfma_f32_16x16x32_bf16 v[112:115], v[132:135], v[180:183], v[112:115]
	v_mfma_f32_16x16x32_bf16 v[104:107], v[140:143], v[180:183], v[104:107]
	v_mfma_f32_16x16x32_bf16 v[96:99], v[132:135], v[208:211], v[96:99]
	v_mfma_f32_16x16x32_bf16 v[88:91], v[140:143], v[208:211], v[88:91]
	v_mfma_f32_16x16x32_bf16 v[80:83], v[132:135], v[216:219], v[80:83]
	v_mfma_f32_16x16x32_bf16 v[72:75], v[140:143], v[216:219], v[72:75]
	s_setprio 0
	s_barrier
	s_add_i32 s22, 0, 0x1c000
	s_add_i32 s23, s52, s28
	v_add_u32_e32 v171, s22, v168
	v_lshl_add_u64 v[236:237], v[236:237], 0, s[82:83]
	s_mov_b32 m0, s23
	ds_read_b128 v[220:223], v171
	ds_read_b128 v[224:227], v171 offset:1024
	ds_read_b128 v[228:231], v171 offset:2048
	ds_read_b128 v[232:235], v171 offset:3072
	global_load_lds_dwordx4 v[236:237], off
	v_lshl_add_u64 v[236:237], v[238:239], 0, s[82:83]
	s_add_i32 m0, s23, 0x2000
	s_nop 0
	global_load_lds_dwordx4 v[236:237], off
	s_barrier
	s_waitcnt lgkmcnt(0)
	s_setprio 1
	v_mfma_f32_16x16x32_bf16 v[116:119], v[220:223], v[164:167], v[116:119]
	v_mfma_f32_16x16x32_bf16 v[108:111], v[228:231], v[164:167], v[108:111]
	v_mfma_f32_16x16x32_bf16 v[100:103], v[220:223], v[176:179], v[100:103]
	v_mfma_f32_16x16x32_bf16 v[92:95], v[228:231], v[176:179], v[92:95]
	v_mfma_f32_16x16x32_bf16 v[84:87], v[220:223], v[184:187], v[84:87]
	v_mfma_f32_16x16x32_bf16 v[76:79], v[228:231], v[184:187], v[76:79]
	v_mfma_f32_16x16x32_bf16 v[68:71], v[220:223], v[212:215], v[68:71]
	v_mfma_f32_16x16x32_bf16 v[64:67], v[228:231], v[212:215], v[64:67]
	v_mfma_f32_16x16x32_bf16 v[116:119], v[224:227], v[172:175], v[116:119]
	v_mfma_f32_16x16x32_bf16 v[108:111], v[232:235], v[172:175], v[108:111]
	v_mfma_f32_16x16x32_bf16 v[100:103], v[224:227], v[180:183], v[100:103]
	v_mfma_f32_16x16x32_bf16 v[92:95], v[232:235], v[180:183], v[92:95]
	v_mfma_f32_16x16x32_bf16 v[84:87], v[224:227], v[208:211], v[84:87]
	v_mfma_f32_16x16x32_bf16 v[76:79], v[232:235], v[208:211], v[76:79]
	v_mfma_f32_16x16x32_bf16 v[68:71], v[224:227], v[216:219], v[68:71]
	v_mfma_f32_16x16x32_bf16 v[64:67], v[232:235], v[216:219], v[64:67]
	s_setprio 0
	s_mov_b32 m0, s35
	v_lshl_add_u64 v[236:237], v[240:241], 0, s[82:83]
	s_barrier
	ds_read_b128 v[164:167], v170 offset:49152
	ds_read_b128 v[172:175], v170 offset:50176
	ds_read_b128 v[176:179], v170 offset:51200
	ds_read_b128 v[180:183], v170 offset:52224
	ds_read_b128 v[184:187], v170 offset:53248
	ds_read_b128 v[208:211], v170 offset:54272
	ds_read_b128 v[212:215], v170 offset:55296
	ds_read_b128 v[216:219], v170 offset:56320
	global_load_lds_dwordx4 v[236:237], off
	v_lshl_add_u64 v[236:237], v[242:243], 0, s[82:83]
	s_mov_b32 m0, s36
	s_nop 0
	global_load_lds_dwordx4 v[236:237], off
	s_barrier
	s_waitcnt lgkmcnt(0)
	s_setprio 1
	v_mfma_f32_16x16x32_bf16 v[60:63], v[128:131], v[164:167], v[60:63]
	v_mfma_f32_16x16x32_bf16 v[56:59], v[136:139], v[164:167], v[56:59]
	v_mfma_f32_16x16x32_bf16 v[48:51], v[128:131], v[176:179], v[48:51]
	v_mfma_f32_16x16x32_bf16 v[40:43], v[136:139], v[176:179], v[40:43]
	v_mfma_f32_16x16x32_bf16 v[32:35], v[128:131], v[184:187], v[32:35]
	v_mfma_f32_16x16x32_bf16 v[24:27], v[136:139], v[184:187], v[24:27]
	v_mfma_f32_16x16x32_bf16 v[16:19], v[128:131], v[212:215], v[16:19]
	v_mfma_f32_16x16x32_bf16 v[8:11], v[136:139], v[212:215], v[8:11]
	v_mfma_f32_16x16x32_bf16 v[60:63], v[132:135], v[172:175], v[60:63]
	v_mfma_f32_16x16x32_bf16 v[56:59], v[140:143], v[172:175], v[56:59]
	v_mfma_f32_16x16x32_bf16 v[48:51], v[132:135], v[180:183], v[48:51]
	v_mfma_f32_16x16x32_bf16 v[40:43], v[140:143], v[180:183], v[40:43]
	v_mfma_f32_16x16x32_bf16 v[32:35], v[132:135], v[208:211], v[32:35]
	v_mfma_f32_16x16x32_bf16 v[24:27], v[140:143], v[208:211], v[24:27]
	v_mfma_f32_16x16x32_bf16 v[16:19], v[132:135], v[216:219], v[16:19]
	v_mfma_f32_16x16x32_bf16 v[8:11], v[140:143], v[216:219], v[8:11]
	s_setprio 0
	s_barrier
	s_add_u32 s20, s20, 0x40080
	s_addc_u32 s21, s21, 0
	s_add_i32 s22, s22, s28
	v_lshl_add_u64 v[128:129], s[20:21], 0, v[144:145]
	s_mov_b32 m0, s22
	s_nop 0
	global_load_lds_dwordx4 v[128:129], off
	v_lshl_add_u64 v[128:129], s[20:21], 0, v[154:155]
	s_add_i32 m0, s22, 0x2000
	s_nop 0
	global_load_lds_dwordx4 v[128:129], off
	s_waitcnt vmcnt(6)
	s_barrier
	s_setprio 1
	v_mfma_f32_16x16x32_bf16 v[52:55], v[220:223], v[164:167], v[52:55]
	v_mfma_f32_16x16x32_bf16 v[44:47], v[228:231], v[164:167], v[44:47]
	v_mfma_f32_16x16x32_bf16 v[36:39], v[220:223], v[176:179], v[36:39]
	v_mfma_f32_16x16x32_bf16 v[28:31], v[228:231], v[176:179], v[28:31]
	v_mfma_f32_16x16x32_bf16 v[20:23], v[220:223], v[184:187], v[20:23]
	v_mfma_f32_16x16x32_bf16 v[12:15], v[228:231], v[184:187], v[12:15]
	v_mfma_f32_16x16x32_bf16 v[4:7], v[220:223], v[212:215], v[4:7]
	v_mfma_f32_16x16x32_bf16 v[0:3], v[228:231], v[212:215], v[0:3]
	v_mfma_f32_16x16x32_bf16 v[52:55], v[224:227], v[172:175], v[52:55]
	v_mfma_f32_16x16x32_bf16 v[44:47], v[232:235], v[172:175], v[44:47]
	v_mfma_f32_16x16x32_bf16 v[36:39], v[224:227], v[180:183], v[36:39]
	v_mfma_f32_16x16x32_bf16 v[28:31], v[232:235], v[180:183], v[28:31]
	v_mfma_f32_16x16x32_bf16 v[20:23], v[224:227], v[208:211], v[20:23]
	v_mfma_f32_16x16x32_bf16 v[12:15], v[232:235], v[208:211], v[12:15]
	v_mfma_f32_16x16x32_bf16 v[4:7], v[224:227], v[216:219], v[4:7]
	v_mfma_f32_16x16x32_bf16 v[0:3], v[232:235], v[216:219], v[0:3]
	s_setprio 0
	s_add_i32 s51, s51, 2
	s_add_u32 s49, s49, 0x100
	s_addc_u32 s50, s50, 0
	s_add_u32 s4, s4, 0x100
	s_addc_u32 s5, s5, 0
	s_cmp_gt_u32 s51, 13
	s_barrier
	s_cbranch_scc0 .LBB0_365
	v_lshl_or_b32 v166, s38, 8, v169
	v_ashrrev_i32_e32 v167, 31, v166
	v_cndmask_b32_e64 v129, 0, 1, s[10:11]
	v_lshl_add_u64 v[164:165], v[166:167], 2, s[8:9]
	v_mov_b32_e32 v128, 0
	v_cmp_ne_u32_e64 s[4:5], 1, v129
	s_andn2_b64 vcc, exec, s[10:11]
	v_mov_b32_e32 v132, 0
	v_mov_b32_e32 v133, 0
	v_mov_b32_e32 v134, 0
	v_mov_b32_e32 v135, 0
	s_cbranch_vccnz .LBB0_368
	global_load_dwordx4 v[132:135], v[164:165], off

; #define PG8_STAGE(bufoff, gbase, voff) do { _Pragma("unroll") for (int _i = 0; _i < 2; ++_i) \
;         __builtin_amdgcn_global_load_lds((const unsigned*)((const char*)(gbase) + (voff)[_i]), (LAS unsigned*)(lds + (bufoff) + ldsw + _i * 8192), 16, 0, 0); } while (0)
; #define PG8_LDA(dst, b, h) do { _Pragma("unroll") for (int m = 0; m < 4; ++m) _Pragma("unroll") for (int k = 0; k < 2; ++k) dst[m][k] = *(const LAS bf16x8*)(lds + PG8_SA(b, h) + aoff + m * 2048 + k * 1024); } while (0)
; #define PG8_LDB(dst, b, h) do { _Pragma("unroll") for (int n = 0; n < 2; ++n) _Pragma("unroll") for (int k = 0; k < 2; ++k) dst[n][k] = *(const LAS bf16x8*)(lds + PG8_SB(b, h) + boff + n * 2048 + k * 1024); } while (0)
; #define PG8_WAIT_L(n) asm volatile("s_waitcnt lgkmcnt(" #n ")" ::: "memory")
; #define PG8_BAR __builtin_amdgcn_s_barrier()
; #define PG8_SCHED __builtin_amdgcn_sched_barrier(0)
; template <class Epi, class Sched>
; __device__ __forceinline__ void gemm_phase(LAS unsigned char* lds, const Gemm g, const Sched& S, const Epi& E) {
;     ...
;         const bool has_next = S.next(ui + 1, nxt);
;         const char* nA = has_next ? (const char*)g.A + (size_t)nxt.pm * tstep : cA; const char* nB = has_next ? (const char*)g.Bt + (size_t)nxt.pn * tstep : cB;
;         for (int t = 0; t < nt; t += 2) {
;             const bool last = (t == nt - 2);
;             const char* a1 = cA + (size_t)(t + 1) * kstep;
;             const char* a2 = last ? nA : cA + (size_t)(t + 2) * kstep; const char* b2 = last ? nB : cB + (size_t)(t + 2) * kstep;
;             const char* a3 = a2 + kstep; const char* b3 = b2 + kstep;
;             PG8_LDB(B0, 0, 0); PG8_SCHED; PG8_LDA(At, 0, 0); PG8_STAGE(PG8_SA(1, 1), a1 + hstep, voffA);
;             PG8_WAIT_L(8); PG8_BAR; PG8_WAIT_L(0); PG8_MMA(0, 0, At, B0); PG8_BAR; PG8_SCHED;
;             PG8_LDB(B1, 0, 1); PG8_STAGE(PG8_SB(0, 0), b2, voffB);
;             PG8_BAR; PG8_WAIT_L(0); PG8_MMA(0, 1, At, B1); PG8_BAR;
;     ...
; #pragma unroll
;         for (int a = 0; a < 2; ++a)
; #pragma unroll
;             for (int b = 0; b < 2; ++b)
; #pragma unroll
;                 for (int m = 0; m < 4; ++m)
; #pragma unroll
;                     for (int n = 0; n < 2; ++n) acc[a][b][m][n] = (f32x4){0.f, 0.f, 0.f, 0.f};
.LBB0_795:
	v_mov_b64_e32 v[0:1], s[68:69]
	s_ashr_i32 s9, s8, 31
	v_cmp_lt_i64_e32 vcc, s[10:11], v[0:1]
	s_lshl_b64 s[10:11], s[8:9], 19
	s_add_u32 s10, s20, s10
	s_addc_u32 s11, s21, s11
	s_and_b64 s[12:13], vcc, exec
	s_cselect_b32 s9, s11, s17
	s_cselect_b32 s35, s10, s16
	s_ashr_i32 s7, s6, 31
	s_lshl_b64 s[12:13], s[6:7], 19
	s_add_u32 s12, s22, s12
	s_addc_u32 s13, s23, s13
	s_and_b64 s[18:19], vcc, exec
	s_cselect_b32 s7, s13, s15
	s_cselect_b32 s36, s12, s14
	s_add_u32 s37, s14, 0x100
	s_addc_u32 s38, s15, 0
	s_add_u32 s14, s16, 0x40080
	v_mov_b32_e32 v0, 0
	s_addc_u32 s15, s17, 0
	s_mov_b32 s39, -2
	v_mov_b32_e32 v1, v0
	v_pk_mov_b32 v[2:3], v[0:1], v[0:1]
	v_pk_mov_b32 v[4:5], v[0:1], v[0:1]
	v_pk_mov_b32 v[6:7], v[0:1], v[0:1]
	v_pk_mov_b32 v[8:9], v[0:1], v[0:1]
	v_pk_mov_b32 v[10:11], v[0:1], v[0:1]
	v_pk_mov_b32 v[12:13], v[0:1], v[0:1]
	v_pk_mov_b32 v[14:15], v[0:1], v[0:1]
	v_pk_mov_b32 v[16:17], v[0:1], v[0:1]
	v_pk_mov_b32 v[18:19], v[0:1], v[0:1]
	v_pk_mov_b32 v[20:21], v[0:1], v[0:1]
	v_pk_mov_b32 v[22:23], v[0:1], v[0:1]
	v_pk_mov_b32 v[24:25], v[0:1], v[0:1]
	v_pk_mov_b32 v[26:27], v[0:1], v[0:1]
	v_pk_mov_b32 v[28:29], v[0:1], v[0:1]
	v_pk_mov_b32 v[30:31], v[0:1], v[0:1]
	v_pk_mov_b32 v[32:33], v[0:1], v[0:1]
	v_pk_mov_b32 v[34:35], v[0:1], v[0:1]
	v_pk_mov_b32 v[36:37], v[0:1], v[0:1]
	v_pk_mov_b32 v[38:39], v[0:1], v[0:1]
	v_pk_mov_b32 v[40:41], v[0:1], v[0:1]
	v_pk_mov_b32 v[42:43], v[0:1], v[0:1]
	v_pk_mov_b32 v[44:45], v[0:1], v[0:1]
	v_pk_mov_b32 v[46:47], v[0:1], v[0:1]
	v_pk_mov_b32 v[48:49], v[0:1], v[0:1]
	v_pk_mov_b32 v[50:51], v[0:1], v[0:1]
	v_pk_mov_b32 v[52:53], v[0:1], v[0:1]
	v_pk_mov_b32 v[54:55], v[0:1], v[0:1]
	v_pk_mov_b32 v[56:57], v[0:1], v[0:1]
	v_pk_mov_b32 v[58:59], v[0:1], v[0:1]
	v_pk_mov_b32 v[60:61], v[0:1], v[0:1]
	v_pk_mov_b32 v[62:63], v[0:1], v[0:1]
	v_pk_mov_b32 v[64:65], v[0:1], v[0:1]
	v_pk_mov_b32 v[66:67], v[0:1], v[0:1]
	v_pk_mov_b32 v[68:69], v[0:1], v[0:1]
	v_pk_mov_b32 v[70:71], v[0:1], v[0:1]
	v_pk_mov_b32 v[72:73], v[0:1], v[0:1]
	v_pk_mov_b32 v[74:75], v[0:1], v[0:1]
	v_pk_mov_b32 v[76:77], v[0:1], v[0:1]
	v_pk_mov_b32 v[78:79], v[0:1], v[0:1]
	v_pk_mov_b32 v[80:81], v[0:1], v[0:1]
	v_pk_mov_b32 v[82:83], v[0:1], v[0:1]
	v_pk_mov_b32 v[84:85], v[0:1], v[0:1]
	v_pk_mov_b32 v[86:87], v[0:1], v[0:1]
	v_pk_mov_b32 v[88:89], v[0:1], v[0:1]
	v_pk_mov_b32 v[90:91], v[0:1], v[0:1]
	v_pk_mov_b32 v[92:93], v[0:1], v[0:1]
	v_pk_mov_b32 v[94:95], v[0:1], v[0:1]
	v_pk_mov_b32 v[96:97], v[0:1], v[0:1]
	v_pk_mov_b32 v[98:99], v[0:1], v[0:1]
	v_pk_mov_b32 v[100:101], v[0:1], v[0:1]
	v_pk_mov_b32 v[102:103], v[0:1], v[0:1]
	v_pk_mov_b32 v[104:105], v[0:1], v[0:1]
	v_pk_mov_b32 v[106:107], v[0:1], v[0:1]
	v_pk_mov_b32 v[108:109], v[0:1], v[0:1]
	v_pk_mov_b32 v[110:111], v[0:1], v[0:1]
	v_pk_mov_b32 v[112:113], v[0:1], v[0:1]
	v_pk_mov_b32 v[114:115], v[0:1], v[0:1]
	v_pk_mov_b32 v[116:117], v[0:1], v[0:1]
	v_pk_mov_b32 v[118:119], v[0:1], v[0:1]
	v_pk_mov_b32 v[120:121], v[0:1], v[0:1]
	v_pk_mov_b32 v[122:123], v[0:1], v[0:1]
	v_pk_mov_b32 v[124:125], v[0:1], v[0:1]
	v_pk_mov_b32 v[126:127], v[0:1], v[0:1]
.LBB0_796:
	s_add_u32 s16, s14, 0xfffc0080
	s_addc_u32 s17, s15, -1
	s_add_i32 s48, 0, 0x10000
	v_add_u32_e32 v155, s48, v143
	ds_read_b128 v[138:141], v155
	ds_read_b128 v[156:159], v155 offset:1024
	ds_read_b128 v[160:163], v155 offset:2048
	ds_read_b128 v[164:167], v155 offset:3072
	s_cmp_eq_u32 s39, 12
	s_cselect_b32 s19, s9, s17
	s_cselect_b32 s18, s35, s16
	s_cselect_b32 s17, s7, s38
	s_cselect_b32 s16, s36, s37
	v_lshl_add_u64 v[220:221], s[14:15], 0, v[136:137]
	s_add_i32 m0, s25, 0xc000
	ds_read_b128 v[168:171], v154
	ds_read_b128 v[172:175], v154 offset:1024
	ds_read_b128 v[176:179], v154 offset:2048
	ds_read_b128 v[180:183], v154 offset:3072
	ds_read_b128 v[184:187], v154 offset:4096
	ds_read_b128 v[208:211], v154 offset:5120
	ds_read_b128 v[212:215], v154 offset:6144
	ds_read_b128 v[216:219], v154 offset:7168
	global_load_lds_dwordx4 v[220:221], off
	v_lshl_add_u64 v[220:221], s[14:15], 0, v[134:135]
	s_add_i32 m0, s25, 0xe000
	s_nop 0
	global_load_lds_dwordx4 v[220:221], off
	s_waitcnt lgkmcnt(8)
	s_barrier
	s_waitcnt lgkmcnt(0)
	s_setprio 1
	v_mfma_f32_16x16x32_bf16 v[124:127], v[138:141], v[168:171], v[124:127]
	v_mfma_f32_16x16x32_bf16 v[120:123], v[160:163], v[168:171], v[120:123]
	v_mfma_f32_16x16x32_bf16 v[112:115], v[138:141], v[176:179], v[112:115]
	v_mfma_f32_16x16x32_bf16 v[104:107], v[160:163], v[176:179], v[104:107]
	v_mfma_f32_16x16x32_bf16 v[96:99], v[138:141], v[184:187], v[96:99]
	v_mfma_f32_16x16x32_bf16 v[88:91], v[160:163], v[184:187], v[88:91]
	v_mfma_f32_16x16x32_bf16 v[80:83], v[138:141], v[212:215], v[80:83]
	v_mfma_f32_16x16x32_bf16 v[72:75], v[160:163], v[212:215], v[72:75]
	v_mfma_f32_16x16x32_bf16 v[124:127], v[156:159], v[172:175], v[124:127]
	v_mfma_f32_16x16x32_bf16 v[120:123], v[164:167], v[172:175], v[120:123]
	v_mfma_f32_16x16x32_bf16 v[112:115], v[156:159], v[180:183], v[112:115]
	v_mfma_f32_16x16x32_bf16 v[104:107], v[164:167], v[180:183], v[104:107]
	v_mfma_f32_16x16x32_bf16 v[96:99], v[156:159], v[208:211], v[96:99]
	v_mfma_f32_16x16x32_bf16 v[88:91], v[164:167], v[208:211], v[88:91]
	v_mfma_f32_16x16x32_bf16 v[80:83], v[156:159], v[216:219], v[80:83]
	v_mfma_f32_16x16x32_bf16 v[72:75], v[164:167], v[216:219], v[72:75]
	s_setprio 0
	s_barrier
	s_add_i32 s50, 0, 0x14000
	s_add_i32 s48, s48, s24
	v_add_u32_e32 v155, s50, v143
	v_lshl_add_u64 v[236:237], s[16:17], 0, v[144:145]
	s_mov_b32 m0, s48
	ds_read_b128 v[220:223], v155
	ds_read_b128 v[224:227], v155 offset:1024
	ds_read_b128 v[228:231], v155 offset:2048
	ds_read_b128 v[232:235], v155 offset:3072
	global_load_lds_dwordx4 v[236:237], off
	v_lshl_add_u64 v[238:239], s[16:17], 0, v[128:129]
	s_add_i32 m0, s48, 0x2000
	s_nop 0
	global_load_lds_dwordx4 v[238:239], off
	s_barrier
; #define PG8_STAGE(bufoff, gbase, voff) do { _Pragma("unroll") for (int _i = 0; _i < 2; ++_i) \
;         __builtin_amdgcn_global_load_lds((const unsigned*)((const char*)(gbase) + (voff)[_i]), (LAS unsigned*)(lds + (bufoff) + ldsw + _i * 8192), 16, 0, 0); } while (0)
; #define PG8_LDA(dst, b, h) do { _Pragma("unroll") for (int m = 0; m < 4; ++m) _Pragma("unroll") for (int k = 0; k < 2; ++k) dst[m][k] = *(const LAS bf16x8*)(lds + PG8_SA(b, h) + aoff + m * 2048 + k * 1024); } while (0)
; #define PG8_LDB(dst, b, h) do { _Pragma("unroll") for (int n = 0; n < 2; ++n) _Pragma("unroll") for (int k = 0; k < 2; ++k) dst[n][k] = *(const LAS bf16x8*)(lds + PG8_SB(b, h) + boff + n * 2048 + k * 1024); } while (0)
; #define PG8_MMA(ai, bj, At, Bt) do { __builtin_amdgcn_s_setprio(1); _Pragma("unroll") for (int m = 0; m < 4; ++m) _Pragma("unroll") for (int n = 0; n < 2; ++n) _Pragma("unroll") for (int k = 0; k < 2; ++k) \
;         acc[ai][bj][m][n] = __builtin_amdgcn_mfma_f32_16x16x32_bf16(Bt[n][k], At[m][k], acc[ai][bj][m][n], 0, 0, 0); __builtin_amdgcn_s_setprio(0); } while (0)
; #define PG8_WAIT_V(n) asm volatile("s_waitcnt vmcnt(" #n ")" ::: "memory")
; #define PG8_WAIT_L(n) asm volatile("s_waitcnt lgkmcnt(" #n ")" ::: "memory")
; #define PG8_BAR __builtin_amdgcn_s_barrier()
; #define PG8_SCHED __builtin_amdgcn_sched_barrier(0)
; template <class Epi, class Sched>
; __device__ __forceinline__ void gemm_phase(LAS unsigned char* lds, const Gemm g, const Sched& S, const Epi& E) {
;     ...
;             PG8_BAR; PG8_WAIT_L(0); PG8_MMA(0, 1, At, B1); PG8_BAR;
;             PG8_LDA(At, 0, 1); PG8_STAGE(PG8_SA(0, 0), a2, voffA);
;             PG8_BAR; PG8_WAIT_L(0); PG8_MMA(1, 0, At, B0); PG8_BAR; PG8_SCHED;
;             PG8_STAGE(PG8_SB(0, 1), b2 + hstep, voffB);
;             PG8_WAIT_V(6); PG8_BAR; PG8_MMA(1, 1, At, B1); PG8_BAR;
;             PG8_LDB(B0, 1, 0); PG8_SCHED; PG8_LDA(At, 1, 0); PG8_STAGE(PG8_SA(0, 1), a2 + hstep, voffA);
;             PG8_WAIT_L(8); PG8_BAR; PG8_WAIT_L(0); PG8_MMA(0, 0, At, B0); PG8_BAR; PG8_SCHED;
	s_waitcnt lgkmcnt(0)
	s_setprio 1
	v_mfma_f32_16x16x32_bf16 v[116:119], v[220:223], v[168:171], v[116:119]
	v_mfma_f32_16x16x32_bf16 v[108:111], v[228:231], v[168:171], v[108:111]
	v_mfma_f32_16x16x32_bf16 v[100:103], v[220:223], v[176:179], v[100:103]
	v_mfma_f32_16x16x32_bf16 v[92:95], v[228:231], v[176:179], v[92:95]
	v_mfma_f32_16x16x32_bf16 v[84:87], v[220:223], v[184:187], v[84:87]
	v_mfma_f32_16x16x32_bf16 v[76:79], v[228:231], v[184:187], v[76:79]
	v_mfma_f32_16x16x32_bf16 v[68:71], v[220:223], v[212:215], v[68:71]
	v_mfma_f32_16x16x32_bf16 v[64:67], v[228:231], v[212:215], v[64:67]
	v_mfma_f32_16x16x32_bf16 v[116:119], v[224:227], v[172:175], v[116:119]
	v_mfma_f32_16x16x32_bf16 v[108:111], v[232:235], v[172:175], v[108:111]
	v_mfma_f32_16x16x32_bf16 v[100:103], v[224:227], v[180:183], v[100:103]
	v_mfma_f32_16x16x32_bf16 v[92:95], v[232:235], v[180:183], v[92:95]
	v_mfma_f32_16x16x32_bf16 v[84:87], v[224:227], v[208:211], v[84:87]
	v_mfma_f32_16x16x32_bf16 v[76:79], v[232:235], v[208:211], v[76:79]
	v_mfma_f32_16x16x32_bf16 v[68:71], v[224:227], v[216:219], v[68:71]
	v_mfma_f32_16x16x32_bf16 v[64:67], v[232:235], v[216:219], v[64:67]
	s_setprio 0
	s_mov_b32 m0, s25
	v_lshl_add_u64 v[240:241], s[18:19], 0, v[132:133]
	s_barrier
	ds_read_b128 v[168:171], v154 offset:16384
	ds_read_b128 v[172:175], v154 offset:17408
	ds_read_b128 v[176:179], v154 offset:18432
	ds_read_b128 v[180:183], v154 offset:19456
	ds_read_b128 v[184:187], v154 offset:20480
	ds_read_b128 v[208:211], v154 offset:21504
	ds_read_b128 v[212:215], v154 offset:22528
	ds_read_b128 v[216:219], v154 offset:23552
	global_load_lds_dwordx4 v[240:241], off
	v_lshl_add_u64 v[242:243], s[18:19], 0, v[130:131]
	s_mov_b32 m0, s26
	s_nop 0
	global_load_lds_dwordx4 v[242:243], off
	s_barrier
	s_waitcnt lgkmcnt(0)
	s_setprio 1
	v_mfma_f32_16x16x32_bf16 v[60:63], v[138:141], v[168:171], v[60:63]
	v_mfma_f32_16x16x32_bf16 v[56:59], v[160:163], v[168:171], v[56:59]
	v_mfma_f32_16x16x32_bf16 v[48:51], v[138:141], v[176:179], v[48:51]
	v_mfma_f32_16x16x32_bf16 v[40:43], v[160:163], v[176:179], v[40:43]
	v_mfma_f32_16x16x32_bf16 v[32:35], v[138:141], v[184:187], v[32:35]
	v_mfma_f32_16x16x32_bf16 v[24:27], v[160:163], v[184:187], v[24:27]
	v_mfma_f32_16x16x32_bf16 v[16:19], v[138:141], v[212:215], v[16:19]
	v_mfma_f32_16x16x32_bf16 v[8:11], v[160:163], v[212:215], v[8:11]
	v_mfma_f32_16x16x32_bf16 v[60:63], v[156:159], v[172:175], v[60:63]
	v_mfma_f32_16x16x32_bf16 v[56:59], v[164:167], v[172:175], v[56:59]
	v_mfma_f32_16x16x32_bf16 v[48:51], v[156:159], v[180:183], v[48:51]
	v_mfma_f32_16x16x32_bf16 v[40:43], v[164:167], v[180:183], v[40:43]
	v_mfma_f32_16x16x32_bf16 v[32:35], v[156:159], v[208:211], v[32:35]
	v_mfma_f32_16x16x32_bf16 v[24:27], v[164:167], v[208:211], v[24:27]
	v_mfma_f32_16x16x32_bf16 v[16:19], v[156:159], v[216:219], v[16:19]
	v_mfma_f32_16x16x32_bf16 v[8:11], v[164:167], v[216:219], v[8:11]
	s_setprio 0
	s_barrier
	s_add_u32 s48, s16, 0x40000
	s_addc_u32 s49, s17, 0
	s_add_i32 s50, s50, s24
	v_lshl_add_u64 v[138:139], s[48:49], 0, v[144:145]
	s_mov_b32 m0, s50
	s_nop 0
	global_load_lds_dwordx4 v[138:139], off
	v_lshl_add_u64 v[138:139], s[48:49], 0, v[128:129]
	s_add_i32 m0, s50, 0x2000
	s_nop 0
	global_load_lds_dwordx4 v[138:139], off
	s_waitcnt vmcnt(6)
	s_barrier
	s_setprio 1
	v_mfma_f32_16x16x32_bf16 v[52:55], v[220:223], v[168:171], v[52:55]
	v_mfma_f32_16x16x32_bf16 v[44:47], v[228:231], v[168:171], v[44:47]
	v_mfma_f32_16x16x32_bf16 v[36:39], v[220:223], v[176:179], v[36:39]
	v_mfma_f32_16x16x32_bf16 v[28:31], v[228:231], v[176:179], v[28:31]
	v_mfma_f32_16x16x32_bf16 v[20:23], v[220:223], v[184:187], v[20:23]
	v_mfma_f32_16x16x32_bf16 v[12:15], v[228:231], v[184:187], v[12:15]
	v_mfma_f32_16x16x32_bf16 v[4:7], v[220:223], v[212:215], v[4:7]
	v_mfma_f32_16x16x32_bf16 v[0:3], v[228:231], v[212:215], v[0:3]
	v_mfma_f32_16x16x32_bf16 v[52:55], v[224:227], v[172:175], v[52:55]
	v_mfma_f32_16x16x32_bf16 v[44:47], v[232:235], v[172:175], v[44:47]
	v_mfma_f32_16x16x32_bf16 v[36:39], v[224:227], v[180:183], v[36:39]
	v_mfma_f32_16x16x32_bf16 v[28:31], v[232:235], v[180:183], v[28:31]
	v_mfma_f32_16x16x32_bf16 v[20:23], v[224:227], v[208:211], v[20:23]
	v_mfma_f32_16x16x32_bf16 v[12:15], v[232:235], v[208:211], v[12:15]
	v_mfma_f32_16x16x32_bf16 v[4:7], v[224:227], v[216:219], v[4:7]
	v_mfma_f32_16x16x32_bf16 v[0:3], v[232:235], v[216:219], v[0:3]
	s_setprio 0
	s_add_i32 s48, 0, 0x18000
	v_add_u32_e32 v155, s48, v143
	s_barrier
	ds_read_b128 v[138:141], v155
	ds_read_b128 v[156:159], v155 offset:1024
	ds_read_b128 v[160:163], v155 offset:2048
	ds_read_b128 v[164:167], v155 offset:3072
	s_add_u32 s18, s18, 0x40000
	s_addc_u32 s19, s19, 0
	s_mov_b32 m0, s27
	v_lshl_add_u64 v[220:221], s[18:19], 0, v[132:133]
	ds_read_b128 v[168:171], v154 offset:32768
	ds_read_b128 v[172:175], v154 offset:33792
	ds_read_b128 v[176:179], v154 offset:34816
	ds_read_b128 v[180:183], v154 offset:35840
	ds_read_b128 v[184:187], v154 offset:36864
	ds_read_b128 v[208:211], v154 offset:37888
	ds_read_b128 v[212:215], v154 offset:38912
	ds_read_b128 v[216:219], v154 offset:39936
	global_load_lds_dwordx4 v[220:221], off
	v_lshl_add_u64 v[220:221], s[18:19], 0, v[130:131]
	s_mov_b32 m0, s28
	s_nop 0
	global_load_lds_dwordx4 v[220:221], off
	s_waitcnt lgkmcnt(8)
	s_barrier
; #define PG8_STAGE(bufoff, gbase, voff) do { _Pragma("unroll") for (int _i = 0; _i < 2; ++_i) \
;         __builtin_amdgcn_global_load_lds((const unsigned*)((const char*)(gbase) + (voff)[_i]), (LAS unsigned*)(lds + (bufoff) + ldsw + _i * 8192), 16, 0, 0); } while (0)
; #define PG8_LDA(dst, b, h) do { _Pragma("unroll") for (int m = 0; m < 4; ++m) _Pragma("unroll") for (int k = 0; k < 2; ++k) dst[m][k] = *(const LAS bf16x8*)(lds + PG8_SA(b, h) + aoff + m * 2048 + k * 1024); } while (0)
; #define PG8_LDB(dst, b, h) do { _Pragma("unroll") for (int n = 0; n < 2; ++n) _Pragma("unroll") for (int k = 0; k < 2; ++k) dst[n][k] = *(const LAS bf16x8*)(lds + PG8_SB(b, h) + boff + n * 2048 + k * 1024); } while (0)
; #define PG8_MMA(ai, bj, At, Bt) do { __builtin_amdgcn_s_setprio(1); _Pragma("unroll") for (int m = 0; m < 4; ++m) _Pragma("unroll") for (int n = 0; n < 2; ++n) _Pragma("unroll") for (int k = 0; k < 2; ++k) \
;         acc[ai][bj][m][n] = __builtin_amdgcn_mfma_f32_16x16x32_bf16(Bt[n][k], At[m][k], acc[ai][bj][m][n], 0, 0, 0); __builtin_amdgcn_s_setprio(0); } while (0)
; #define PG8_WAIT_V(n) asm volatile("s_waitcnt vmcnt(" #n ")" ::: "memory")
; #define PG8_WAIT_L(n) asm volatile("s_waitcnt lgkmcnt(" #n ")" ::: "memory")
; #define PG8_BAR __builtin_amdgcn_s_barrier()
; #define PG8_SCHED __builtin_amdgcn_sched_barrier(0)
; template <class Epi, class Sched>
; __device__ __forceinline__ void gemm_phase(LAS unsigned char* lds, const Gemm g, const Sched& S, const Epi& E) {
;     ...
;             PG8_WAIT_L(8); PG8_BAR; PG8_WAIT_L(0); PG8_MMA(0, 0, At, B0); PG8_BAR; PG8_SCHED;
;             PG8_LDB(B1, 1, 1); PG8_STAGE(PG8_SB(1, 0), b3, voffB);
;             PG8_BAR; PG8_WAIT_L(0); PG8_MMA(0, 1, At, B1); PG8_BAR;
;             PG8_LDA(At, 1, 1); PG8_STAGE(PG8_SA(1, 0), a3, voffA);
;             PG8_BAR; PG8_WAIT_L(0); PG8_MMA(1, 0, At, B0); PG8_BAR; PG8_SCHED;
;             PG8_STAGE(PG8_SB(1, 1), b3 + hstep, voffB);
;             PG8_WAIT_V(6); PG8_BAR; PG8_MMA(1, 1, At, B1); PG8_BAR;
	s_waitcnt lgkmcnt(0)
	s_setprio 1
	v_mfma_f32_16x16x32_bf16 v[124:127], v[138:141], v[168:171], v[124:127]
	v_mfma_f32_16x16x32_bf16 v[120:123], v[160:163], v[168:171], v[120:123]
	v_mfma_f32_16x16x32_bf16 v[112:115], v[138:141], v[176:179], v[112:115]
	v_mfma_f32_16x16x32_bf16 v[104:107], v[160:163], v[176:179], v[104:107]
	v_mfma_f32_16x16x32_bf16 v[96:99], v[138:141], v[184:187], v[96:99]
	v_mfma_f32_16x16x32_bf16 v[88:91], v[160:163], v[184:187], v[88:91]
	v_mfma_f32_16x16x32_bf16 v[80:83], v[138:141], v[212:215], v[80:83]
	v_mfma_f32_16x16x32_bf16 v[72:75], v[160:163], v[212:215], v[72:75]
	v_mfma_f32_16x16x32_bf16 v[124:127], v[156:159], v[172:175], v[124:127]
	v_mfma_f32_16x16x32_bf16 v[120:123], v[164:167], v[172:175], v[120:123]
	v_mfma_f32_16x16x32_bf16 v[112:115], v[156:159], v[180:183], v[112:115]
	v_mfma_f32_16x16x32_bf16 v[104:107], v[164:167], v[180:183], v[104:107]
	v_mfma_f32_16x16x32_bf16 v[96:99], v[156:159], v[208:211], v[96:99]
	v_mfma_f32_16x16x32_bf16 v[88:91], v[164:167], v[208:211], v[88:91]
	v_mfma_f32_16x16x32_bf16 v[80:83], v[156:159], v[216:219], v[80:83]
	v_mfma_f32_16x16x32_bf16 v[72:75], v[164:167], v[216:219], v[72:75]
	s_setprio 0
	s_barrier
	s_add_i32 s18, 0, 0x1c000
	s_add_i32 s19, s48, s24
	v_add_u32_e32 v155, s18, v143
	v_lshl_add_u64 v[236:237], v[236:237], 0, s[82:83]
	s_mov_b32 m0, s19
	ds_read_b128 v[220:223], v155
	ds_read_b128 v[224:227], v155 offset:1024
	ds_read_b128 v[228:231], v155 offset:2048
	ds_read_b128 v[232:235], v155 offset:3072
	global_load_lds_dwordx4 v[236:237], off
	v_lshl_add_u64 v[236:237], v[238:239], 0, s[82:83]
	s_add_i32 m0, s19, 0x2000
	s_nop 0
	global_load_lds_dwordx4 v[236:237], off
	s_barrier
	s_waitcnt lgkmcnt(0)
	s_setprio 1
	v_mfma_f32_16x16x32_bf16 v[116:119], v[220:223], v[168:171], v[116:119]
	v_mfma_f32_16x16x32_bf16 v[108:111], v[228:231], v[168:171], v[108:111]
	v_mfma_f32_16x16x32_bf16 v[100:103], v[220:223], v[176:179], v[100:103]
	v_mfma_f32_16x16x32_bf16 v[92:95], v[228:231], v[176:179], v[92:95]
	v_mfma_f32_16x16x32_bf16 v[84:87], v[220:223], v[184:187], v[84:87]
	v_mfma_f32_16x16x32_bf16 v[76:79], v[228:231], v[184:187], v[76:79]
	v_mfma_f32_16x16x32_bf16 v[68:71], v[220:223], v[212:215], v[68:71]
	v_mfma_f32_16x16x32_bf16 v[64:67], v[228:231], v[212:215], v[64:67]
	v_mfma_f32_16x16x32_bf16 v[116:119], v[224:227], v[172:175], v[116:119]
	v_mfma_f32_16x16x32_bf16 v[108:111], v[232:235], v[172:175], v[108:111]
	v_mfma_f32_16x16x32_bf16 v[100:103], v[224:227], v[180:183], v[100:103]
	v_mfma_f32_16x16x32_bf16 v[92:95], v[232:235], v[180:183], v[92:95]
	v_mfma_f32_16x16x32_bf16 v[84:87], v[224:227], v[208:211], v[84:87]
	v_mfma_f32_16x16x32_bf16 v[76:79], v[232:235], v[208:211], v[76:79]
	v_mfma_f32_16x16x32_bf16 v[68:71], v[224:227], v[216:219], v[68:71]
	v_mfma_f32_16x16x32_bf16 v[64:67], v[232:235], v[216:219], v[64:67]
	s_setprio 0
	s_mov_b32 m0, s29
	v_lshl_add_u64 v[236:237], v[240:241], 0, s[82:83]
	s_barrier
	ds_read_b128 v[168:171], v154 offset:49152
	ds_read_b128 v[172:175], v154 offset:50176
	ds_read_b128 v[176:179], v154 offset:51200
	ds_read_b128 v[180:183], v154 offset:52224
	ds_read_b128 v[184:187], v154 offset:53248
	ds_read_b128 v[208:211], v154 offset:54272
	ds_read_b128 v[212:215], v154 offset:55296
	ds_read_b128 v[216:219], v154 offset:56320
	global_load_lds_dwordx4 v[236:237], off
	v_lshl_add_u64 v[236:237], v[242:243], 0, s[82:83]
	s_mov_b32 m0, s30
	s_nop 0
	global_load_lds_dwordx4 v[236:237], off
	s_barrier
	s_waitcnt lgkmcnt(0)
	s_setprio 1
	v_mfma_f32_16x16x32_bf16 v[60:63], v[138:141], v[168:171], v[60:63]
	v_mfma_f32_16x16x32_bf16 v[56:59], v[160:163], v[168:171], v[56:59]
	v_mfma_f32_16x16x32_bf16 v[48:51], v[138:141], v[176:179], v[48:51]
	v_mfma_f32_16x16x32_bf16 v[40:43], v[160:163], v[176:179], v[40:43]
	v_mfma_f32_16x16x32_bf16 v[32:35], v[138:141], v[184:187], v[32:35]
	v_mfma_f32_16x16x32_bf16 v[24:27], v[160:163], v[184:187], v[24:27]
	v_mfma_f32_16x16x32_bf16 v[16:19], v[138:141], v[212:215], v[16:19]
	v_mfma_f32_16x16x32_bf16 v[8:11], v[160:163], v[212:215], v[8:11]
	v_mfma_f32_16x16x32_bf16 v[60:63], v[156:159], v[172:175], v[60:63]
	v_mfma_f32_16x16x32_bf16 v[56:59], v[164:167], v[172:175], v[56:59]
	v_mfma_f32_16x16x32_bf16 v[48:51], v[156:159], v[180:183], v[48:51]
	v_mfma_f32_16x16x32_bf16 v[40:43], v[164:167], v[180:183], v[40:43]
	v_mfma_f32_16x16x32_bf16 v[32:35], v[156:159], v[208:211], v[32:35]
	v_mfma_f32_16x16x32_bf16 v[24:27], v[164:167], v[208:211], v[24:27]
	v_mfma_f32_16x16x32_bf16 v[16:19], v[156:159], v[216:219], v[16:19]
	v_mfma_f32_16x16x32_bf16 v[8:11], v[164:167], v[216:219], v[8:11]
	s_setprio 0
	s_barrier
	s_add_u32 s16, s16, 0x40080
	s_addc_u32 s17, s17, 0
	s_add_i32 s18, s18, s24
	v_lshl_add_u64 v[138:139], s[16:17], 0, v[144:145]
	s_mov_b32 m0, s18
	s_nop 0
	global_load_lds_dwordx4 v[138:139], off
	v_lshl_add_u64 v[138:139], s[16:17], 0, v[128:129]
	s_add_i32 m0, s18, 0x2000
	s_nop 0
	global_load_lds_dwordx4 v[138:139], off
	s_waitcnt vmcnt(6)
	s_barrier
	s_setprio 1
	v_mfma_f32_16x16x32_bf16 v[52:55], v[220:223], v[168:171], v[52:55]
	v_mfma_f32_16x16x32_bf16 v[44:47], v[228:231], v[168:171], v[44:47]
	v_mfma_f32_16x16x32_bf16 v[36:39], v[220:223], v[176:179], v[36:39]
	v_mfma_f32_16x16x32_bf16 v[28:31], v[228:231], v[176:179], v[28:31]
	v_mfma_f32_16x16x32_bf16 v[20:23], v[220:223], v[184:187], v[20:23]
	v_mfma_f32_16x16x32_bf16 v[12:15], v[228:231], v[184:187], v[12:15]
	v_mfma_f32_16x16x32_bf16 v[4:7], v[220:223], v[212:215], v[4:7]
	v_mfma_f32_16x16x32_bf16 v[0:3], v[228:231], v[212:215], v[0:3]
	v_mfma_f32_16x16x32_bf16 v[52:55], v[224:227], v[172:175], v[52:55]
	v_mfma_f32_16x16x32_bf16 v[44:47], v[232:235], v[172:175], v[44:47]
	v_mfma_f32_16x16x32_bf16 v[36:39], v[224:227], v[180:183], v[36:39]
	v_mfma_f32_16x16x32_bf16 v[28:31], v[232:235], v[180:183], v[28:31]
	v_mfma_f32_16x16x32_bf16 v[20:23], v[224:227], v[208:211], v[20:23]
	v_mfma_f32_16x16x32_bf16 v[12:15], v[232:235], v[208:211], v[12:15]
	v_mfma_f32_16x16x32_bf16 v[4:7], v[224:227], v[216:219], v[4:7]
	v_mfma_f32_16x16x32_bf16 v[0:3], v[232:235], v[216:219], v[0:3]
	s_setprio 0
	s_add_i32 s39, s39, 2
	s_add_u32 s37, s37, 0x100
	s_addc_u32 s38, s38, 0
	s_add_u32 s14, s14, 0x100
	s_addc_u32 s15, s15, 0
	s_cmp_gt_u32 s39, 13
	s_barrier
; __device__ __forceinline__ unsigned cvt_pk_bf16(float lo, float hi) { unsigned r; asm volatile("v_cvt_pk_bf16_f32 %0, %1, %2" : "=v"(r) : "v"(lo), "v"(hi)); return r; }
;     __device__ __forceinline__ void operator()(const f32x4 (&acc)[2][2][4][2], const Unit& u, int wr, int wc, int fr, int fq) const {
;         const int row0 = u.pm * BM + wr * 64 + fr; const int col0 = u.pn * BM + wc * 32 + 8 * fq;
;         f32x4 bv[2][2];
; #pragma unroll
;         for (int bj = 0; bj < 2; ++bj)
; #pragma unroll
;             for (int n = 0; n < 2; ++n) bv[bj][n] = bias ? *(const f32x4*)(bias + col0 + bj * HALF + 4 * n) : (f32x4){0.f, 0.f, 0.f, 0.f};
; #pragma unroll
;         for (int ai = 0; ai < 2; ++ai)
; #pragma unroll
;             for (int m = 0; m < 4; ++m) { bf16_t* rowp = O + (size_t)(row0 + ai * HALF + m * 16) * ldc + col0;
; #pragma unroll
;                 for (int bj = 0; bj < 2; ++bj) { f32x4 v0 = acc[ai][bj][m][0] + bv[bj][0], v1 = acc[ai][bj][m][1] + bv[bj][1];
;                     u32x4 w; w.x = cvt_pk_bf16(v0[0], v0[1]); w.y = cvt_pk_bf16(v0[2], v0[3]); w.z = cvt_pk_bf16(v1[0], v1[1]); w.w = cvt_pk_bf16(v1[2], v1[3]);
;                     *(u32x4*)(rowp + bj * HALF) = w; } }
;     }
	s_cbranch_scc0 .LBB0_796
	v_lshl_or_b32 v140, s34, 8, v149
	v_ashrrev_i32_e32 v141, 31, v140
	v_lshl_add_u32 v155, s33, 8, v142
	v_mov_b64_e32 v[138:139], s[4:5]
	v_mad_i64_i32 v[156:157], s[14:15], v155, s54, v[138:139]
	v_lshlrev_b64 v[140:141], 1, v[140:141]
	v_lshl_add_u64 v[156:157], v[156:157], 0, v[140:141]
	v_pk_add_f32 v[126:127], v[126:127], 0 op_sel_hi:[1,0]
	v_pk_add_f32 v[124:125], v[124:125], 0 op_sel_hi:[1,0]
	v_pk_add_f32 v[158:159], v[122:123], 0 op_sel_hi:[1,0]
	v_pk_add_f32 v[122:123], v[120:121], 0 op_sel_hi:[1,0]
	v_cvt_pk_bf16_f32 v120, v124, v125
	v_cvt_pk_bf16_f32 v121, v126, v127
	v_pk_add_f32 v[116:117], v[116:117], 0 op_sel_hi:[1,0]
	v_cvt_pk_bf16_f32 v122, v122, v123
	v_cvt_pk_bf16_f32 v123, v158, v159
	global_store_dwordx4 v[156:157], v[120:123], off
	v_pk_add_f32 v[118:119], v[118:119], 0 op_sel_hi:[1,0]
	v_pk_add_f32 v[112:113], v[112:113], 0 op_sel_hi:[1,0]
	v_pk_add_f32 v[120:121], v[110:111], 0 op_sel_hi:[1,0]
	v_pk_add_f32 v[110:111], v[108:109], 0 op_sel_hi:[1,0]
	v_cvt_pk_bf16_f32 v108, v116, v117
	v_cvt_pk_bf16_f32 v109, v118, v119
	v_pk_add_f32 v[100:101], v[100:101], 0 op_sel_hi:[1,0]
	v_cvt_pk_bf16_f32 v110, v110, v111
	v_cvt_pk_bf16_f32 v111, v120, v121
	global_store_dwordx4 v[156:157], v[108:111], off offset:256
	v_pk_add_f32 v[102:103], v[102:103], 0 op_sel_hi:[1,0]
	v_pk_add_f32 v[96:97], v[96:97], 0 op_sel_hi:[1,0]
	v_or_b32_e32 v108, 16, v155
	v_mad_i64_i32 v[108:109], s[14:15], v108, s54, v[138:139]
	v_lshl_add_u64 v[108:109], v[108:109], 0, v[140:141]
	v_pk_add_f32 v[110:111], v[114:115], 0 op_sel_hi:[1,0]
	v_pk_add_f32 v[114:115], v[106:107], 0 op_sel_hi:[1,0]
	v_pk_add_f32 v[106:107], v[104:105], 0 op_sel_hi:[1,0]
	v_cvt_pk_bf16_f32 v104, v112, v113
	v_cvt_pk_bf16_f32 v105, v110, v111
	v_pk_add_f32 v[84:85], v[84:85], 0 op_sel_hi:[1,0]
	v_cvt_pk_bf16_f32 v106, v106, v107
	v_cvt_pk_bf16_f32 v107, v114, v115
	global_store_dwordx4 v[108:109], v[104:107], off
	v_pk_add_f32 v[86:87], v[86:87], 0 op_sel_hi:[1,0]
	v_pk_add_f32 v[80:81], v[80:81], 0 op_sel_hi:[1,0]
	v_pk_add_f32 v[104:105], v[94:95], 0 op_sel_hi:[1,0]
	v_pk_add_f32 v[94:95], v[92:93], 0 op_sel_hi:[1,0]
	v_cvt_pk_bf16_f32 v92, v100, v101
	v_cvt_pk_bf16_f32 v93, v102, v103
	v_pk_add_f32 v[68:69], v[68:69], 0 op_sel_hi:[1,0]
	v_cvt_pk_bf16_f32 v94, v94, v95
	v_cvt_pk_bf16_f32 v95, v104, v105
	global_store_dwordx4 v[108:109], v[92:95], off offset:256
	v_pk_add_f32 v[70:71], v[70:71], 0 op_sel_hi:[1,0]
	v_pk_add_f32 v[62:63], v[62:63], 0 op_sel_hi:[1,0]
	v_or_b32_e32 v92, 32, v155
	v_mad_i64_i32 v[92:93], s[14:15], v92, s54, v[138:139]
	v_lshl_add_u64 v[92:93], v[92:93], 0, v[140:141]
	v_pk_add_f32 v[94:95], v[98:99], 0 op_sel_hi:[1,0]
	v_pk_add_f32 v[98:99], v[90:91], 0 op_sel_hi:[1,0]
	v_pk_add_f32 v[90:91], v[88:89], 0 op_sel_hi:[1,0]
	v_cvt_pk_bf16_f32 v88, v96, v97
	v_cvt_pk_bf16_f32 v89, v94, v95
	v_pk_add_f32 v[60:61], v[60:61], 0 op_sel_hi:[1,0]
	v_cvt_pk_bf16_f32 v90, v90, v91
	v_cvt_pk_bf16_f32 v91, v98, v99
	global_store_dwordx4 v[92:93], v[88:91], off
	v_pk_add_f32 v[52:53], v[52:53], 0 op_sel_hi:[1,0]
	v_pk_add_f32 v[54:55], v[54:55], 0 op_sel_hi:[1,0]
	v_pk_add_f32 v[88:89], v[78:79], 0 op_sel_hi:[1,0]
	v_pk_add_f32 v[78:79], v[76:77], 0 op_sel_hi:[1,0]
	v_cvt_pk_bf16_f32 v76, v84, v85
	v_cvt_pk_bf16_f32 v77, v86, v87
	v_pk_add_f32 v[48:49], v[48:49], 0 op_sel_hi:[1,0]
	v_cvt_pk_bf16_f32 v78, v78, v79
	v_cvt_pk_bf16_f32 v79, v88, v89
	global_store_dwordx4 v[92:93], v[76:79], off offset:256
	v_pk_add_f32 v[36:37], v[36:37], 0 op_sel_hi:[1,0]
	v_pk_add_f32 v[38:39], v[38:39], 0 op_sel_hi:[1,0]
	v_or_b32_e32 v76, 48, v155
	v_mad_i64_i32 v[76:77], s[14:15], v76, s54, v[138:139]
	v_lshl_add_u64 v[76:77], v[76:77], 0, v[140:141]
	v_pk_add_f32 v[78:79], v[82:83], 0 op_sel_hi:[1,0]
	v_pk_add_f32 v[82:83], v[74:75], 0 op_sel_hi:[1,0]
	v_pk_add_f32 v[74:75], v[72:73], 0 op_sel_hi:[1,0]
	v_cvt_pk_bf16_f32 v72, v80, v81
	v_cvt_pk_bf16_f32 v73, v78, v79
	v_pk_add_f32 v[32:33], v[32:33], 0 op_sel_hi:[1,0]
; __device__ __forceinline__ unsigned cvt_pk_bf16(float lo, float hi) { unsigned r; asm volatile("v_cvt_pk_bf16_f32 %0, %1, %2" : "=v"(r) : "v"(lo), "v"(hi)); return r; }
; #define PG8_WAIT_V(n) asm volatile("s_waitcnt vmcnt(" #n ")" ::: "memory")
; #define PG8_BAR __builtin_amdgcn_s_barrier()
;     __device__ __forceinline__ void operator()(const f32x4 (&acc)[2][2][4][2], const Unit& u, int wr, int wc, int fr, int fq) const {
;     ...
;         for (int ai = 0; ai < 2; ++ai)
; #pragma unroll
;             for (int m = 0; m < 4; ++m) { bf16_t* rowp = O + (size_t)(row0 + ai * HALF + m * 16) * ldc + col0;
; #pragma unroll
;                 for (int bj = 0; bj < 2; ++bj) { f32x4 v0 = acc[ai][bj][m][0] + bv[bj][0], v1 = acc[ai][bj][m][1] + bv[bj][1];
;                     u32x4 w; w.x = cvt_pk_bf16(v0[0], v0[1]); w.y = cvt_pk_bf16(v0[2], v0[3]); w.z = cvt_pk_bf16(v1[0], v1[1]); w.w = cvt_pk_bf16(v1[2], v1[3]);
;                     *(u32x4*)(rowp + bj * HALF) = w; } }
;     }
; template <class Epi, class Sched>
; __device__ __forceinline__ void gemm_phase(LAS unsigned char* lds, const Gemm g, const Sched& S, const Epi& E) {
;     ...
;         if constexpr (!Epi::AFTER_DRAIN) E(acc, cur, wr, wc, fr, fq);
;         if (!has_next) break;
; #pragma unroll
;         for (int a = 0; a < 2; ++a)
; #pragma unroll
;             for (int b = 0; b < 2; ++b)
; #pragma unroll
;                 for (int m = 0; m < 4; ++m)
; #pragma unroll
;                     for (int n = 0; n < 2; ++n) acc[a][b][m][n] = (f32x4){0.f, 0.f, 0.f, 0.f};
;         cur = nxt; cA = nA; cB = nB; ++ui;
;     }
;     PG8_WAIT_V(0);
;     if (wr == 0) PG8_BAR;
;     PG8_BAR;
	v_cvt_pk_bf16_f32 v74, v74, v75
	v_cvt_pk_bf16_f32 v75, v82, v83
	global_store_dwordx4 v[76:77], v[72:75], off
	v_pk_add_f32 v[20:21], v[20:21], 0 op_sel_hi:[1,0]
	v_pk_add_f32 v[22:23], v[22:23], 0 op_sel_hi:[1,0]
	v_pk_add_f32 v[72:73], v[66:67], 0 op_sel_hi:[1,0]
	v_pk_add_f32 v[66:67], v[64:65], 0 op_sel_hi:[1,0]
	v_cvt_pk_bf16_f32 v64, v68, v69
	v_cvt_pk_bf16_f32 v65, v70, v71
	v_pk_add_f32 v[16:17], v[16:17], 0 op_sel_hi:[1,0]
	v_cvt_pk_bf16_f32 v66, v66, v67
	v_cvt_pk_bf16_f32 v67, v72, v73
	global_store_dwordx4 v[76:77], v[64:67], off offset:256
	s_and_b64 vcc, exec, s[0:1]
	s_mov_b32 s34, s6
	v_add_u32_e32 v64, 0x80, v155
	v_mad_i64_i32 v[64:65], s[14:15], v64, s54, v[138:139]
	v_lshl_add_u64 v[64:65], v[64:65], 0, v[140:141]
	v_pk_add_f32 v[66:67], v[58:59], 0 op_sel_hi:[1,0]
	v_pk_add_f32 v[58:59], v[56:57], 0 op_sel_hi:[1,0]
	v_cvt_pk_bf16_f32 v56, v60, v61
	v_cvt_pk_bf16_f32 v57, v62, v63
	s_mov_b32 s33, s8
	v_cvt_pk_bf16_f32 v58, v58, v59
	v_cvt_pk_bf16_f32 v59, v66, v67
	global_store_dwordx4 v[64:65], v[56:59], off
	s_mov_b64 s[16:17], s[10:11]
	v_pk_add_f32 v[6:7], v[6:7], 0 op_sel_hi:[1,0]
	v_pk_add_f32 v[56:57], v[46:47], 0 op_sel_hi:[1,0]
	v_pk_add_f32 v[46:47], v[44:45], 0 op_sel_hi:[1,0]
	v_cvt_pk_bf16_f32 v44, v52, v53
	v_cvt_pk_bf16_f32 v45, v54, v55
	v_pk_add_f32 v[4:5], v[4:5], 0 op_sel_hi:[1,0]
	v_cvt_pk_bf16_f32 v46, v46, v47
	v_cvt_pk_bf16_f32 v47, v56, v57
	global_store_dwordx4 v[64:65], v[44:47], off offset:256
	s_nop 1
	v_add_u32_e32 v44, 0x90, v155
	v_mad_i64_i32 v[44:45], s[14:15], v44, s54, v[138:139]
	v_lshl_add_u64 v[44:45], v[44:45], 0, v[140:141]
	v_pk_add_f32 v[46:47], v[50:51], 0 op_sel_hi:[1,0]
	v_pk_add_f32 v[50:51], v[42:43], 0 op_sel_hi:[1,0]
	v_pk_add_f32 v[42:43], v[40:41], 0 op_sel_hi:[1,0]
	v_cvt_pk_bf16_f32 v40, v48, v49
	v_cvt_pk_bf16_f32 v41, v46, v47
	s_nop 0
	v_cvt_pk_bf16_f32 v42, v42, v43
	v_cvt_pk_bf16_f32 v43, v50, v51
	global_store_dwordx4 v[44:45], v[40:43], off
	s_nop 1
	v_pk_add_f32 v[40:41], v[30:31], 0 op_sel_hi:[1,0]
	v_pk_add_f32 v[30:31], v[28:29], 0 op_sel_hi:[1,0]
	v_cvt_pk_bf16_f32 v28, v36, v37
	v_cvt_pk_bf16_f32 v29, v38, v39
	s_nop 0
	v_cvt_pk_bf16_f32 v30, v30, v31
	v_cvt_pk_bf16_f32 v31, v40, v41
	global_store_dwordx4 v[44:45], v[28:31], off offset:256
	s_nop 1
	v_add_u32_e32 v28, 0xa0, v155
	v_mad_i64_i32 v[28:29], s[14:15], v28, s54, v[138:139]
	v_lshl_add_u64 v[28:29], v[28:29], 0, v[140:141]
	v_pk_add_f32 v[30:31], v[34:35], 0 op_sel_hi:[1,0]
	v_pk_add_f32 v[34:35], v[26:27], 0 op_sel_hi:[1,0]
	v_pk_add_f32 v[26:27], v[24:25], 0 op_sel_hi:[1,0]
	v_cvt_pk_bf16_f32 v24, v32, v33
	v_cvt_pk_bf16_f32 v25, v30, v31
	s_nop 0
	v_cvt_pk_bf16_f32 v26, v26, v27
	v_cvt_pk_bf16_f32 v27, v34, v35
	global_store_dwordx4 v[28:29], v[24:27], off
	s_nop 1
	v_pk_add_f32 v[24:25], v[14:15], 0 op_sel_hi:[1,0]
	v_pk_add_f32 v[14:15], v[12:13], 0 op_sel_hi:[1,0]
	v_cvt_pk_bf16_f32 v12, v20, v21
	v_cvt_pk_bf16_f32 v13, v22, v23
	s_nop 0
	v_cvt_pk_bf16_f32 v14, v14, v15
	v_cvt_pk_bf16_f32 v15, v24, v25
	global_store_dwordx4 v[28:29], v[12:15], off offset:256
	s_nop 1
	v_add_u32_e32 v12, 0xb0, v155
	v_mad_i64_i32 v[12:13], s[14:15], v12, s54, v[138:139]
	v_lshl_add_u64 v[12:13], v[12:13], 0, v[140:141]
	v_pk_add_f32 v[14:15], v[18:19], 0 op_sel_hi:[1,0]
	v_pk_add_f32 v[18:19], v[10:11], 0 op_sel_hi:[1,0]
	v_pk_add_f32 v[10:11], v[8:9], 0 op_sel_hi:[1,0]
	v_cvt_pk_bf16_f32 v8, v16, v17
	v_cvt_pk_bf16_f32 v9, v14, v15
	s_mov_b64 s[14:15], s[12:13]
	v_cvt_pk_bf16_f32 v10, v10, v11
	v_cvt_pk_bf16_f32 v11, v18, v19
	global_store_dwordx4 v[12:13], v[8:11], off
	s_nop 1
	v_pk_add_f32 v[8:9], v[2:3], 0 op_sel_hi:[1,0]
	v_pk_add_f32 v[2:3], v[0:1], 0 op_sel_hi:[1,0]
	v_cvt_pk_bf16_f32 v0, v4, v5
	v_cvt_pk_bf16_f32 v1, v6, v7
	s_nop 0
	v_cvt_pk_bf16_f32 v2, v2, v3
	v_cvt_pk_bf16_f32 v3, v8, v9
	global_store_dwordx4 v[12:13], v[0:3], off offset:256
	s_cbranch_vccz .LBB0_789
	s_waitcnt vmcnt(0)
	s_cmpk_gt_u32 s2, 0xff
	s_cbranch_scc1 .LBB0_800
	s_barrier

; __device__ __forceinline__ float log_sigmoid(float x) { return -log1pf(expf(-x)); }
; __device__ __forceinline__ void m3_outputs(const KQ p_in, int e, bool ctx_full, unsigned char* smem, unsigned* scan_word) {
;     ...
;         const int t0 = chunk_t0(b, cidx); const bool lat = cidx < 32;
;         f32x4 O[4];
; #pragma unroll
;         for (int m = 0; m < 4; ++m) O[m] = (f32x4){0.f, 0.f, 0.f, 0.f};
;         if (!is_attn) {
;             const float lgf = log_sigmoid(dec[h]), lgb = log_sigmoid(dec[8 + h]);
;             __syncthreads();
.LBB0_960:
	v_add_u32_e32 v106, s7, v81
	s_bfe_u32 s6, s2, 0x30003
	s_mov_b64 s[0:1], -1
	s_andn2_b64 vcc, exec, s[36:37]
	v_ashrrev_i32_e32 v107, 31, v106
	v_lshlrev_b32_e32 v144, 1, v84
	s_cbranch_vccnz .LBB0_962
	s_lshl_b32 s0, s6, 2
	s_add_u32 s0, s73, s0
	s_addc_u32 s1, s64, 0
	v_mov_b64_e32 v[0:1], s[0:1]
	global_load_dword v2, v[0:1], off
	s_mov_b32 s0, 0xc2b17218
	global_load_dword v0, v[0:1], off offset:32
	s_mov_b32 s11, 0x3f2aaaab
	s_mov_b32 s12, 0x3f317218
	s_mov_b32 s1, 0x7f800000
	s_mov_b32 s10, 0x33800000
	s_lshl_b32 s80, s6, 7
	s_waitcnt lgkmcnt(0)
	s_barrier
	s_waitcnt vmcnt(2)
	s_waitcnt vmcnt(1)
	v_mul_f32_e32 v3, 0xbfb8aa3b, v2
	v_fma_f32 v4, v2, s42, -v3
	v_rndne_f32_e32 v5, v3
	v_fmac_f32_e32 v4, 0xb2a5705f, v2
	v_sub_f32_e32 v3, v3, v5
	v_add_f32_e32 v3, v3, v4
	v_exp_f32_e32 v3, v3
	v_cvt_i32_f32_e32 v4, v5
	v_cmp_nlt_f32_e32 vcc, s9, v2
	s_waitcnt vmcnt(0)
	v_mul_f32_e32 v1, 0xbfb8aa3b, v0
	v_ldexp_f32 v3, v3, v4
	v_cndmask_b32_e32 v3, 0, v3, vcc
	v_cmp_ngt_f32_e32 vcc, s0, v2
	s_nop 1
	v_cndmask_b32_e32 v16, v203, v3, vcc
	v_add_f32_e32 v4, 1.0, v16
	v_add_f32_e32 v2, -1.0, v4
	v_sub_f32_e32 v3, v2, v4
	v_add_f32_e32 v3, 1.0, v3
	v_sub_f32_e32 v2, v16, v2
	v_add_f32_e32 v5, v2, v3
	v_frexp_mant_f32_e32 v2, v4
	v_cmp_gt_f32_e32 vcc, s11, v2
	v_cvt_f64_f32_e32 v[2:3], v4
	v_frexp_exp_i32_f64_e32 v2, v[2:3]
	v_subbrev_co_u32_e32 v10, vcc, 0, v2, vcc
	v_sub_u32_e32 v2, 0, v10
	v_ldexp_f32 v3, v4, v2
	v_add_f32_e32 v4, -1.0, v3
	v_add_f32_e32 v6, 1.0, v3
	v_ldexp_f32 v2, v5, v2
	v_add_f32_e32 v5, 1.0, v4
	v_add_f32_e32 v7, -1.0, v6
	v_sub_f32_e32 v5, v3, v5
	v_sub_f32_e32 v3, v3, v7
	v_add_f32_e32 v5, v2, v5
	v_add_f32_e32 v2, v2, v3
	v_add_f32_e32 v11, v6, v2
	v_rcp_f32_e32 v13, v11
	v_sub_f32_e32 v3, v6, v11
	v_add_f32_e32 v12, v2, v3
	v_add_f32_e32 v3, v4, v5
	v_mul_f32_e32 v15, v3, v13
	v_sub_f32_e32 v2, v4, v3
	v_mul_f32_e32 v4, v11, v15
	v_fma_f32 v6, v15, v11, -v4
	v_fmac_f32_e32 v6, v15, v12
	v_add_f32_e32 v14, v5, v2
	v_add_f32_e32 v2, v4, v6
	v_sub_f32_e32 v5, v3, v2
	v_pk_add_f32 v[8:9], v[2:3], v[4:5] neg_lo:[0,1] neg_hi:[0,1]
	v_mov_b32_e32 v7, v2
	v_pk_add_f32 v[2:3], v[8:9], v[6:7] neg_lo:[0,1] neg_hi:[0,1]
	v_cmp_neq_f32_e32 vcc, s1, v16
	v_add_f32_e32 v3, v14, v3
	v_add_f32_e32 v2, v2, v3
	v_add_f32_e32 v3, v5, v2
	v_mul_f32_e32 v14, v13, v3
	v_mul_f32_e32 v4, v11, v14
	v_fma_f32 v6, v14, v11, -v4
	v_fmac_f32_e32 v6, v14, v12
	v_sub_f32_e32 v5, v5, v3
	v_add_f32_e32 v11, v2, v5
	v_add_f32_e32 v2, v4, v6
	v_sub_f32_e32 v5, v3, v2
	v_pk_add_f32 v[8:9], v[2:3], v[4:5] neg_lo:[0,1] neg_hi:[0,1]
	v_mov_b32_e32 v7, v2
	v_pk_add_f32 v[2:3], v[8:9], v[6:7] neg_lo:[0,1] neg_hi:[0,1]
	s_nop 0
	v_add_f32_e32 v3, v11, v3
	v_add_f32_e32 v2, v2, v3
	v_add_f32_e32 v3, v15, v14
	v_add_f32_e32 v2, v5, v2
	v_sub_f32_e32 v4, v3, v15
	v_mul_f32_e32 v2, v13, v2
	v_sub_f32_e32 v4, v14, v4
	v_add_f32_e32 v4, v4, v2
	v_add_f32_e32 v6, v3, v4
	v_mul_f32_e32 v7, v6, v6
	v_fmamk_f32 v2, v7, 0x3e9b6dac, v191
	v_fmaak_f32 v149, v7, v2, 0x3f2aaada
	v_cvt_f32_i32_e32 v2, v10
	v_sub_f32_e32 v3, v6, v3
	v_sub_f32_e32 v3, v4, v3
	v_ldexp_f32 v8, v3, 1
	v_mul_f32_e32 v3, v6, v7
	v_ldexp_f32 v5, v6, 1
	v_pk_mul_f32 v[6:7], v[2:3], v[148:149]
	s_nop 0
	v_fma_f32 v4, v2, s12, -v6
	v_fmac_f32_e32 v4, 0xb102e308, v2
	v_pk_add_f32 v[2:3], v[6:7], v[4:5]
	s_nop 0
	v_sub_f32_e32 v5, v3, v5
	v_sub_f32_e32 v5, v7, v5
	v_add_f32_e32 v9, v8, v5
	v_mov_b32_e32 v8, v6
	v_pk_add_f32 v[6:7], v[2:3], v[6:7] neg_lo:[0,1] neg_hi:[0,1]
	v_pk_add_f32 v[10:11], v[2:3], v[8:9]
	v_mov_b32_e32 v5, v2
	v_mov_b32_e32 v7, v11
	v_pk_add_f32 v[12:13], v[4:5], v[6:7] neg_lo:[0,1] neg_hi:[0,1]
	v_pk_add_f32 v[4:5], v[4:5], v[6:7]
	v_mov_b32_e32 v8, v9
	v_pk_add_f32 v[6:7], v[4:5], v[2:3] op_sel:[1,0] op_sel_hi:[0,1] neg_lo:[0,1] neg_hi:[0,1]
	v_pk_add_f32 v[14:15], v[10:11], v[6:7] op_sel_hi:[1,0] neg_lo:[0,1] neg_hi:[0,1]
	v_mov_b32_e32 v10, v11
	v_mov_b32_e32 v11, v5
	v_pk_mov_b32 v[6:7], v[2:3], v[6:7] op_sel:[1,0]
	v_mov_b32_e32 v9, v2
	v_pk_add_f32 v[6:7], v[10:11], v[6:7] neg_lo:[0,1] neg_hi:[0,1]
	v_mov_b32_e32 v14, v12
	v_pk_add_f32 v[2:3], v[8:9], v[6:7] neg_lo:[0,1] neg_hi:[0,1]
	v_mov_b32_e32 v13, v5
	v_pk_add_f32 v[6:7], v[14:15], v[2:3]
	s_nop 0
	v_pk_add_f32 v[8:9], v[6:7], v[6:7] op_sel:[0,1] op_sel_hi:[1,0]
	s_nop 0
	v_pk_add_f32 v[4:5], v[4:5], v[8:9] op_sel:[1,0] op_sel_hi:[0,1]
	v_mov_b32_e32 v7, v4
	v_pk_add_f32 v[10:11], v[6:7], v[12:13] neg_lo:[0,1] neg_hi:[0,1]
	v_mov_b32_e32 v3, v8
	v_sub_f32_e32 v5, v6, v10
	v_pk_add_f32 v[2:3], v[2:3], v[10:11] neg_lo:[0,1] neg_hi:[0,1]
	v_sub_f32_e32 v5, v12, v5
	v_add_f32_e32 v2, v2, v5
	v_add_f32_e32 v2, v2, v3
	v_add_f32_e32 v2, v4, v2
	v_cndmask_b32_e32 v2, v203, v2, vcc
	v_cmp_lt_f32_e64 vcc, |v16|, s10
	v_rndne_f32_e32 v3, v1
	s_nop 0
	v_cndmask_b32_e32 v26, v2, v16, vcc
	v_fma_f32 v2, v0, s42, -v1
	v_fmac_f32_e32 v2, 0xb2a5705f, v0
	v_sub_f32_e32 v1, v1, v3
	v_add_f32_e32 v1, v1, v2
	v_exp_f32_e32 v1, v1
	v_cvt_i32_f32_e32 v2, v3
	v_cmp_nlt_f32_e32 vcc, s9, v0
	v_ldexp_f32 v1, v1, v2
	s_nop 0
	v_cndmask_b32_e32 v1, 0, v1, vcc
	v_cmp_ngt_f32_e32 vcc, s0, v0
	s_nop 1
	v_cndmask_b32_e32 v14, v203, v1, vcc
	v_add_f32_e32 v2, 1.0, v14
	v_add_f32_e32 v0, -1.0, v2
	v_sub_f32_e32 v1, v0, v2
	v_add_f32_e32 v1, 1.0, v1
	v_sub_f32_e32 v0, v14, v0
	v_add_f32_e32 v3, v0, v1
	v_frexp_mant_f32_e32 v0, v2
	v_cmp_gt_f32_e32 vcc, s11, v0
	v_cvt_f64_f32_e32 v[0:1], v2
	v_frexp_exp_i32_f64_e32 v0, v[0:1]
	v_subbrev_co_u32_e32 v8, vcc, 0, v0, vcc
	v_sub_u32_e32 v0, 0, v8
	v_ldexp_f32 v1, v2, v0
	v_add_f32_e32 v2, -1.0, v1
	v_add_f32_e32 v4, 1.0, v1
	v_ldexp_f32 v0, v3, v0
	v_add_f32_e32 v3, 1.0, v2
	v_add_f32_e32 v5, -1.0, v4
; __device__ __forceinline__ float log_sigmoid(float x) { return -log1pf(expf(-x)); }
; __device__ __forceinline__ void m3_outputs(const KQ p_in, int e, bool ctx_full, unsigned char* smem, unsigned* scan_word) {
;     ...
;             const float lgf = log_sigmoid(dec[h]), lgb = log_sigmoid(dec[8 + h]);
;             __syncthreads();
; #pragma unroll
;             for (int q = 0; q < 2; ++q) { const int idx = tid + 512 * q; const int r = idx >> 3, pc = idx & 7; const bf16_t* zr = Z + (size_t)(t0 + r) * INW + h * 64 + pc * 8;
;                 *(u32x4*)(Kt + r * 72 + pc * 8) = *(const u32x4*)(zr + 1792);
;                 const bf16x8 vv = *(const bf16x8*)(zr + 2304);
; #pragma unroll
;                 for (int j = 0; j < 8; ++j) Vt[(pc * 8 + j) * 136 + (r ^ (pc << 2))] = (bf16_t)vv[j]; }
;             const size_t so = ((size_t)(b * NCH + cidx) * 8 + h) * 4096;
	v_sub_f32_e32 v3, v1, v3
	v_sub_f32_e32 v1, v1, v5
	v_add_f32_e32 v3, v0, v3
	v_add_f32_e32 v0, v0, v1
	v_add_f32_e32 v9, v4, v0
	v_rcp_f32_e32 v11, v9
	v_sub_f32_e32 v1, v4, v9
	v_add_f32_e32 v10, v0, v1
	v_add_f32_e32 v1, v2, v3
	v_mul_f32_e32 v13, v1, v11
	v_sub_f32_e32 v0, v2, v1
	v_mul_f32_e32 v2, v9, v13
	v_fma_f32 v4, v13, v9, -v2
	v_fmac_f32_e32 v4, v13, v10
	v_add_f32_e32 v12, v3, v0
	v_add_f32_e32 v0, v2, v4
	v_sub_f32_e32 v3, v1, v0
	v_pk_add_f32 v[6:7], v[0:1], v[2:3] neg_lo:[0,1] neg_hi:[0,1]
	v_mov_b32_e32 v5, v0
	v_pk_add_f32 v[0:1], v[6:7], v[4:5] neg_lo:[0,1] neg_hi:[0,1]
	v_cmp_neq_f32_e32 vcc, s1, v14
	v_add_f32_e32 v1, v12, v1
	v_add_f32_e32 v0, v0, v1
	v_add_f32_e32 v1, v3, v0
	v_mul_f32_e32 v12, v11, v1
	v_mul_f32_e32 v2, v9, v12
	v_fma_f32 v4, v12, v9, -v2
	v_fmac_f32_e32 v4, v12, v10
	v_sub_f32_e32 v3, v3, v1
	v_add_f32_e32 v9, v0, v3
	v_add_f32_e32 v0, v2, v4
	v_sub_f32_e32 v3, v1, v0
	v_pk_add_f32 v[6:7], v[0:1], v[2:3] neg_lo:[0,1] neg_hi:[0,1]
	v_mov_b32_e32 v5, v0
	v_pk_add_f32 v[0:1], v[6:7], v[4:5] neg_lo:[0,1] neg_hi:[0,1]
	s_nop 0
	v_add_f32_e32 v1, v9, v1
	v_add_f32_e32 v0, v0, v1
	v_add_f32_e32 v1, v13, v12
	v_add_f32_e32 v0, v3, v0
	v_sub_f32_e32 v2, v1, v13
	v_mul_f32_e32 v0, v11, v0
	v_sub_f32_e32 v2, v12, v2
	v_add_f32_e32 v2, v2, v0
	v_add_f32_e32 v4, v1, v2
	v_mul_f32_e32 v5, v4, v4
	v_fmamk_f32 v0, v5, 0x3e9b6dac, v191
	v_fmaak_f32 v149, v5, v0, 0x3f2aaada
	v_cvt_f32_i32_e32 v0, v8
	v_sub_f32_e32 v1, v4, v1
	v_sub_f32_e32 v1, v2, v1
	v_ldexp_f32 v6, v1, 1
	v_mul_f32_e32 v1, v4, v5
	v_ldexp_f32 v3, v4, 1
	v_pk_mul_f32 v[4:5], v[0:1], v[148:149]
	s_nop 0
	v_fma_f32 v2, v0, s12, -v4
	v_fmac_f32_e32 v2, 0xb102e308, v0
	v_pk_add_f32 v[0:1], v[4:5], v[2:3]
	s_nop 0
	v_sub_f32_e32 v3, v1, v3
	v_sub_f32_e32 v3, v5, v3
	v_add_f32_e32 v7, v6, v3
	v_mov_b32_e32 v6, v4
	v_pk_add_f32 v[4:5], v[0:1], v[4:5] neg_lo:[0,1] neg_hi:[0,1]
	v_pk_add_f32 v[8:9], v[0:1], v[6:7]
	v_mov_b32_e32 v3, v0
	v_mov_b32_e32 v5, v9
	v_pk_add_f32 v[10:11], v[2:3], v[4:5] neg_lo:[0,1] neg_hi:[0,1]
	v_pk_add_f32 v[2:3], v[2:3], v[4:5]
	v_mov_b32_e32 v6, v7
	v_pk_add_f32 v[4:5], v[2:3], v[0:1] op_sel:[1,0] op_sel_hi:[0,1] neg_lo:[0,1] neg_hi:[0,1]
	v_pk_add_f32 v[12:13], v[8:9], v[4:5] op_sel_hi:[1,0] neg_lo:[0,1] neg_hi:[0,1]
	v_mov_b32_e32 v8, v9
	v_mov_b32_e32 v9, v3
	v_pk_mov_b32 v[4:5], v[0:1], v[4:5] op_sel:[1,0]
	v_mov_b32_e32 v7, v0
	v_pk_add_f32 v[4:5], v[8:9], v[4:5] neg_lo:[0,1] neg_hi:[0,1]
	v_mov_b32_e32 v12, v10
	v_pk_add_f32 v[0:1], v[6:7], v[4:5] neg_lo:[0,1] neg_hi:[0,1]
	v_mov_b32_e32 v11, v3
	v_pk_add_f32 v[4:5], v[12:13], v[0:1]
	s_nop 0
	v_pk_add_f32 v[6:7], v[4:5], v[4:5] op_sel:[0,1] op_sel_hi:[1,0]
	s_nop 0
	v_pk_add_f32 v[2:3], v[2:3], v[6:7] op_sel:[1,0] op_sel_hi:[0,1]
	v_mov_b32_e32 v5, v2
	v_pk_add_f32 v[8:9], v[4:5], v[10:11] neg_lo:[0,1] neg_hi:[0,1]
	v_mov_b32_e32 v1, v6
	v_sub_f32_e32 v3, v4, v8
	v_pk_add_f32 v[0:1], v[0:1], v[8:9] neg_lo:[0,1] neg_hi:[0,1]
	v_sub_f32_e32 v3, v10, v3
	v_add_f32_e32 v0, v0, v3
	v_add_f32_e32 v0, v0, v1
	v_add_f32_e32 v0, v2, v0
	v_cndmask_b32_e32 v0, v203, v0, vcc
	v_cmp_lt_f32_e64 vcc, |v14|, s10
	v_add_u32_e32 v2, s7, v114
	s_nop 0
	v_cndmask_b32_e32 v27, v0, v14, vcc
	v_lshl_add_u64 v[0:1], v[82:83], 0, s[80:81]
	v_mad_i64_i32 v[6:7], s[0:1], v2, s54, v[0:1]
	global_load_dwordx4 v[2:5], v[6:7], off offset:3584
	s_waitcnt lgkmcnt(0)
	s_waitcnt vmcnt(0)
	ds_write_b128 v158, v[2:5]
	v_add_co_u32_e32 v2, vcc, s43, v6
	s_nop 1
	v_addc_co_u32_e32 v3, vcc, 0, v7, vcc
	global_load_dwordx4 v[2:5], v[2:3], off offset:512
	s_waitcnt lgkmcnt(0)
	s_waitcnt vmcnt(0)
	ds_write_b16 v159, v2 offset:18432
	ds_write_b16_d16_hi v159, v2 offset:18704
	ds_write_b16 v159, v3 offset:18976
	ds_write_b16_d16_hi v159, v3 offset:19248
	ds_write_b16 v159, v4 offset:19520
	ds_write_b16_d16_hi v159, v4 offset:19792
	ds_write_b16 v159, v5 offset:20064
	ds_write_b16_d16_hi v159, v5 offset:20336
	v_add_u32_e32 v2, s7, v115
	v_mad_i64_i32 v[4:5], s[0:1], v2, s54, v[0:1]
	global_load_dwordx4 v[0:3], v[4:5], off offset:3584
	s_mul_i32 s0, s5, 34
	s_add_i32 s0, s0, s8
	s_ashr_i32 s1, s0, 31
	s_lshl_b64 s[0:1], s[0:1], 15
	s_lshl_b32 s7, s6, 12
	s_or_b32 s0, s0, s7
	s_waitcnt lgkmcnt(0)
	s_waitcnt vmcnt(0)
	ds_write_b128 v160, v[0:3]
	v_add_co_u32_e32 v0, vcc, s43, v4
	s_nop 1
	v_addc_co_u32_e32 v1, vcc, 0, v5, vcc
	global_load_dwordx4 v[0:3], v[0:1], off offset:512
	s_waitcnt lgkmcnt(0)
	s_waitcnt vmcnt(0)
; __device__ __forceinline__ float bf2f(bf16_t b) { return __uint_as_float(((unsigned)b) << 16); }
; __device__ __forceinline__ unsigned cvt_pk_bf16(float lo, float hi) { unsigned r; asm volatile("v_cvt_pk_bf16_f32 %0, %1, %2" : "=v"(r) : "v"(lo), "v"(hi)); return r; }
; __device__ __forceinline__ void m3_outputs(const KQ p_in, int e, bool ctx_full, unsigned char* smem, unsigned* scan_word) {
;     ...
;             const size_t so = ((size_t)(b * NCH + cidx) * 8 + h) * 4096;
;             {
;                 const int ee = tid & 63, d0 = (tid >> 6) * 8;
;                 float tf[8], tb[8];
; #pragma unroll
;                 for (int j = 0; j < 8; ++j) { tf[j] = TF[so + (d0 + j) * 64 + ee]; tb[j] = TB[so + (d0 + j) * 64 + ee]; }
;                 u32x4 wf4, wb4;
;                 wf4.x = pg8::cvt_pk_bf16(tf[0], tf[1]); wf4.y = pg8::cvt_pk_bf16(tf[2], tf[3]); wf4.z = pg8::cvt_pk_bf16(tf[4], tf[5]); wf4.w = pg8::cvt_pk_bf16(tf[6], tf[7]);
;                 wb4.x = pg8::cvt_pk_bf16(tb[0], tb[1]); wb4.y = pg8::cvt_pk_bf16(tb[2], tb[3]); wb4.z = pg8::cvt_pk_bf16(tb[4], tb[5]); wb4.w = pg8::cvt_pk_bf16(tb[6], tb[7]);
;                 *(u32x4*)(TfT + ee * 72 + d0) = wf4; *(u32x4*)(TbT + ee * 72 + d0) = wb4;
;             }
;             __builtin_amdgcn_sched_barrier(0);
;             bf16x8 qf[2], qff[2], qfb[2];
;             { const bf16_t* qr = Z + (size_t)(t0 + i) * INW + 512 + h * 64 + 8 * g4;
;               const float cf = __expf(lgf * (float)(i + 1)), cb = __expf(lgb * (float)(128 - i));
; #pragma unroll
;               for (int k2 = 0; k2 < 2; ++k2) { qf[k2] = *(const bf16x8*)(qr + 32 * k2);
;                   f32x4 a0, a1, b0, b1;
; #pragma unroll
;                   for (int j = 0; j < 4; ++j) { const float x0 = bf2f((bf16_t)qf[k2][j]), x1 = bf2f((bf16_t)qf[k2][4 + j]); a0[j] = x0 * cf; a1[j] = x1 * cf; b0[j] = x0 * cb; b1[j] = x1 * cb; }
;                   qff[k2] = pack8(a0, a1); qfb[k2] = pack8(b0, b1); } }
;             __builtin_amdgcn_sched_barrier(0);
;             __syncthreads();
	ds_write_b16 v161, v0 offset:18432
	ds_write_b16_d16_hi v161, v0 offset:18704
	ds_write_b16 v161, v1 offset:18976
	ds_write_b16_d16_hi v161, v1 offset:19248
	ds_write_b16 v161, v2 offset:19520
	ds_write_b16_d16_hi v161, v2 offset:19792
	ds_write_b16 v161, v3 offset:20064
	ds_write_b16_d16_hi v161, v3 offset:20336
	v_mov_b32_e32 v3, s1
	v_or_b32_e32 v2, s0, v80
	v_lshl_add_u64 v[0:1], v[2:3], 0, v[90:91]
	v_lshl_add_u64 v[6:7], v[2:3], 0, v[92:93]
	v_lshl_add_u64 v[10:11], v[2:3], 0, v[94:95]
	v_lshl_add_u64 v[14:15], v[2:3], 0, v[96:97]
	v_lshl_add_u64 v[18:19], v[2:3], 0, v[98:99]
	v_lshlrev_b64 v[0:1], 2, v[0:1]
	v_lshlrev_b64 v[6:7], 2, v[6:7]
	v_lshlrev_b64 v[10:11], 2, v[10:11]
	v_lshlrev_b64 v[14:15], 2, v[14:15]
	v_lshlrev_b64 v[18:19], 2, v[18:19]
	v_lshl_add_u64 v[22:23], v[2:3], 0, v[100:101]
	v_lshl_add_u64 v[28:29], v[2:3], 0, v[102:103]
	v_lshl_add_u64 v[2:3], v[2:3], 0, v[104:105]
	v_lshl_add_u64 v[4:5], s[92:93], 0, v[0:1]
	v_lshl_add_u64 v[8:9], s[92:93], 0, v[6:7]
	v_lshl_add_u64 v[6:7], s[94:95], 0, v[6:7]
	v_lshl_add_u64 v[12:13], s[92:93], 0, v[10:11]
	v_lshl_add_u64 v[10:11], s[94:95], 0, v[10:11]
	v_lshl_add_u64 v[16:17], s[92:93], 0, v[14:15]
	v_lshl_add_u64 v[14:15], s[94:95], 0, v[14:15]
	v_lshl_add_u64 v[20:21], s[92:93], 0, v[18:19]
	v_lshl_add_u64 v[18:19], s[94:95], 0, v[18:19]
	v_lshlrev_b64 v[22:23], 2, v[22:23]
	v_lshlrev_b64 v[28:29], 2, v[28:29]
	v_lshlrev_b64 v[2:3], 2, v[2:3]
	v_lshl_add_u64 v[0:1], s[94:95], 0, v[0:1]
	v_lshl_add_u64 v[24:25], s[92:93], 0, v[22:23]
	v_lshl_add_u64 v[22:23], s[94:95], 0, v[22:23]
	v_lshl_add_u64 v[30:31], s[92:93], 0, v[28:29]
	v_lshl_add_u64 v[28:29], s[94:95], 0, v[28:29]
	v_lshl_add_u64 v[32:33], s[92:93], 0, v[2:3]
	v_lshl_add_u64 v[2:3], s[94:95], 0, v[2:3]
	global_load_dword v8, v[8:9], off
	s_nop 0
	global_load_dword v4, v[4:5], off
	s_nop 0
	global_load_dword v5, v[16:17], off
	global_load_dword v9, v[12:13], off
	s_nop 0
	global_load_dword v12, v[24:25], off
	global_load_dword v13, v[20:21], off
	global_load_dword v16, v[32:33], off
	global_load_dword v17, v[30:31], off
	s_nop 0
	global_load_dword v6, v[6:7], off
	s_nop 0
	global_load_dword v7, v[0:1], off
	s_nop 0
	global_load_dword v14, v[14:15], off
	s_nop 0
	global_load_dword v10, v[10:11], off
	s_nop 0
	global_load_dword v11, v[22:23], off
	global_load_dword v15, v[18:19], off
	s_nop 0
	global_load_dword v18, v[2:3], off
	global_load_dword v19, v[28:29], off
	s_waitcnt lgkmcnt(0)
	s_waitcnt vmcnt(14)
	v_cvt_pk_bf16_f32 v0, v4, v8
	s_waitcnt vmcnt(12)
	v_cvt_pk_bf16_f32 v1, v9, v5
	s_waitcnt vmcnt(10)
	v_cvt_pk_bf16_f32 v2, v13, v12
	s_waitcnt vmcnt(8)
	v_cvt_pk_bf16_f32 v3, v17, v16
	s_waitcnt vmcnt(6)
	v_cvt_pk_bf16_f32 v4, v7, v6
	s_waitcnt vmcnt(4)
	v_cvt_pk_bf16_f32 v5, v10, v14
	s_waitcnt vmcnt(2)
	v_cvt_pk_bf16_f32 v6, v15, v11
	s_waitcnt vmcnt(0)
	v_cvt_pk_bf16_f32 v7, v19, v18
	ds_write_b128 v85, v[0:3] offset:35840
	ds_write_b128 v85, v[4:7] offset:45056
	v_mov_b64_e32 v[0:1], s[88:89]
	v_mad_i64_i32 v[0:1], s[0:1], v106, s54, v[0:1]
	v_lshl_add_u64 v[24:25], v[0:1], 0, s[80:81]
	v_lshl_add_u64 v[4:5], v[24:25], 0, v[144:145]
	global_load_dwordx4 v[0:3], v[4:5], off offset:1024
	v_mul_f32_e32 v6, v87, v26
	v_mul_f32_e32 v7, v110, v27
	v_mul_f32_e32 v6, 0xbfb8aa3b, v6
	v_mul_f32_e32 v7, 0xbfb8aa3b, v7
	v_exp_f32_e32 v6, v6
	v_exp_f32_e32 v7, v7
	s_waitcnt lgkmcnt(0)
	s_waitcnt vmcnt(0)
	v_lshlrev_b32_e32 v8, 16, v0
	v_lshlrev_b32_e32 v9, 16, v2
	v_and_b32_e32 v10, 0xffff0000, v0
	v_and_b32_e32 v11, 0xffff0000, v2
	v_lshlrev_b32_e32 v12, 16, v1
	v_lshlrev_b32_e32 v13, 16, v3
	v_and_b32_e32 v14, 0xffff0000, v1
	v_and_b32_e32 v15, 0xffff0000, v3
	v_mul_f32_e32 v16, v6, v8
	v_mul_f32_e32 v18, v6, v9
	v_mul_f32_e32 v17, v6, v10
	v_mul_f32_e32 v19, v6, v11
	v_mul_f32_e32 v20, v6, v12
	v_mul_f32_e32 v21, v6, v13
	v_mul_f32_e32 v22, v6, v14
	v_mul_f32_e32 v23, v6, v15
	v_mul_f32_e32 v8, v7, v8
	v_mul_f32_e32 v9, v7, v9
	v_mul_f32_e32 v10, v7, v10
	v_mul_f32_e32 v11, v7, v11
	v_mul_f32_e32 v12, v7, v12
	v_mul_f32_e32 v13, v7, v13
	v_mul_f32_e32 v14, v7, v14
	v_mul_f32_e32 v15, v7, v15
	v_cvt_pk_bf16_f32 v16, v16, v17
	v_cvt_pk_bf16_f32 v17, v20, v22
	v_cvt_pk_bf16_f32 v18, v18, v19
	v_cvt_pk_bf16_f32 v19, v21, v23
	v_cvt_pk_bf16_f32 v28, v8, v10
	v_cvt_pk_bf16_f32 v29, v12, v14
	v_cvt_pk_bf16_f32 v30, v9, v11
	v_cvt_pk_bf16_f32 v31, v13, v15
	global_load_dwordx4 v[20:23], v[4:5], off offset:1088
	s_waitcnt lgkmcnt(0)
	s_waitcnt vmcnt(0)
	v_and_b32_e32 v8, 0xffff0000, v20
	v_and_b32_e32 v9, 0xffff0000, v22
	v_lshlrev_b32_e32 v10, 16, v21
	v_lshlrev_b32_e32 v11, 16, v23
	v_and_b32_e32 v12, 0xffff0000, v21
	v_lshlrev_b32_e32 v4, 16, v20
	v_lshlrev_b32_e32 v5, 16, v22
	v_and_b32_e32 v13, 0xffff0000, v23
	v_mul_f32_e32 v32, v6, v8
	v_mul_f32_e32 v34, v6, v9
	v_mul_f32_e32 v33, v6, v10
	v_mul_f32_e32 v35, v6, v11
	v_mul_f32_e32 v36, v6, v12
	v_mul_f32_e32 v14, v6, v4
	v_mul_f32_e32 v15, v6, v5
	v_mul_f32_e32 v4, v7, v4
	v_mul_f32_e32 v5, v7, v5
	v_mul_f32_e32 v8, v7, v8
	v_mul_f32_e32 v9, v7, v9
	v_mul_f32_e32 v10, v7, v10
	v_mul_f32_e32 v11, v7, v11
	v_mul_f32_e32 v6, v6, v13
	v_mul_f32_e32 v12, v7, v12
	v_mul_f32_e32 v7, v7, v13
	v_cvt_pk_bf16_f32 v32, v14, v32
	v_cvt_pk_bf16_f32 v33, v33, v36
	v_cvt_pk_bf16_f32 v34, v15, v34
	v_cvt_pk_bf16_f32 v35, v35, v6
	v_cvt_pk_bf16_f32 v36, v4, v8
	v_cvt_pk_bf16_f32 v37, v10, v12
	v_cvt_pk_bf16_f32 v38, v5, v9
	v_cvt_pk_bf16_f32 v39, v11, v7
	s_barrier
; __device__ __forceinline__ void m3_outputs(const KQ p_in, int e, bool ctx_full, unsigned char* smem, unsigned* scan_word) {
;     ...
; #pragma unroll
;             for (int m = 0; m < 4; ++m)
; #pragma unroll
;                 for (int k2 = 0; k2 < 2; ++k2) {
;                     const bf16x8 af = *(const bf16x8*)(TfT + (16 * m + ln) * 72 + 32 * k2 + 8 * g4);
;                     const bf16x8 ab = *(const bf16x8*)(TbT + (16 * m + ln) * 72 + 32 * k2 + 8 * g4);
;                     O[m] = __builtin_amdgcn_mfma_f32_16x16x32_bf16(af, qff[k2], O[m], 0, 0, 0);
;                     O[m] = __builtin_amdgcn_mfma_f32_16x16x32_bf16(ab, qfb[k2], O[m], 0, 0, 0);
;                     __builtin_amdgcn_sched_barrier(0);
;                 }
;             const float lf2 = lgf * 1.44269504f, lb2 = lgb * 1.44269504f; const int di = i - 4 * g4;
;             const float bfw = lf2 * (float)di, bbw = -lb2 * (float)di;
;             f32x4 st[8];
; #pragma unroll
;             for (int mt = 0; mt < 8; ++mt) {
;                 f32x4 a = (f32x4){0.f, 0.f, 0.f, 0.f};
; #pragma unroll
;                 for (int k2 = 0; k2 < 2; ++k2) { const bf16x8 kf = *(const bf16x8*)(Kt + (16 * mt + ln) * 72 + 32 * k2 + 8 * g4); a = __builtin_amdgcn_mfma_f32_16x16x32_bf16(kf, qf[k2], a, 0, 0, 0); }
; #pragma unroll
;                 for (int rg = 0; rg < 4; ++rg) { const int cc = 16 * mt + rg; const int df = di - cc;
;                     const float arg = (df > 0) ? fmaf(-lf2, (float)cc, bfw) : fmaf(lb2, (float)cc, bbw);
;                     float wgt = __builtin_amdgcn_exp2f(arg); wgt = (df == 0) ? 2.0f : wgt;
;                     a[rg] *= wgt; }
;                 st[mt] = a;
;                 __builtin_amdgcn_sched_barrier(0);
;             }
	ds_read_b128 v[4:7], v116 offset:35840
	ds_read_b128 v[8:11], v116 offset:45056
	s_waitcnt lgkmcnt(1)
	v_mfma_f32_16x16x32_bf16 v[4:7], v[4:7], v[16:19], 0
	s_waitcnt lgkmcnt(0)
	v_mfma_f32_16x16x32_bf16 v[4:7], v[8:11], v[28:31], v[4:7]
	ds_read_b128 v[8:11], v116 offset:35904
	s_waitcnt lgkmcnt(0)
	v_mfma_f32_16x16x32_bf16 v[4:7], v[8:11], v[32:35], v[4:7]
	ds_read_b128 v[8:11], v116 offset:45120
	s_waitcnt lgkmcnt(0)
	v_mfma_f32_16x16x32_bf16 v[4:7], v[8:11], v[36:39], v[4:7]
	ds_read_b128 v[8:11], v116 offset:38144
	ds_read_b128 v[12:15], v116 offset:47360
	s_waitcnt lgkmcnt(1)
	v_mfma_f32_16x16x32_bf16 v[8:11], v[8:11], v[16:19], 0
	s_waitcnt lgkmcnt(0)
	v_mfma_f32_16x16x32_bf16 v[8:11], v[12:15], v[28:31], v[8:11]
	ds_read_b128 v[12:15], v116 offset:38208
	s_waitcnt lgkmcnt(0)
	v_mfma_f32_16x16x32_bf16 v[8:11], v[12:15], v[32:35], v[8:11]
	ds_read_b128 v[12:15], v116 offset:47424
	s_waitcnt lgkmcnt(0)
	v_mfma_f32_16x16x32_bf16 v[8:11], v[12:15], v[36:39], v[8:11]
	ds_read_b128 v[12:15], v116 offset:40448
	ds_read_b128 v[40:43], v116 offset:49664
	s_waitcnt lgkmcnt(1)
	v_mfma_f32_16x16x32_bf16 v[12:15], v[12:15], v[16:19], 0
	s_waitcnt lgkmcnt(0)
	v_mfma_f32_16x16x32_bf16 v[12:15], v[40:43], v[28:31], v[12:15]
	ds_read_b128 v[40:43], v116 offset:40512
	s_waitcnt lgkmcnt(0)
	v_mfma_f32_16x16x32_bf16 v[12:15], v[40:43], v[32:35], v[12:15]
	ds_read_b128 v[40:43], v116 offset:49728
	s_waitcnt lgkmcnt(0)
	v_mfma_f32_16x16x32_bf16 v[12:15], v[40:43], v[36:39], v[12:15]
	ds_read_b128 v[40:43], v116 offset:42752
	s_waitcnt lgkmcnt(0)
	v_mfma_f32_16x16x32_bf16 v[16:19], v[40:43], v[16:19], 0
	ds_read_b128 v[40:43], v116 offset:51968
	s_waitcnt lgkmcnt(0)
	v_mfma_f32_16x16x32_bf16 v[16:19], v[40:43], v[28:31], v[16:19]
	ds_read_b128 v[28:31], v116 offset:42816
	s_waitcnt lgkmcnt(0)
	v_mfma_f32_16x16x32_bf16 v[16:19], v[28:31], v[32:35], v[16:19]
	ds_read_b128 v[28:31], v116 offset:52032
	s_waitcnt lgkmcnt(0)
	v_mfma_f32_16x16x32_bf16 v[16:19], v[28:31], v[36:39], v[16:19]
	v_add_u32_e32 v33, v111, v117
	ds_read_b128 v[34:37], v33
	ds_read_b128 v[38:41], v33 offset:64
	v_mul_f32_e32 v28, 0xbfb8aa3b, v26
	v_mul_f32_e32 v26, 0xbfb8aa3b, v27
	v_mul_f32_e32 v27, v28, v112
	v_mul_f32_e64 v29, v112, -v26
	v_readlane_b32 s0, v253, 41
	v_fmamk_f32 v30, v28, 0x80000000, v27
	v_fma_f32 v31, 0, v26, v29
	v_readlane_b32 s1, v253, 42
	s_waitcnt lgkmcnt(1)
	v_mfma_f32_16x16x32_bf16 v[34:37], v[34:37], v[0:3], 0
	v_fma_f32 v32, v112, -v26, v26
	v_cndmask_b32_e64 v30, v31, v30, s[0:1]
	v_exp_f32_e32 v30, v30
	v_readlane_b32 s0, v253, 43
	v_readlane_b32 s1, v253, 44
	v_fma_f32 v31, v28, v112, -v28
	s_waitcnt lgkmcnt(0)
	v_mfma_f32_16x16x32_bf16 v[34:37], v[38:41], v[20:23], v[34:37]
	v_cndmask_b32_e64 v30, v30, 2.0, s[0:1]
	v_readlane_b32 s0, v253, 45
	v_readlane_b32 s1, v253, 46
	s_nop 1
	v_cndmask_b32_e64 v31, v32, v31, s[0:1]
	v_exp_f32_e32 v31, v31
	v_readlane_b32 s0, v253, 47
	v_readlane_b32 s1, v253, 48
	v_mul_f32_e32 v30, v30, v34
	v_fma_f32 v32, -2.0, v28, v27
	v_cndmask_b32_e64 v31, v31, 2.0, s[0:1]
	v_readlane_b32 s0, v253, 49
	v_fma_f32 v34, 2.0, v26, v29
	v_readlane_b32 s1, v253, 50
	v_mul_f32_e32 v31, v31, v35
	v_fmamk_f32 v35, v26, 0x40400000, v29
	v_cndmask_b32_e64 v32, v34, v32, s[0:1]
	v_exp_f32_e32 v32, v32
	v_readlane_b32 s0, v253, 51
	v_readlane_b32 s1, v253, 52
	v_fmamk_f32 v34, v28, 0xc0400000, v27
	s_nop 0
	v_cndmask_b32_e64 v32, v32, 2.0, s[0:1]
	v_readlane_b32 s0, v253, 53
	v_readlane_b32 s1, v253, 54
	v_mul_f32_e32 v32, v32, v36
	s_nop 0
	v_cndmask_b32_e64 v34, v35, v34, s[0:1]
	v_exp_f32_e32 v34, v34
	v_readlane_b32 s0, v253, 55
	v_readlane_b32 s1, v253, 56
	s_nop 1
	v_cndmask_b32_e64 v34, v34, 2.0, s[0:1]
	v_mul_f32_e32 v34, v34, v37
	ds_read_b128 v[36:39], v33 offset:2304
	ds_read_b128 v[40:43], v33 offset:2368
	v_readlane_b32 s0, v253, 57
	v_fmamk_f32 v35, v28, 0xc1800000, v27
	v_readlane_b32 s1, v253, 58
	s_waitcnt lgkmcnt(1)
	v_mfma_f32_16x16x32_bf16 v[36:39], v[36:39], v[0:3], 0
	s_waitcnt lgkmcnt(0)
	v_mfma_f32_16x16x32_bf16 v[36:39], v[40:43], v[20:23], v[36:39]
	v_fmamk_f32 v40, v26, 0x41800000, v29
	v_cndmask_b32_e64 v35, v40, v35, s[0:1]
	v_exp_f32_e32 v35, v35
	v_readlane_b32 s0, v253, 59
	v_readlane_b32 s1, v253, 60
	v_fmamk_f32 v40, v26, 0x41880000, v29
	s_nop 0
	v_cndmask_b32_e64 v35, v35, 2.0, s[0:1]
	v_readlane_b32 s0, v253, 61
	v_mul_f32_e32 v35, v35, v36
	v_fmamk_f32 v36, v28, 0xc1880000, v27
	v_readlane_b32 s1, v253, 62
	s_nop 1
	v_cndmask_b32_e64 v36, v40, v36, s[0:1]
	v_exp_f32_e32 v36, v36
	v_readlane_b32 s0, v253, 63
	v_readlane_b32 s1, v254, 0
	v_fmamk_f32 v40, v26, 0x41900000, v29
	s_nop 0
	v_cndmask_b32_e64 v36, v36, 2.0, s[0:1]
	v_readlane_b32 s0, v254, 1
	v_mul_f32_e32 v36, v36, v37
	v_fmamk_f32 v37, v28, 0xc1900000, v27
	v_readlane_b32 s1, v254, 2
	s_nop 1
	v_cndmask_b32_e64 v37, v40, v37, s[0:1]
	v_exp_f32_e32 v37, v37
	v_readlane_b32 s0, v254, 3
	v_readlane_b32 s1, v254, 4
	v_fmamk_f32 v40, v26, 0x41980000, v29
	s_nop 0
	v_cndmask_b32_e64 v37, v37, 2.0, s[0:1]
	v_readlane_b32 s0, v254, 5
	v_mul_f32_e32 v38, v37, v38
	v_fmamk_f32 v37, v28, 0xc1980000, v27
	v_readlane_b32 s1, v254, 6
	s_nop 1
	v_cndmask_b32_e64 v37, v40, v37, s[0:1]
	v_exp_f32_e32 v37, v37
	v_readlane_b32 s0, v254, 7
	v_readlane_b32 s1, v254, 8
	s_nop 1
	v_cndmask_b32_e64 v37, v37, 2.0, s[0:1]
	v_mul_f32_e32 v40, v37, v39
	ds_read_b128 v[42:45], v33 offset:4608
	ds_read_b128 v[46:49], v33 offset:4672
	v_readlane_b32 s0, v254, 9
	v_fmamk_f32 v37, v28, 0xc2000000, v27
	v_fmamk_f32 v39, v26, 0x42000000, v29
	v_readlane_b32 s1, v254, 10
	v_fmamk_f32 v41, v26, 0x42040000, v29
	s_waitcnt lgkmcnt(1)
; __device__ __forceinline__ void m3_outputs(const KQ p_in, int e, bool ctx_full, unsigned char* smem, unsigned* scan_word) {
;     ...
;             for (int mt = 0; mt < 8; ++mt) {
;                 f32x4 a = (f32x4){0.f, 0.f, 0.f, 0.f};
; #pragma unroll
;                 for (int k2 = 0; k2 < 2; ++k2) { const bf16x8 kf = *(const bf16x8*)(Kt + (16 * mt + ln) * 72 + 32 * k2 + 8 * g4); a = __builtin_amdgcn_mfma_f32_16x16x32_bf16(kf, qf[k2], a, 0, 0, 0); }
; #pragma unroll
;                 for (int rg = 0; rg < 4; ++rg) { const int cc = 16 * mt + rg; const int df = di - cc;
;                     const float arg = (df > 0) ? fmaf(-lf2, (float)cc, bfw) : fmaf(lb2, (float)cc, bbw);
;                     float wgt = __builtin_amdgcn_exp2f(arg); wgt = (df == 0) ? 2.0f : wgt;
;                     a[rg] *= wgt; }
;                 st[mt] = a;
;                 __builtin_amdgcn_sched_barrier(0);
;             }
	v_mfma_f32_16x16x32_bf16 v[42:45], v[42:45], v[0:3], 0
	v_cndmask_b32_e64 v37, v39, v37, s[0:1]
	v_exp_f32_e32 v37, v37
	v_readlane_b32 s0, v254, 11
	v_readlane_b32 s1, v254, 12
	v_fmamk_f32 v39, v28, 0xc2040000, v27
	s_waitcnt lgkmcnt(0)
	v_mfma_f32_16x16x32_bf16 v[42:45], v[46:49], v[20:23], v[42:45]
	v_cndmask_b32_e64 v37, v37, 2.0, s[0:1]
	v_readlane_b32 s0, v254, 13
	v_readlane_b32 s1, v254, 14
	s_nop 1
	v_cndmask_b32_e64 v39, v41, v39, s[0:1]
	v_exp_f32_e32 v39, v39
	v_readlane_b32 s0, v254, 15
	v_readlane_b32 s1, v254, 16
	v_mul_f32_e32 v37, v37, v42
	v_fmamk_f32 v41, v28, 0xc2080000, v27
	v_cndmask_b32_e64 v39, v39, 2.0, s[0:1]
	v_readlane_b32 s0, v254, 17
	v_fmamk_f32 v42, v26, 0x42080000, v29
	v_readlane_b32 s1, v254, 18
	v_mul_f32_e32 v39, v39, v43
	v_fmamk_f32 v43, v26, 0x420c0000, v29
	v_cndmask_b32_e64 v41, v42, v41, s[0:1]
	v_exp_f32_e32 v41, v41
	v_readlane_b32 s0, v254, 19
	v_readlane_b32 s1, v254, 20
	v_fmamk_f32 v42, v28, 0xc20c0000, v27
	s_nop 0
	v_cndmask_b32_e64 v41, v41, 2.0, s[0:1]
	v_readlane_b32 s0, v254, 21
	v_readlane_b32 s1, v254, 22
	v_mul_f32_e32 v41, v41, v44
	s_nop 0
	v_cndmask_b32_e64 v42, v43, v42, s[0:1]
	v_exp_f32_e32 v42, v42
	v_readlane_b32 s0, v254, 23
	v_readlane_b32 s1, v254, 24
	s_nop 1
	v_cndmask_b32_e64 v42, v42, 2.0, s[0:1]
	v_mul_f32_e32 v42, v42, v45
	ds_read_b128 v[44:47], v33 offset:6912
	ds_read_b128 v[48:51], v33 offset:6976
	v_readlane_b32 s0, v254, 25
	v_fmamk_f32 v43, v28, 0xc2400000, v27
	v_readlane_b32 s1, v254, 26
	s_waitcnt lgkmcnt(1)
	v_mfma_f32_16x16x32_bf16 v[44:47], v[44:47], v[0:3], 0
	s_waitcnt lgkmcnt(0)
	v_mfma_f32_16x16x32_bf16 v[44:47], v[48:51], v[20:23], v[44:47]
	v_fmamk_f32 v48, v26, 0x42400000, v29
	v_cndmask_b32_e64 v43, v48, v43, s[0:1]
	v_exp_f32_e32 v43, v43
	v_readlane_b32 s0, v254, 27
	v_readlane_b32 s1, v254, 28
	v_fmamk_f32 v48, v26, 0x42440000, v29
	s_nop 0
	v_cndmask_b32_e64 v43, v43, 2.0, s[0:1]
	v_readlane_b32 s0, v254, 29
	v_mul_f32_e32 v43, v43, v44
	v_fmamk_f32 v44, v28, 0xc2440000, v27
	v_readlane_b32 s1, v254, 30
	s_nop 1
	v_cndmask_b32_e64 v44, v48, v44, s[0:1]
	v_exp_f32_e32 v44, v44
	v_readlane_b32 s0, v254, 31
	v_readlane_b32 s1, v254, 32
	v_fmamk_f32 v48, v26, 0x42480000, v29
	s_nop 0
	v_cndmask_b32_e64 v44, v44, 2.0, s[0:1]
	v_readlane_b32 s0, v254, 33
	v_mul_f32_e32 v44, v44, v45
	v_fmamk_f32 v45, v28, 0xc2480000, v27
	v_readlane_b32 s1, v254, 34
	s_nop 1
	v_cndmask_b32_e64 v45, v48, v45, s[0:1]
	v_exp_f32_e32 v45, v45
	v_readlane_b32 s0, v254, 35
	v_readlane_b32 s1, v254, 36
	v_fmamk_f32 v48, v26, 0x424c0000, v29
	s_nop 0
	v_cndmask_b32_e64 v45, v45, 2.0, s[0:1]
	v_readlane_b32 s0, v254, 37
	v_mul_f32_e32 v45, v45, v46
	v_fmamk_f32 v46, v28, 0xc24c0000, v27
	v_readlane_b32 s1, v254, 38
	s_nop 1
	v_cndmask_b32_e64 v46, v48, v46, s[0:1]
	v_exp_f32_e32 v46, v46
	v_readlane_b32 s0, v254, 39
	v_readlane_b32 s1, v254, 40
	s_nop 1
	v_cndmask_b32_e64 v46, v46, 2.0, s[0:1]
	v_mul_f32_e32 v54, v46, v47
	ds_read_b128 v[46:49], v33 offset:9216
	ds_read_b128 v[50:53], v33 offset:9280
	v_readlane_b32 s0, v254, 41
	v_readlane_b32 s1, v254, 42
	s_waitcnt lgkmcnt(1)
	v_mfma_f32_16x16x32_bf16 v[46:49], v[46:49], v[0:3], 0
	s_waitcnt lgkmcnt(0)
	v_mfma_f32_16x16x32_bf16 v[46:49], v[50:53], v[20:23], v[46:49]
	v_fmamk_f32 v50, v28, 0xc2800000, v27
	v_fmamk_f32 v51, v26, 0x42800000, v29
	v_cndmask_b32_e64 v50, v51, v50, s[0:1]
	v_exp_f32_e32 v50, v50
	v_readlane_b32 s0, v254, 43
	v_readlane_b32 s1, v254, 44
	s_nop 1
	v_cndmask_b32_e64 v50, v50, 2.0, s[0:1]
	v_readlane_b32 s0, v254, 45
	v_mul_f32_e32 v55, v50, v46
	v_fmamk_f32 v46, v28, 0xc2820000, v27
	v_fmamk_f32 v50, v26, 0x42820000, v29
	v_readlane_b32 s1, v254, 46
	s_nop 1
	v_cndmask_b32_e64 v46, v50, v46, s[0:1]
	v_exp_f32_e32 v46, v46
	v_readlane_b32 s0, v254, 47
	v_readlane_b32 s1, v254, 48
	s_nop 1
	v_cndmask_b32_e64 v46, v46, 2.0, s[0:1]
	v_readlane_b32 s0, v254, 49
	v_mul_f32_e32 v56, v46, v47
	v_fmamk_f32 v46, v28, 0xc2840000, v27
	v_fmamk_f32 v47, v26, 0x42840000, v29
	v_readlane_b32 s1, v254, 50
	s_nop 1
	v_cndmask_b32_e64 v46, v47, v46, s[0:1]
	v_exp_f32_e32 v46, v46
	v_readlane_b32 s0, v254, 51
	v_readlane_b32 s1, v254, 52
	v_fmamk_f32 v47, v26, 0x42860000, v29
	s_nop 0
	v_cndmask_b32_e64 v46, v46, 2.0, s[0:1]
	v_readlane_b32 s0, v254, 53
	v_mul_f32_e32 v57, v46, v48
	v_fmamk_f32 v46, v28, 0xc2860000, v27
	v_readlane_b32 s1, v254, 54
	s_nop 1
	v_cndmask_b32_e64 v46, v47, v46, s[0:1]
	v_exp_f32_e32 v46, v46
	v_readlane_b32 s0, v254, 55
	v_readlane_b32 s1, v254, 56
	s_nop 1
	v_cndmask_b32_e64 v46, v46, 2.0, s[0:1]
	v_mul_f32_e32 v58, v46, v49
	ds_read_b128 v[46:49], v33 offset:11520
	ds_read_b128 v[50:53], v33 offset:11584
	v_readlane_b32 s0, v254, 57
	v_readlane_b32 s1, v254, 58
	s_waitcnt lgkmcnt(1)
	v_mfma_f32_16x16x32_bf16 v[46:49], v[46:49], v[0:3], 0
	s_waitcnt lgkmcnt(0)
	v_mfma_f32_16x16x32_bf16 v[46:49], v[50:53], v[20:23], v[46:49]
	v_fmamk_f32 v50, v28, 0xc2a00000, v27
	v_fmamk_f32 v51, v26, 0x42a00000, v29
	v_cndmask_b32_e64 v50, v51, v50, s[0:1]
	v_exp_f32_e32 v50, v50
	v_readlane_b32 s0, v254, 59
	v_readlane_b32 s1, v254, 60
	s_nop 1
	v_cndmask_b32_e64 v50, v50, 2.0, s[0:1]
	v_readlane_b32 s0, v254, 61
	v_mul_f32_e32 v59, v50, v46
	v_fmamk_f32 v46, v28, 0xc2a20000, v27
	v_fmamk_f32 v50, v26, 0x42a20000, v29
	v_readlane_b32 s1, v254, 62
	s_nop 1
	v_cndmask_b32_e64 v46, v50, v46, s[0:1]
	v_exp_f32_e32 v46, v46
	v_readlane_b32 s0, v254, 63
	v_readlane_b32 s1, v255, 0
	s_nop 1
	v_cndmask_b32_e64 v46, v46, 2.0, s[0:1]
	v_readlane_b32 s0, v255, 1
	v_mul_f32_e32 v60, v46, v47
	v_fmamk_f32 v46, v28, 0xc2a40000, v27
	v_fmamk_f32 v47, v26, 0x42a40000, v29
	v_readlane_b32 s1, v255, 2
	s_nop 1
	v_cndmask_b32_e64 v46, v47, v46, s[0:1]
	v_exp_f32_e32 v46, v46
	v_readlane_b32 s0, v255, 3
	v_readlane_b32 s1, v255, 4
	v_fmamk_f32 v47, v26, 0x42a60000, v29
	s_nop 0
	v_cndmask_b32_e64 v46, v46, 2.0, s[0:1]
	v_readlane_b32 s0, v255, 5
	v_mul_f32_e32 v61, v46, v48
	v_fmamk_f32 v46, v28, 0xc2a60000, v27
	v_readlane_b32 s1, v255, 6
	s_nop 1
	v_cndmask_b32_e64 v46, v47, v46, s[0:1]
	v_exp_f32_e32 v46, v46
	v_readlane_b32 s0, v255, 7
	v_readlane_b32 s1, v255, 8
	s_nop 1
	v_cndmask_b32_e64 v46, v46, 2.0, s[0:1]
	v_mul_f32_e32 v62, v46, v49
	ds_read_b128 v[46:49], v33 offset:13824
	ds_read_b128 v[50:53], v33 offset:13888
	v_readlane_b32 s0, v255, 9
	v_readlane_b32 s1, v255, 10
	s_waitcnt lgkmcnt(1)
; __device__ __forceinline__ void m3_outputs(const KQ p_in, int e, bool ctx_full, unsigned char* smem, unsigned* scan_word) {
;     ...
;             for (int mt = 0; mt < 8; ++mt) {
;                 f32x4 a = (f32x4){0.f, 0.f, 0.f, 0.f};
; #pragma unroll
;                 for (int k2 = 0; k2 < 2; ++k2) { const bf16x8 kf = *(const bf16x8*)(Kt + (16 * mt + ln) * 72 + 32 * k2 + 8 * g4); a = __builtin_amdgcn_mfma_f32_16x16x32_bf16(kf, qf[k2], a, 0, 0, 0); }
; #pragma unroll
;                 for (int rg = 0; rg < 4; ++rg) { const int cc = 16 * mt + rg; const int df = di - cc;
;                     const float arg = (df > 0) ? fmaf(-lf2, (float)cc, bfw) : fmaf(lb2, (float)cc, bbw);
;                     float wgt = __builtin_amdgcn_exp2f(arg); wgt = (df == 0) ? 2.0f : wgt;
;                     a[rg] *= wgt; }
;                 st[mt] = a;
;                 __builtin_amdgcn_sched_barrier(0);
;             }
; #pragma unroll
;             for (int ks = 0; ks < 4; ++ks) {
;                 const bf16x8 pfr = pack8(st[2 * ks], st[2 * ks + 1]);
; #pragma unroll
;                 for (int m = 0; m < 4; ++m) {
;                     const int vrow = 16 * m + ln; const int kx = (32 * ks + 4 * g4) ^ (((vrow >> 3) & 7) << 2);
;                     const bf16_t* vr = Vt + vrow * 136;
;                     const bf16x4 v0 = *(const bf16x4*)(vr + kx), v1 = *(const bf16x4*)(vr + (kx ^ 16));
;                     const bf16x8 vf = __builtin_shufflevector(v0, v1, 0, 1, 2, 3, 4, 5, 6, 7);
;                     O[m] = __builtin_amdgcn_mfma_f32_16x16x32_bf16(vf, pfr, O[m], 0, 0, 0);
;                 }
;                 __builtin_amdgcn_sched_barrier(0);
;             }
	v_mfma_f32_16x16x32_bf16 v[46:49], v[46:49], v[0:3], 0
	s_waitcnt lgkmcnt(0)
	v_mfma_f32_16x16x32_bf16 v[46:49], v[50:53], v[20:23], v[46:49]
	v_fmamk_f32 v50, v28, 0xc2c00000, v27
	v_fmamk_f32 v51, v26, 0x42c00000, v29
	v_cndmask_b32_e64 v50, v51, v50, s[0:1]
	v_exp_f32_e32 v50, v50
	v_readlane_b32 s0, v255, 11
	v_readlane_b32 s1, v255, 12
	v_fmamk_f32 v51, v26, 0x42c20000, v29
	s_nop 0
	v_cndmask_b32_e64 v50, v50, 2.0, s[0:1]
	v_readlane_b32 s0, v255, 13
	v_mul_f32_e32 v50, v50, v46
	v_fmamk_f32 v46, v28, 0xc2c20000, v27
	v_readlane_b32 s1, v255, 14
	s_nop 1
	v_cndmask_b32_e64 v46, v51, v46, s[0:1]
	v_exp_f32_e32 v46, v46
	v_readlane_b32 s0, v255, 15
	v_readlane_b32 s1, v255, 16
	s_nop 1
	v_cndmask_b32_e64 v46, v46, 2.0, s[0:1]
	v_readlane_b32 s0, v255, 17
	v_mul_f32_e32 v51, v46, v47
	v_fmamk_f32 v46, v28, 0xc2c40000, v27
	v_fmamk_f32 v47, v26, 0x42c40000, v29
	v_readlane_b32 s1, v255, 18
	s_nop 1
	v_cndmask_b32_e64 v46, v47, v46, s[0:1]
	v_exp_f32_e32 v46, v46
	v_readlane_b32 s0, v255, 19
	v_readlane_b32 s1, v255, 20
	v_fmamk_f32 v47, v26, 0x42c60000, v29
	s_nop 0
	v_cndmask_b32_e64 v46, v46, 2.0, s[0:1]
	v_readlane_b32 s0, v255, 21
	v_mul_f32_e32 v52, v46, v48
	v_fmamk_f32 v46, v28, 0xc2c60000, v27
	v_readlane_b32 s1, v255, 22
	s_nop 1
	v_cndmask_b32_e64 v46, v47, v46, s[0:1]
	v_exp_f32_e32 v46, v46
	v_readlane_b32 s0, v255, 23
	v_readlane_b32 s1, v255, 24
	s_nop 1
	v_cndmask_b32_e64 v46, v46, 2.0, s[0:1]
	v_mul_f32_e32 v53, v46, v49
	ds_read_b128 v[46:49], v33 offset:16128
	s_waitcnt lgkmcnt(0)
	v_mfma_f32_16x16x32_bf16 v[0:3], v[46:49], v[0:3], 0
	ds_read_b128 v[46:49], v33 offset:16192
	s_waitcnt lgkmcnt(0)
	v_mfma_f32_16x16x32_bf16 v[0:3], v[46:49], v[20:23], v[0:3]
	v_fmamk_f32 v20, v28, 0xc2e00000, v27
	v_fmamk_f32 v21, v26, 0x42e00000, v29
	v_cndmask_b32_e64 v20, v21, v20, s[16:17]
	v_exp_f32_e32 v20, v20
	s_nop 0
	v_cndmask_b32_e64 v20, v20, 2.0, s[18:19]
	s_nop 1
	v_mul_f32_e32 v33, v20, v0
	v_fmamk_f32 v0, v28, 0xc2e20000, v27
	v_fmamk_f32 v20, v26, 0x42e20000, v29
	v_cndmask_b32_e64 v0, v20, v0, s[20:21]
	v_exp_f32_e32 v0, v0
	s_nop 0
	v_cndmask_b32_e64 v0, v0, 2.0, s[22:23]
	v_mul_f32_e32 v46, v0, v1
	v_fmamk_f32 v0, v28, 0xc2e40000, v27
	v_fmamk_f32 v1, v26, 0x42e40000, v29
	v_cndmask_b32_e64 v0, v1, v0, s[24:25]
	v_exp_f32_e32 v0, v0
	v_fmac_f32_e32 v27, 0xc2e60000, v28
	v_fmac_f32_e32 v29, 0x42e60000, v26
	v_cndmask_b32_e64 v0, v0, 2.0, s[26:27]
	v_mul_f32_e32 v47, v0, v2
	v_cndmask_b32_e64 v0, v29, v27, s[28:29]
	v_exp_f32_e32 v0, v0
	s_nop 0
	v_cndmask_b32_e64 v0, v0, 2.0, s[30:31]
	v_mul_f32_e32 v26, v0, v3
	v_add_u32_e32 v20, 0x4800, v118
	v_cvt_pk_bf16_f32 v0, v30, v31
	v_cvt_pk_bf16_f32 v1, v32, v34
	v_cvt_pk_bf16_f32 v2, v35, v36
	v_cvt_pk_bf16_f32 v3, v38, v40
	ds_read2_b64 v[20:23], v20 offset1:4
	s_waitcnt lgkmcnt(0)
	v_mfma_f32_16x16x32_bf16 v[4:7], v[20:23], v[0:3], v[4:7]
	v_add_u32_e32 v20, 0x4800, v119
	ds_read2_b64 v[20:23], v20 offset1:4
	s_waitcnt lgkmcnt(0)
	v_mfma_f32_16x16x32_bf16 v[8:11], v[20:23], v[0:3], v[8:11]
	ds_read_b64 v[20:21], v120 offset:18432
	ds_read_b64 v[22:23], v121 offset:18432
	s_waitcnt lgkmcnt(0)
	v_mfma_f32_16x16x32_bf16 v[12:15], v[20:23], v[0:3], v[12:15]
	ds_read_b64 v[20:21], v122 offset:18432
	ds_read_b64 v[22:23], v123 offset:18432
	s_waitcnt lgkmcnt(0)
	v_mfma_f32_16x16x32_bf16 v[0:3], v[20:23], v[0:3], v[16:19]
	v_add_u32_e32 v20, 0x4800, v125
	v_cvt_pk_bf16_f32 v16, v37, v39
	v_cvt_pk_bf16_f32 v17, v41, v42
	v_cvt_pk_bf16_f32 v18, v43, v44
	v_cvt_pk_bf16_f32 v19, v45, v54
	ds_read2_b64 v[20:23], v20 offset1:4
	s_waitcnt lgkmcnt(0)
	v_mfma_f32_16x16x32_bf16 v[4:7], v[20:23], v[16:19], v[4:7]
	v_add_u32_e32 v20, 0x4800, v126
	ds_read2_b64 v[20:23], v20 offset1:4
	s_waitcnt lgkmcnt(0)
	v_mfma_f32_16x16x32_bf16 v[8:11], v[20:23], v[16:19], v[8:11]
	ds_read_b64 v[20:21], v127 offset:18432
	ds_read_b64 v[22:23], v128 offset:18432
	s_waitcnt lgkmcnt(0)
	v_mfma_f32_16x16x32_bf16 v[12:15], v[20:23], v[16:19], v[12:15]
	ds_read_b64 v[20:21], v129 offset:18432
	ds_read_b64 v[22:23], v130 offset:18432
	s_waitcnt lgkmcnt(0)
	v_mfma_f32_16x16x32_bf16 v[0:3], v[20:23], v[16:19], v[0:3]
	v_add_u32_e32 v20, 0x4800, v132
	v_cvt_pk_bf16_f32 v16, v55, v56
	v_cvt_pk_bf16_f32 v17, v57, v58
	v_cvt_pk_bf16_f32 v18, v59, v60
	v_cvt_pk_bf16_f32 v19, v61, v62
	ds_read2_b64 v[20:23], v20 offset1:4
	s_waitcnt lgkmcnt(0)
	v_mfma_f32_16x16x32_bf16 v[4:7], v[20:23], v[16:19], v[4:7]
	v_add_u32_e32 v20, 0x4800, v133
	ds_read2_b64 v[20:23], v20 offset1:4
	s_waitcnt lgkmcnt(0)
	v_mfma_f32_16x16x32_bf16 v[8:11], v[20:23], v[16:19], v[8:11]
	ds_read_b64 v[20:21], v134 offset:18432
	ds_read_b64 v[22:23], v135 offset:18432
	s_waitcnt lgkmcnt(0)
	v_mfma_f32_16x16x32_bf16 v[20:23], v[20:23], v[16:19], v[12:15]
	s_nop 2
	ds_read_b64 v[12:13], v136 offset:18432
	ds_read_b64 v[14:15], v137 offset:18432
	s_waitcnt lgkmcnt(0)
	v_mfma_f32_16x16x32_bf16 v[0:3], v[12:15], v[16:19], v[0:3]
	v_add_u32_e32 v12, 0x4800, v139
	v_cvt_pk_bf16_f32 v16, v50, v51
	v_cvt_pk_bf16_f32 v17, v52, v53
	v_cvt_pk_bf16_f32 v18, v33, v46
	v_cvt_pk_bf16_f32 v19, v47, v26
	ds_read2_b64 v[12:15], v12 offset1:4
	s_waitcnt lgkmcnt(0)
	v_mfma_f32_16x16x32_bf16 v[12:15], v[12:15], v[16:19], v[4:7]
	s_nop 2
	v_add_u32_e32 v4, 0x4800, v140
	ds_read2_b64 v[4:7], v4 offset1:4
	s_waitcnt lgkmcnt(0)
	v_mfma_f32_16x16x32_bf16 v[8:11], v[4:7], v[16:19], v[8:11]
	ds_read_b64 v[4:5], v141 offset:18432
	ds_read_b64 v[6:7], v142 offset:18432
	s_waitcnt lgkmcnt(0)
	v_mfma_f32_16x16x32_bf16 v[4:7], v[4:7], v[16:19], v[20:23]
	s_nop 2
	ds_read_b64 v[20:21], v143 offset:18432
	ds_read_b64 v[22:23], v154 offset:18432
	s_waitcnt lgkmcnt(0)
; __device__ __forceinline__ float bf2f(bf16_t b) { return __uint_as_float(((unsigned)b) << 16); }
; __device__ __forceinline__ float silu_f(float x) { return x * __builtin_amdgcn_rcpf(1.0f + __expf(-x)); }
; __device__ __forceinline__ unsigned cvt_pk_bf16(float lo, float hi) { unsigned r; asm volatile("v_cvt_pk_bf16_f32 %0, %1, %2" : "=v"(r) : "v"(lo), "v"(hi)); return r; }
; __device__ __forceinline__ void m3_outputs(const KQ p_in, int e, bool ctx_full, unsigned char* smem, unsigned* scan_word) {
;     ...
;             float ss = 0.f;
; #pragma unroll
;             for (int m = 0; m < 4; ++m)
; #pragma unroll
;                 for (int rg = 0; rg < 4; ++rg) ss += O[m][rg] * O[m][rg];
;             ss += __shfl_xor(ss, 16, 64); ss += __shfl_xor(ss, 32, 64);
;             const float rn = rsqrtf(ss * (1.0f / 64.0f) + EPS);
; #pragma unroll
;             for (int m = 0; m < 4; ++m) {
;                 const int ee = 16 * m + 4 * g4;
;                 const bf16x4 gv = *(const bf16x4*)(Z + (size_t)(t0 + i) * INW + 1024 + h * 64 + ee);
;                 uint2 o2; o2.x = pg8::cvt_pk_bf16(O[m][0] * rn * silu_f(bf2f((bf16_t)gv[0])), O[m][1] * rn * silu_f(bf2f((bf16_t)gv[1])));
;                 o2.y = pg8::cvt_pk_bf16(O[m][2] * rn * silu_f(bf2f((bf16_t)gv[2])), O[m][3] * rn * silu_f(bf2f((bf16_t)gv[3])));
;                 *(uint2*)(MIX + (size_t)(t0 + i) * D + 512 + h * 64 + ee) = o2;
;             }
	v_mfma_f32_16x16x32_bf16 v[0:3], v[20:23], v[16:19], v[0:3]
	v_mul_f32_e32 v20, v13, v13
	v_fmac_f32_e32 v20, v12, v12
	v_fmac_f32_e32 v20, v14, v14
	v_fmac_f32_e32 v20, v15, v15
	v_fmac_f32_e32 v20, v8, v8
	v_fmac_f32_e32 v20, v9, v9
	v_fmac_f32_e32 v20, v10, v10
	v_fmac_f32_e32 v20, v11, v11
	v_pk_mul_f32 v[18:19], v[4:5], v[4:5]
	v_pk_mul_f32 v[16:17], v[6:7], v[6:7]
	v_add_f32_e32 v18, v18, v20
	v_add_f32_e32 v18, v19, v18
	v_add_f32_e32 v16, v16, v18
	v_add_f32_e32 v20, v17, v16
	v_pk_mul_f32 v[18:19], v[0:1], v[0:1]
	v_pk_mul_f32 v[16:17], v[2:3], v[2:3]
	v_add_f32_e32 v18, v18, v20
	v_add_f32_e32 v18, v19, v18
	v_add_f32_e32 v16, v16, v18
	v_and_b32_e32 v18, 64, v205
	v_add_f32_e32 v16, v17, v16
	v_xor_b32_e32 v17, 16, v205
	v_add_u32_e32 v18, 64, v18
	v_cmp_lt_i32_e32 vcc, v17, v18
	v_lshlrev_b32_e32 v20, 1, v86
	v_mov_b32_e32 v21, v145
	v_cndmask_b32_e32 v17, v205, v17, vcc
	v_lshlrev_b32_e32 v17, 2, v17
	ds_bpermute_b32 v17, v17, v16
	s_waitcnt lgkmcnt(0)
	v_add_f32_e32 v16, v16, v17
	v_xor_b32_e32 v17, 32, v205
	v_cmp_lt_i32_e32 vcc, v17, v18
	s_nop 1
	v_cndmask_b32_e32 v17, v205, v17, vcc
	v_lshlrev_b32_e32 v17, 2, v17
	ds_bpermute_b32 v17, v17, v16
	s_waitcnt lgkmcnt(0)
	v_add_f32_e32 v16, v16, v17
	v_fmamk_f32 v16, v16, 0x3c800000, v146
	v_cmp_gt_f32_e32 vcc, s67, v16
	v_mul_f32_e32 v17, 0x4b800000, v16
	s_nop 0
	v_cndmask_b32_e32 v16, v16, v17, vcc
	v_rsq_f32_e32 v16, v16
	s_nop 0
	v_mul_f32_e32 v17, 0x45800000, v16
	v_cndmask_b32_e32 v26, v16, v17, vcc
	v_lshlrev_b64 v[16:17], 11, v[106:107]
	v_lshl_add_u64 v[16:17], s[90:91], 0, v[16:17]
	v_lshl_add_u64 v[18:19], v[16:17], 0, s[80:81]
	v_lshl_add_u64 v[16:17], v[24:25], 0, v[20:21]
	global_load_dwordx2 v[22:23], v[16:17], off offset:2048
	global_load_dwordx2 v[28:29], v[16:17], off offset:2080
	global_load_dwordx2 v[30:31], v[16:17], off offset:2112
	global_load_dwordx2 v[32:33], v[16:17], off offset:2144
	v_mul_f32_e32 v12, v12, v26
	v_mul_f32_e32 v13, v13, v26
	v_mul_f32_e32 v8, v8, v26
	v_mul_f32_e32 v9, v9, v26
	v_mul_f32_e32 v4, v4, v26
	v_mul_f32_e32 v5, v5, v26
	v_mul_f32_e32 v0, v0, v26
	v_mul_f32_e32 v1, v1, v26
	s_waitcnt lgkmcnt(0)
	s_waitcnt vmcnt(0)
	v_lshlrev_b32_e32 v24, 16, v22
	v_mul_f32_e32 v25, 0xbfb8aa3b, v24
	v_exp_f32_e32 v25, v25
	v_and_b32_e32 v22, 0xffff0000, v22
	v_add_f32_e32 v25, 1.0, v25
	v_rcp_f32_e32 v25, v25
	s_nop 0
	v_mul_f32_e32 v24, v25, v24
	v_mul_f32_e32 v12, v24, v12
	v_mul_f32_e32 v24, 0xbfb8aa3b, v22
	v_exp_f32_e32 v24, v24
	s_nop 0
	v_add_f32_e32 v24, 1.0, v24
	v_rcp_f32_e32 v24, v24
	s_nop 0
	v_mul_f32_e32 v22, v24, v22
	v_mul_f32_e32 v13, v22, v13
	v_cvt_pk_bf16_f32 v22, v12, v13
	v_lshlrev_b32_e32 v13, 16, v23
	v_mul_f32_e32 v12, v14, v26
	v_mul_f32_e32 v14, 0xbfb8aa3b, v13
	v_exp_f32_e32 v14, v14
	s_nop 0
	v_add_f32_e32 v14, 1.0, v14
	v_rcp_f32_e32 v14, v14
	s_nop 0
	v_mul_f32_e32 v13, v14, v13
	v_and_b32_e32 v14, 0xffff0000, v23
	v_mul_f32_e32 v12, v13, v12
	v_mul_f32_e32 v13, v15, v26
	v_mul_f32_e32 v15, 0xbfb8aa3b, v14
	v_exp_f32_e32 v15, v15
	s_nop 0
	v_add_f32_e32 v15, 1.0, v15
	v_rcp_f32_e32 v15, v15
	s_nop 0
	v_mul_f32_e32 v14, v15, v14
	v_mul_f32_e32 v13, v14, v13
	v_cvt_pk_bf16_f32 v23, v12, v13
	v_mov_b32_e32 v14, v28
	v_mov_b32_e32 v15, v29
	v_lshl_add_u64 v[12:13], v[18:19], 0, v[20:21]
	global_store_dwordx2 v[12:13], v[22:23], off offset:1024
	s_waitcnt lgkmcnt(0)
	s_waitcnt vmcnt(1)
	v_lshlrev_b32_e32 v18, 16, v14
	v_mul_f32_e32 v19, 0xbfb8aa3b, v18
	v_exp_f32_e32 v19, v19
	v_and_b32_e32 v14, 0xffff0000, v14
	v_add_f32_e32 v19, 1.0, v19
	v_rcp_f32_e32 v19, v19
	s_nop 0
	v_mul_f32_e32 v18, v19, v18
	v_mul_f32_e32 v8, v8, v18
	v_mul_f32_e32 v18, 0xbfb8aa3b, v14
	v_exp_f32_e32 v18, v18
	s_nop 0
	v_add_f32_e32 v18, 1.0, v18
	v_rcp_f32_e32 v18, v18
	s_nop 0
	v_mul_f32_e32 v14, v18, v14
	v_mul_f32_e32 v9, v9, v14
	v_cvt_pk_bf16_f32 v8, v8, v9
	v_mul_f32_e32 v9, v10, v26
	v_lshlrev_b32_e32 v10, 16, v15
	v_mul_f32_e32 v14, 0xbfb8aa3b, v10
	v_exp_f32_e32 v14, v14
	s_nop 0
	v_add_f32_e32 v14, 1.0, v14
	v_rcp_f32_e32 v14, v14
	s_nop 0
	v_mul_f32_e32 v10, v14, v10
	v_mul_f32_e32 v9, v9, v10
	v_mul_f32_e32 v10, v11, v26
	v_and_b32_e32 v11, 0xffff0000, v15
	v_mul_f32_e32 v14, 0xbfb8aa3b, v11
	v_exp_f32_e32 v14, v14
	s_nop 0
	v_add_f32_e32 v14, 1.0, v14
	v_rcp_f32_e32 v14, v14
	s_nop 0
	v_mul_f32_e32 v11, v14, v11
	v_mul_f32_e32 v10, v10, v11
	v_cvt_pk_bf16_f32 v9, v9, v10
	global_store_dwordx2 v[12:13], v[8:9], off offset:1056
	v_mov_b32_e32 v8, v30
	v_mov_b32_e32 v9, v31
	s_waitcnt lgkmcnt(0)
	s_waitcnt vmcnt(0)
	v_lshlrev_b32_e32 v10, 16, v8
	v_mul_f32_e32 v11, 0xbfb8aa3b, v10
	v_exp_f32_e32 v11, v11
	v_and_b32_e32 v8, 0xffff0000, v8
	v_add_f32_e32 v11, 1.0, v11
	v_rcp_f32_e32 v11, v11
	s_nop 0
	v_mul_f32_e32 v10, v11, v10
	v_mul_f32_e32 v4, v4, v10
	v_mul_f32_e32 v10, 0xbfb8aa3b, v8
	v_exp_f32_e32 v10, v10
	s_nop 0
	v_add_f32_e32 v10, 1.0, v10
	v_rcp_f32_e32 v10, v10
	s_nop 0
	v_mul_f32_e32 v8, v10, v8
	v_mul_f32_e32 v5, v5, v8
	v_cvt_pk_bf16_f32 v4, v4, v5
	v_mul_f32_e32 v5, v6, v26
	v_lshlrev_b32_e32 v6, 16, v9
	v_mul_f32_e32 v8, 0xbfb8aa3b, v6
	v_exp_f32_e32 v8, v8
	s_nop 0
	v_add_f32_e32 v8, 1.0, v8
	v_rcp_f32_e32 v8, v8
	s_nop 0
	v_mul_f32_e32 v6, v8, v6
	v_mul_f32_e32 v5, v5, v6
	v_mul_f32_e32 v6, v7, v26
	v_and_b32_e32 v7, 0xffff0000, v9
	v_mul_f32_e32 v8, 0xbfb8aa3b, v7
	v_exp_f32_e32 v8, v8
	s_nop 0
	v_add_f32_e32 v8, 1.0, v8
	v_rcp_f32_e32 v8, v8
	s_nop 0
	v_mul_f32_e32 v7, v8, v7
	v_mul_f32_e32 v6, v6, v7
	v_cvt_pk_bf16_f32 v5, v5, v6
	global_store_dwordx2 v[12:13], v[4:5], off offset:1088
	v_mov_b32_e32 v4, v32
	v_mov_b32_e32 v5, v33
	s_waitcnt lgkmcnt(0)
	s_waitcnt vmcnt(0)
	v_lshlrev_b32_e32 v6, 16, v4
	v_mul_f32_e32 v7, 0xbfb8aa3b, v6
	v_exp_f32_e32 v7, v7
	v_and_b32_e32 v4, 0xffff0000, v4
	v_add_f32_e32 v7, 1.0, v7
	v_rcp_f32_e32 v7, v7
	s_nop 0
	v_mul_f32_e32 v6, v7, v6
	v_mul_f32_e32 v0, v0, v6
	v_mul_f32_e32 v6, 0xbfb8aa3b, v4
	v_exp_f32_e32 v6, v6
	s_nop 0
	v_add_f32_e32 v6, 1.0, v6
	v_rcp_f32_e32 v6, v6
	s_nop 0
	v_mul_f32_e32 v4, v6, v4
	v_mul_f32_e32 v1, v1, v4
	v_cvt_pk_bf16_f32 v0, v0, v1
	v_mul_f32_e32 v1, v2, v26
	v_lshlrev_b32_e32 v2, 16, v5
	v_mul_f32_e32 v4, 0xbfb8aa3b, v2
	v_exp_f32_e32 v4, v4
	s_nop 0
	v_add_f32_e32 v4, 1.0, v4
	v_rcp_f32_e32 v4, v4
	s_nop 0
	v_mul_f32_e32 v2, v4, v2
	v_mul_f32_e32 v1, v1, v2
	v_mul_f32_e32 v2, v3, v26
	v_and_b32_e32 v3, 0xffff0000, v5
	v_mul_f32_e32 v4, 0xbfb8aa3b, v3
	v_exp_f32_e32 v4, v4
	s_nop 0
	v_add_f32_e32 v4, 1.0, v4
	v_rcp_f32_e32 v4, v4
	s_nop 0
	v_mul_f32_e32 v3, v4, v3
	v_mul_f32_e32 v2, v2, v3
	v_cvt_pk_bf16_f32 v1, v1, v2
	global_store_dwordx2 v[12:13], v[0:1], off offset:1120
	s_cbranch_execnz .LBB0_933
	s_branch .LBB0_963

; #define PG8_STAGE(bufoff, gbase, voff) do { _Pragma("unroll") for (int _i = 0; _i < 2; ++_i) \
;         __builtin_amdgcn_global_load_lds((const unsigned*)((const char*)(gbase) + (voff)[_i]), (LAS unsigned*)(lds + (bufoff) + ldsw + _i * 8192), 16, 0, 0); } while (0)
; #define PG8_LDA(dst, b, h) do { _Pragma("unroll") for (int m = 0; m < 4; ++m) _Pragma("unroll") for (int k = 0; k < 2; ++k) dst[m][k] = *(const LAS bf16x8*)(lds + PG8_SA(b, h) + aoff + m * 2048 + k * 1024); } while (0)
; #define PG8_LDB(dst, b, h) do { _Pragma("unroll") for (int n = 0; n < 2; ++n) _Pragma("unroll") for (int k = 0; k < 2; ++k) dst[n][k] = *(const LAS bf16x8*)(lds + PG8_SB(b, h) + boff + n * 2048 + k * 1024); } while (0)
; #define PG8_MMA(ai, bj, At, Bt) do { __builtin_amdgcn_s_setprio(1); _Pragma("unroll") for (int m = 0; m < 4; ++m) _Pragma("unroll") for (int n = 0; n < 2; ++n) _Pragma("unroll") for (int k = 0; k < 2; ++k) \
;         acc[ai][bj][m][n] = __builtin_amdgcn_mfma_f32_16x16x32_bf16(Bt[n][k], At[m][k], acc[ai][bj][m][n], 0, 0, 0); __builtin_amdgcn_s_setprio(0); } while (0)
; #define PG8_WAIT_L(n) asm volatile("s_waitcnt lgkmcnt(" #n ")" ::: "memory")
; #define PG8_BAR __builtin_amdgcn_s_barrier()
; #define PG8_SCHED __builtin_amdgcn_sched_barrier(0)
; template <class Epi, class Sched>
; __device__ __forceinline__ void gemm_phase(LAS unsigned char* lds, const Gemm g, const Sched& S, const Epi& E) {
;     ...
;             const char* a1 = cA + (size_t)(t + 1) * kstep;
;             const char* a2 = last ? nA : cA + (size_t)(t + 2) * kstep; const char* b2 = last ? nB : cB + (size_t)(t + 2) * kstep;
;             const char* a3 = a2 + kstep; const char* b3 = b2 + kstep;
;             PG8_LDB(B0, 0, 0); PG8_SCHED; PG8_LDA(At, 0, 0); PG8_STAGE(PG8_SA(1, 1), a1 + hstep, voffA);
;             PG8_WAIT_L(8); PG8_BAR; PG8_WAIT_L(0); PG8_MMA(0, 0, At, B0); PG8_BAR; PG8_SCHED;
;             PG8_LDB(B1, 0, 1); PG8_STAGE(PG8_SB(0, 0), b2, voffB);
;             PG8_BAR; PG8_WAIT_L(0); PG8_MMA(0, 1, At, B1); PG8_BAR;
;             PG8_LDA(At, 0, 1); PG8_STAGE(PG8_SA(0, 0), a2, voffA);
;             PG8_BAR; PG8_WAIT_L(0); PG8_MMA(1, 0, At, B0); PG8_BAR; PG8_SCHED;
.LBB0_1076:
	s_add_i32 s62, s50, 2
	s_add_u32 s52, s0, vcc_lo
	s_addc_u32 s51, s1, vcc_hi
	s_add_u32 s20, s48, vcc_lo
	s_addc_u32 s21, s49, vcc_hi
	s_add_i32 s18, 0, 0x10000
	v_add_u32_e32 v141, s18, v139
	ds_read_b128 v[158:161], v141
	ds_read_b128 v[162:165], v141 offset:1024
	ds_read_b128 v[166:169], v141 offset:2048
	ds_read_b128 v[170:173], v141 offset:3072
	s_cmp_eq_u32 s77, s50
	s_cselect_b32 s50, s6, s52
	s_cselect_b32 s51, s7, s51
	s_cselect_b32 s53, s97, s21
	s_cselect_b32 s52, s96, s20
	v_lshl_add_u64 v[142:143], s[0:1], 0, v[134:135]
	s_add_i32 m0, s70, 0xc000
	ds_read_b128 v[178:181], v140
	ds_read_b128 v[182:185], v140 offset:1024
	ds_read_b128 v[208:211], v140 offset:2048
	ds_read_b128 v[212:215], v140 offset:3072
	ds_read_b128 v[216:219], v140 offset:4096
	ds_read_b128 v[220:223], v140 offset:5120
	ds_read_b128 v[224:227], v140 offset:6144
	ds_read_b128 v[228:231], v140 offset:7168
	global_load_lds_dwordx4 v[142:143], off
	v_lshl_add_u64 v[142:143], s[0:1], 0, v[136:137]
	s_add_i32 m0, s70, 0xe000
	s_nop 0
	global_load_lds_dwordx4 v[142:143], off
	s_waitcnt lgkmcnt(8)
	s_barrier
	s_waitcnt lgkmcnt(0)
	s_setprio 1
	v_mfma_f32_16x16x32_bf16 v[88:91], v[158:161], v[178:181], v[88:91]
	v_mfma_f32_16x16x32_bf16 v[104:107], v[166:169], v[178:181], v[104:107]
	v_mfma_f32_16x16x32_bf16 v[76:79], v[158:161], v[208:211], v[76:79]
	v_mfma_f32_16x16x32_bf16 v[92:95], v[166:169], v[208:211], v[92:95]
	v_mfma_f32_16x16x32_bf16 v[108:111], v[158:161], v[216:219], v[108:111]
	v_mfma_f32_16x16x32_bf16 v[124:127], v[166:169], v[216:219], v[124:127]
	v_mfma_f32_16x16x32_bf16 v[112:115], v[158:161], v[224:227], v[112:115]
	v_mfma_f32_16x16x32_bf16 v[96:99], v[166:169], v[224:227], v[96:99]
	v_mfma_f32_16x16x32_bf16 v[88:91], v[162:165], v[182:185], v[88:91]
	v_mfma_f32_16x16x32_bf16 v[104:107], v[170:173], v[182:185], v[104:107]
	v_mfma_f32_16x16x32_bf16 v[76:79], v[162:165], v[212:215], v[76:79]
	v_mfma_f32_16x16x32_bf16 v[92:95], v[170:173], v[212:215], v[92:95]
	v_mfma_f32_16x16x32_bf16 v[108:111], v[162:165], v[220:223], v[108:111]
	v_mfma_f32_16x16x32_bf16 v[124:127], v[170:173], v[220:223], v[124:127]
	v_mfma_f32_16x16x32_bf16 v[112:115], v[162:165], v[228:231], v[112:115]
	v_mfma_f32_16x16x32_bf16 v[96:99], v[170:173], v[228:231], v[96:99]
	s_setprio 0
	s_barrier
	s_add_i32 s19, 0, 0x14000
	s_add_i32 s18, s18, s87
	v_add_u32_e32 v141, s19, v139
	v_lshl_add_u64 v[142:143], s[52:53], 0, v[144:145]
	s_mov_b32 m0, s18
	ds_read_b128 v[232:235], v141
	ds_read_b128 v[236:239], v141 offset:1024
	ds_read_b128 v[240:243], v141 offset:2048
	ds_read_b128 v[244:247], v141 offset:3072
	global_load_lds_dwordx4 v[142:143], off
	v_lshl_add_u64 v[154:155], s[52:53], 0, v[128:129]
	s_add_i32 m0, s18, 0x2000
	s_nop 0
	global_load_lds_dwordx4 v[154:155], off
	s_barrier
	s_waitcnt lgkmcnt(0)
	s_setprio 1
	v_mfma_f32_16x16x32_bf16 v[100:103], v[232:235], v[178:181], v[100:103]
	v_mfma_f32_16x16x32_bf16 v[84:87], v[240:243], v[178:181], v[84:87]
	v_mfma_f32_16x16x32_bf16 v[80:83], v[232:235], v[208:211], v[80:83]
	v_mfma_f32_16x16x32_bf16 v[72:75], v[240:243], v[208:211], v[72:75]
	v_mfma_f32_16x16x32_bf16 v[120:123], v[232:235], v[216:219], v[120:123]
	v_mfma_f32_16x16x32_bf16 v[116:119], v[240:243], v[216:219], v[116:119]
	v_mfma_f32_16x16x32_bf16 v[68:71], v[232:235], v[224:227], v[68:71]
	v_mfma_f32_16x16x32_bf16 v[64:67], v[240:243], v[224:227], v[64:67]
	v_mfma_f32_16x16x32_bf16 v[100:103], v[236:239], v[182:185], v[100:103]
	v_mfma_f32_16x16x32_bf16 v[84:87], v[244:247], v[182:185], v[84:87]
	v_mfma_f32_16x16x32_bf16 v[80:83], v[236:239], v[212:215], v[80:83]
	v_mfma_f32_16x16x32_bf16 v[72:75], v[244:247], v[212:215], v[72:75]
	v_mfma_f32_16x16x32_bf16 v[120:123], v[236:239], v[220:223], v[120:123]
	v_mfma_f32_16x16x32_bf16 v[116:119], v[244:247], v[220:223], v[116:119]
	v_mfma_f32_16x16x32_bf16 v[68:71], v[236:239], v[228:231], v[68:71]
	v_mfma_f32_16x16x32_bf16 v[64:67], v[244:247], v[228:231], v[64:67]
	s_setprio 0
	s_mov_b32 m0, s70
	v_lshl_add_u64 v[174:175], s[50:51], 0, v[144:145]
	s_barrier
	ds_read_b128 v[178:181], v140 offset:16384
	ds_read_b128 v[182:185], v140 offset:17408
	ds_read_b128 v[208:211], v140 offset:18432
	ds_read_b128 v[212:215], v140 offset:19456
	ds_read_b128 v[216:219], v140 offset:20480
	ds_read_b128 v[220:223], v140 offset:21504
	ds_read_b128 v[224:227], v140 offset:22528
	ds_read_b128 v[228:231], v140 offset:23552
	global_load_lds_dwordx4 v[174:175], off
	v_lshl_add_u64 v[186:187], s[50:51], 0, v[128:129]
	s_mov_b32 m0, s71
	s_nop 0
	global_load_lds_dwordx4 v[186:187], off
	s_barrier
	s_waitcnt lgkmcnt(0)
	s_setprio 1
	v_mfma_f32_16x16x32_bf16 v[60:63], v[158:161], v[178:181], v[60:63]
	v_mfma_f32_16x16x32_bf16 v[56:59], v[166:169], v[178:181], v[56:59]
	v_mfma_f32_16x16x32_bf16 v[44:47], v[158:161], v[208:211], v[44:47]
	v_mfma_f32_16x16x32_bf16 v[40:43], v[166:169], v[208:211], v[40:43]
	v_mfma_f32_16x16x32_bf16 v[28:31], v[158:161], v[216:219], v[28:31]
	v_mfma_f32_16x16x32_bf16 v[24:27], v[166:169], v[216:219], v[24:27]
	v_mfma_f32_16x16x32_bf16 v[12:15], v[158:161], v[224:227], v[12:15]
	v_mfma_f32_16x16x32_bf16 v[8:11], v[166:169], v[224:227], v[8:11]
	v_mfma_f32_16x16x32_bf16 v[60:63], v[162:165], v[182:185], v[60:63]
	v_mfma_f32_16x16x32_bf16 v[56:59], v[170:173], v[182:185], v[56:59]
	v_mfma_f32_16x16x32_bf16 v[44:47], v[162:165], v[212:215], v[44:47]
	v_mfma_f32_16x16x32_bf16 v[40:43], v[170:173], v[212:215], v[40:43]
	v_mfma_f32_16x16x32_bf16 v[28:31], v[162:165], v[220:223], v[28:31]
	v_mfma_f32_16x16x32_bf16 v[24:27], v[170:173], v[220:223], v[24:27]
	v_mfma_f32_16x16x32_bf16 v[12:15], v[162:165], v[228:231], v[12:15]
	v_mfma_f32_16x16x32_bf16 v[8:11], v[170:173], v[228:231], v[8:11]
	s_setprio 0
	s_barrier
; #define PG8_STAGE(bufoff, gbase, voff) do { _Pragma("unroll") for (int _i = 0; _i < 2; ++_i) \
;         __builtin_amdgcn_global_load_lds((const unsigned*)((const char*)(gbase) + (voff)[_i]), (LAS unsigned*)(lds + (bufoff) + ldsw + _i * 8192), 16, 0, 0); } while (0)
; #define PG8_LDA(dst, b, h) do { _Pragma("unroll") for (int m = 0; m < 4; ++m) _Pragma("unroll") for (int k = 0; k < 2; ++k) dst[m][k] = *(const LAS bf16x8*)(lds + PG8_SA(b, h) + aoff + m * 2048 + k * 1024); } while (0)
; #define PG8_LDB(dst, b, h) do { _Pragma("unroll") for (int n = 0; n < 2; ++n) _Pragma("unroll") for (int k = 0; k < 2; ++k) dst[n][k] = *(const LAS bf16x8*)(lds + PG8_SB(b, h) + boff + n * 2048 + k * 1024); } while (0)
; #define PG8_MMA(ai, bj, At, Bt) do { __builtin_amdgcn_s_setprio(1); _Pragma("unroll") for (int m = 0; m < 4; ++m) _Pragma("unroll") for (int n = 0; n < 2; ++n) _Pragma("unroll") for (int k = 0; k < 2; ++k) \
;         acc[ai][bj][m][n] = __builtin_amdgcn_mfma_f32_16x16x32_bf16(Bt[n][k], At[m][k], acc[ai][bj][m][n], 0, 0, 0); __builtin_amdgcn_s_setprio(0); } while (0)
; #define PG8_WAIT_V(n) asm volatile("s_waitcnt vmcnt(" #n ")" ::: "memory")
; #define PG8_WAIT_L(n) asm volatile("s_waitcnt lgkmcnt(" #n ")" ::: "memory")
; #define PG8_BAR __builtin_amdgcn_s_barrier()
; #define PG8_SCHED __builtin_amdgcn_sched_barrier(0)
; template <class Epi, class Sched>
; __device__ __forceinline__ void gemm_phase(LAS unsigned char* lds, const Gemm g, const Sched& S, const Epi& E) {
;     ...
;             PG8_STAGE(PG8_SB(0, 1), b2 + hstep, voffB);
;             PG8_WAIT_V(6); PG8_BAR; PG8_MMA(1, 1, At, B1); PG8_BAR;
;             PG8_LDB(B0, 1, 0); PG8_SCHED; PG8_LDA(At, 1, 0); PG8_STAGE(PG8_SA(0, 1), a2 + hstep, voffA);
;             PG8_WAIT_L(8); PG8_BAR; PG8_WAIT_L(0); PG8_MMA(0, 0, At, B0); PG8_BAR; PG8_SCHED;
;             PG8_LDB(B1, 1, 1); PG8_STAGE(PG8_SB(1, 0), b3, voffB);
;             PG8_BAR; PG8_WAIT_L(0); PG8_MMA(0, 1, At, B1); PG8_BAR;
;             PG8_LDA(At, 1, 1); PG8_STAGE(PG8_SA(1, 0), a3, voffA);
;             PG8_BAR; PG8_WAIT_L(0); PG8_MMA(1, 0, At, B0); PG8_BAR; PG8_SCHED;
	s_add_u32 s52, s52, s13
	s_addc_u32 s53, s53, 0
	s_add_i32 s18, s19, s87
	v_lshl_add_u64 v[248:249], s[52:53], 0, v[144:145]
	s_mov_b32 m0, s18
	v_lshl_add_u64 v[192:193], s[52:53], 0, v[128:129]
	global_load_lds_dwordx4 v[248:249], off
	s_add_i32 m0, s18, 0x2000
	s_nop 0
	global_load_lds_dwordx4 v[192:193], off
	s_waitcnt vmcnt(6)
	s_barrier
	s_setprio 1
	v_mfma_f32_16x16x32_bf16 v[52:55], v[232:235], v[178:181], v[52:55]
	v_mfma_f32_16x16x32_bf16 v[48:51], v[240:243], v[178:181], v[48:51]
	v_mfma_f32_16x16x32_bf16 v[36:39], v[232:235], v[208:211], v[36:39]
	v_mfma_f32_16x16x32_bf16 v[32:35], v[240:243], v[208:211], v[32:35]
	v_mfma_f32_16x16x32_bf16 v[20:23], v[232:235], v[216:219], v[20:23]
	v_mfma_f32_16x16x32_bf16 v[16:19], v[240:243], v[216:219], v[16:19]
	v_mfma_f32_16x16x32_bf16 v[4:7], v[232:235], v[224:227], v[4:7]
	v_mfma_f32_16x16x32_bf16 v[0:3], v[240:243], v[224:227], v[0:3]
	v_mfma_f32_16x16x32_bf16 v[52:55], v[236:239], v[182:185], v[52:55]
	v_mfma_f32_16x16x32_bf16 v[48:51], v[244:247], v[182:185], v[48:51]
	v_mfma_f32_16x16x32_bf16 v[36:39], v[236:239], v[212:215], v[36:39]
	v_mfma_f32_16x16x32_bf16 v[32:35], v[244:247], v[212:215], v[32:35]
	v_mfma_f32_16x16x32_bf16 v[20:23], v[236:239], v[220:223], v[20:23]
	v_mfma_f32_16x16x32_bf16 v[16:19], v[244:247], v[220:223], v[16:19]
	v_mfma_f32_16x16x32_bf16 v[4:7], v[236:239], v[228:231], v[4:7]
	v_mfma_f32_16x16x32_bf16 v[0:3], v[244:247], v[228:231], v[0:3]
	s_setprio 0
	s_add_i32 s18, 0, 0x18000
	v_add_u32_e32 v141, s18, v139
	s_barrier
	ds_read_b128 v[158:161], v141
	ds_read_b128 v[162:165], v141 offset:1024
	ds_read_b128 v[166:169], v141 offset:2048
	ds_read_b128 v[170:173], v141 offset:3072
	s_add_u32 s50, s50, s13
	s_addc_u32 s51, s51, 0
	s_mov_b32 m0, s72
	v_lshl_add_u64 v[232:233], s[50:51], 0, v[144:145]
	ds_read_b128 v[178:181], v140 offset:32768
	ds_read_b128 v[182:185], v140 offset:33792
	ds_read_b128 v[208:211], v140 offset:34816
	ds_read_b128 v[212:215], v140 offset:35840
	ds_read_b128 v[216:219], v140 offset:36864
	ds_read_b128 v[220:223], v140 offset:37888
	ds_read_b128 v[224:227], v140 offset:38912
	ds_read_b128 v[228:231], v140 offset:39936
	global_load_lds_dwordx4 v[232:233], off
	v_lshl_add_u64 v[232:233], s[50:51], 0, v[128:129]
	s_mov_b32 m0, s73
	s_nop 0
	global_load_lds_dwordx4 v[232:233], off
	s_waitcnt lgkmcnt(8)
	s_barrier
	s_waitcnt lgkmcnt(0)
	s_setprio 1
	v_mfma_f32_16x16x32_bf16 v[88:91], v[158:161], v[178:181], v[88:91]
	v_mfma_f32_16x16x32_bf16 v[104:107], v[166:169], v[178:181], v[104:107]
	v_mfma_f32_16x16x32_bf16 v[76:79], v[158:161], v[208:211], v[76:79]
	v_mfma_f32_16x16x32_bf16 v[92:95], v[166:169], v[208:211], v[92:95]
	v_mfma_f32_16x16x32_bf16 v[108:111], v[158:161], v[216:219], v[108:111]
	v_mfma_f32_16x16x32_bf16 v[124:127], v[166:169], v[216:219], v[124:127]
	v_mfma_f32_16x16x32_bf16 v[112:115], v[158:161], v[224:227], v[112:115]
	v_mfma_f32_16x16x32_bf16 v[96:99], v[166:169], v[224:227], v[96:99]
	v_mfma_f32_16x16x32_bf16 v[88:91], v[162:165], v[182:185], v[88:91]
	v_mfma_f32_16x16x32_bf16 v[104:107], v[170:173], v[182:185], v[104:107]
	v_mfma_f32_16x16x32_bf16 v[76:79], v[162:165], v[212:215], v[76:79]
	v_mfma_f32_16x16x32_bf16 v[92:95], v[170:173], v[212:215], v[92:95]
	v_mfma_f32_16x16x32_bf16 v[108:111], v[162:165], v[220:223], v[108:111]
	v_mfma_f32_16x16x32_bf16 v[124:127], v[170:173], v[220:223], v[124:127]
	v_mfma_f32_16x16x32_bf16 v[112:115], v[162:165], v[228:231], v[112:115]
	v_mfma_f32_16x16x32_bf16 v[96:99], v[170:173], v[228:231], v[96:99]
	s_setprio 0
	s_barrier
	s_add_i32 s19, 0, 0x1c000
	s_add_i32 s18, s18, s87
	v_add_u32_e32 v141, s19, v139
	v_lshl_add_u64 v[142:143], v[142:143], 0, s[82:83]
	s_mov_b32 m0, s18
	ds_read_b128 v[232:235], v141
	ds_read_b128 v[236:239], v141 offset:1024
	ds_read_b128 v[240:243], v141 offset:2048
	ds_read_b128 v[244:247], v141 offset:3072
	global_load_lds_dwordx4 v[142:143], off
	v_lshl_add_u64 v[142:143], v[154:155], 0, s[82:83]
	s_add_i32 m0, s18, 0x2000
	s_nop 0
	global_load_lds_dwordx4 v[142:143], off
	s_barrier
	s_waitcnt lgkmcnt(0)
	s_setprio 1
	v_mfma_f32_16x16x32_bf16 v[100:103], v[232:235], v[178:181], v[100:103]
	v_mfma_f32_16x16x32_bf16 v[84:87], v[240:243], v[178:181], v[84:87]
	v_mfma_f32_16x16x32_bf16 v[80:83], v[232:235], v[208:211], v[80:83]
	v_mfma_f32_16x16x32_bf16 v[72:75], v[240:243], v[208:211], v[72:75]
	v_mfma_f32_16x16x32_bf16 v[120:123], v[232:235], v[216:219], v[120:123]
	v_mfma_f32_16x16x32_bf16 v[116:119], v[240:243], v[216:219], v[116:119]
	v_mfma_f32_16x16x32_bf16 v[68:71], v[232:235], v[224:227], v[68:71]
	v_mfma_f32_16x16x32_bf16 v[64:67], v[240:243], v[224:227], v[64:67]
	v_mfma_f32_16x16x32_bf16 v[100:103], v[236:239], v[182:185], v[100:103]
	v_mfma_f32_16x16x32_bf16 v[84:87], v[244:247], v[182:185], v[84:87]
	v_mfma_f32_16x16x32_bf16 v[80:83], v[236:239], v[212:215], v[80:83]
	v_mfma_f32_16x16x32_bf16 v[72:75], v[244:247], v[212:215], v[72:75]
	v_mfma_f32_16x16x32_bf16 v[120:123], v[236:239], v[220:223], v[120:123]
	v_mfma_f32_16x16x32_bf16 v[116:119], v[244:247], v[220:223], v[116:119]
	v_mfma_f32_16x16x32_bf16 v[68:71], v[236:239], v[228:231], v[68:71]
	v_mfma_f32_16x16x32_bf16 v[64:67], v[244:247], v[228:231], v[64:67]
	s_setprio 0
	s_mov_b32 m0, s74
	v_lshl_add_u64 v[142:143], v[174:175], 0, s[82:83]
	s_barrier
	ds_read_b128 v[178:181], v140 offset:49152
	ds_read_b128 v[182:185], v140 offset:50176
	ds_read_b128 v[208:211], v140 offset:51200
	ds_read_b128 v[212:215], v140 offset:52224
	ds_read_b128 v[216:219], v140 offset:53248
	ds_read_b128 v[220:223], v140 offset:54272
	ds_read_b128 v[224:227], v140 offset:55296
	ds_read_b128 v[228:231], v140 offset:56320
	global_load_lds_dwordx4 v[142:143], off
	v_lshl_add_u64 v[142:143], v[186:187], 0, s[82:83]
	s_mov_b32 m0, s75
	s_nop 0
	global_load_lds_dwordx4 v[142:143], off
	s_barrier
; #define PG8_STAGE(bufoff, gbase, voff) do { _Pragma("unroll") for (int _i = 0; _i < 2; ++_i) \
;         __builtin_amdgcn_global_load_lds((const unsigned*)((const char*)(gbase) + (voff)[_i]), (LAS unsigned*)(lds + (bufoff) + ldsw + _i * 8192), 16, 0, 0); } while (0)
; #define PG8_MMA(ai, bj, At, Bt) do { __builtin_amdgcn_s_setprio(1); _Pragma("unroll") for (int m = 0; m < 4; ++m) _Pragma("unroll") for (int n = 0; n < 2; ++n) _Pragma("unroll") for (int k = 0; k < 2; ++k) \
;         acc[ai][bj][m][n] = __builtin_amdgcn_mfma_f32_16x16x32_bf16(Bt[n][k], At[m][k], acc[ai][bj][m][n], 0, 0, 0); __builtin_amdgcn_s_setprio(0); } while (0)
; #define PG8_WAIT_V(n) asm volatile("s_waitcnt vmcnt(" #n ")" ::: "memory")
; #define PG8_WAIT_L(n) asm volatile("s_waitcnt lgkmcnt(" #n ")" ::: "memory")
; #define PG8_BAR __builtin_amdgcn_s_barrier()
; #define PG8_SCHED __builtin_amdgcn_sched_barrier(0)
; template <class Epi, class Sched>
; __device__ __forceinline__ void gemm_phase(LAS unsigned char* lds, const Gemm g, const Sched& S, const Epi& E) {
;     ...
;             PG8_BAR; PG8_WAIT_L(0); PG8_MMA(1, 0, At, B0); PG8_BAR; PG8_SCHED;
;             PG8_STAGE(PG8_SB(1, 1), b3 + hstep, voffB);
;             PG8_WAIT_V(6); PG8_BAR; PG8_MMA(1, 1, At, B1); PG8_BAR;
;         }
;         if constexpr (!Epi::AFTER_DRAIN) E(acc, cur, wr, wc, fr, fq);
;         if (!has_next) break;
; #pragma unroll
;         for (int a = 0; a < 2; ++a)
; #pragma unroll
;             for (int b = 0; b < 2; ++b)
; #pragma unroll
;                 for (int m = 0; m < 4; ++m)
; #pragma unroll
;                     for (int n = 0; n < 2; ++n) acc[a][b][m][n] = (f32x4){0.f, 0.f, 0.f, 0.f};
;         cur = nxt; cA = nA; cB = nB; ++ui;
	s_waitcnt lgkmcnt(0)
	s_setprio 1
	v_mfma_f32_16x16x32_bf16 v[60:63], v[158:161], v[178:181], v[60:63]
	v_mfma_f32_16x16x32_bf16 v[56:59], v[166:169], v[178:181], v[56:59]
	v_mfma_f32_16x16x32_bf16 v[44:47], v[158:161], v[208:211], v[44:47]
	v_mfma_f32_16x16x32_bf16 v[40:43], v[166:169], v[208:211], v[40:43]
	v_mfma_f32_16x16x32_bf16 v[28:31], v[158:161], v[216:219], v[28:31]
	v_mfma_f32_16x16x32_bf16 v[24:27], v[166:169], v[216:219], v[24:27]
	v_mfma_f32_16x16x32_bf16 v[12:15], v[158:161], v[224:227], v[12:15]
	v_mfma_f32_16x16x32_bf16 v[8:11], v[166:169], v[224:227], v[8:11]
	v_mfma_f32_16x16x32_bf16 v[60:63], v[162:165], v[182:185], v[60:63]
	v_mfma_f32_16x16x32_bf16 v[56:59], v[170:173], v[182:185], v[56:59]
	v_mfma_f32_16x16x32_bf16 v[44:47], v[162:165], v[212:215], v[44:47]
	v_mfma_f32_16x16x32_bf16 v[40:43], v[170:173], v[212:215], v[40:43]
	v_mfma_f32_16x16x32_bf16 v[28:31], v[162:165], v[220:223], v[28:31]
	v_mfma_f32_16x16x32_bf16 v[24:27], v[170:173], v[220:223], v[24:27]
	v_mfma_f32_16x16x32_bf16 v[12:15], v[162:165], v[228:231], v[12:15]
	v_mfma_f32_16x16x32_bf16 v[8:11], v[170:173], v[228:231], v[8:11]
	s_setprio 0
	s_barrier
	s_add_i32 s18, s19, s87
	v_lshl_add_u64 v[142:143], v[248:249], 0, s[82:83]
	s_mov_b32 m0, s18
	s_nop 0
	global_load_lds_dwordx4 v[142:143], off
	v_lshl_add_u64 v[142:143], v[192:193], 0, s[82:83]
	s_add_i32 m0, s18, 0x2000
	s_nop 0
	global_load_lds_dwordx4 v[142:143], off
	s_waitcnt vmcnt(6)
	s_barrier
	s_setprio 1
	v_mfma_f32_16x16x32_bf16 v[52:55], v[232:235], v[178:181], v[52:55]
	v_mfma_f32_16x16x32_bf16 v[48:51], v[240:243], v[178:181], v[48:51]
	v_mfma_f32_16x16x32_bf16 v[36:39], v[232:235], v[208:211], v[36:39]
	v_mfma_f32_16x16x32_bf16 v[32:35], v[240:243], v[208:211], v[32:35]
	v_mfma_f32_16x16x32_bf16 v[20:23], v[232:235], v[216:219], v[20:23]
	v_mfma_f32_16x16x32_bf16 v[16:19], v[240:243], v[216:219], v[16:19]
	v_mfma_f32_16x16x32_bf16 v[4:7], v[232:235], v[224:227], v[4:7]
	v_mfma_f32_16x16x32_bf16 v[0:3], v[240:243], v[224:227], v[0:3]
	v_mfma_f32_16x16x32_bf16 v[52:55], v[236:239], v[182:185], v[52:55]
	v_mfma_f32_16x16x32_bf16 v[48:51], v[244:247], v[182:185], v[48:51]
	v_mfma_f32_16x16x32_bf16 v[36:39], v[236:239], v[212:215], v[36:39]
	v_mfma_f32_16x16x32_bf16 v[32:35], v[244:247], v[212:215], v[32:35]
	v_mfma_f32_16x16x32_bf16 v[20:23], v[236:239], v[220:223], v[20:23]
	v_mfma_f32_16x16x32_bf16 v[16:19], v[244:247], v[220:223], v[16:19]
	v_mfma_f32_16x16x32_bf16 v[4:7], v[236:239], v[228:231], v[4:7]
	v_mfma_f32_16x16x32_bf16 v[0:3], v[244:247], v[228:231], v[0:3]
	s_setprio 0
	s_add_u32 vcc_lo, vcc_lo, 0x100
	s_addc_u32 vcc_hi, vcc_hi, 0
	v_lshl_add_u64 v[136:137], v[136:137], 0, s[84:85]
	v_lshl_add_u64 v[134:135], v[134:135], 0, s[84:85]
	s_cmp_ge_u32 s62, s76
	s_mov_b32 s50, s62
	s_barrier
	s_cbranch_scc0 .LBB0_1076
	s_and_b64 vcc, exec, s[4:5]
	s_cbranch_vccnz .LBB0_1064
	v_mov_b32_e32 v0, 0
	s_mov_b32 s86, s79
	s_mov_b32 s33, s67
	s_mov_b64 s[48:49], s[96:97]
	s_mov_b64 s[0:1], s[6:7]
	s_mov_b32 s64, s78
	v_mov_b32_e32 v1, v0
	v_mov_b32_e32 v2, v0
	v_mov_b32_e32 v3, v0
	v_mov_b32_e32 v4, v0
	v_mov_b32_e32 v5, v0
	v_mov_b32_e32 v6, v0
	v_mov_b32_e32 v7, v0
	v_mov_b32_e32 v16, v0
	v_mov_b32_e32 v17, v0
	v_mov_b32_e32 v18, v0
	v_mov_b32_e32 v19, v0
	v_mov_b32_e32 v20, v0
	v_mov_b32_e32 v21, v0
	v_mov_b32_e32 v22, v0
	v_mov_b32_e32 v23, v0
	v_mov_b32_e32 v32, v0
	v_mov_b32_e32 v33, v0
	v_mov_b32_e32 v34, v0
	v_mov_b32_e32 v35, v0
	v_mov_b32_e32 v36, v0
	v_mov_b32_e32 v37, v0
	v_mov_b32_e32 v38, v0
	v_mov_b32_e32 v39, v0
	v_mov_b32_e32 v48, v0
	v_mov_b32_e32 v49, v0
	v_mov_b32_e32 v50, v0
	v_mov_b32_e32 v51, v0
	v_mov_b32_e32 v52, v0
	v_mov_b32_e32 v53, v0
	v_mov_b32_e32 v54, v0
	v_mov_b32_e32 v55, v0
	v_mov_b32_e32 v8, v0
	v_mov_b32_e32 v9, v0
	v_mov_b32_e32 v10, v0
	v_mov_b32_e32 v11, v0
	v_mov_b32_e32 v12, v0
	v_mov_b32_e32 v13, v0
	v_mov_b32_e32 v14, v0
	v_mov_b32_e32 v15, v0
	v_mov_b32_e32 v24, v0
	v_mov_b32_e32 v25, v0
	v_mov_b32_e32 v26, v0
	v_mov_b32_e32 v27, v0
	v_mov_b32_e32 v28, v0
	v_mov_b32_e32 v29, v0
	v_mov_b32_e32 v30, v0
	v_mov_b32_e32 v31, v0
	v_mov_b32_e32 v40, v0
	v_mov_b32_e32 v41, v0
	v_mov_b32_e32 v42, v0
	v_mov_b32_e32 v43, v0
	v_mov_b32_e32 v44, v0
	v_mov_b32_e32 v45, v0
	v_mov_b32_e32 v46, v0
	v_mov_b32_e32 v47, v0
	v_mov_b32_e32 v56, v0
	v_mov_b32_e32 v57, v0
	v_mov_b32_e32 v58, v0
	v_mov_b32_e32 v59, v0
	v_mov_b32_e32 v60, v0
	v_mov_b32_e32 v61, v0
	v_mov_b32_e32 v62, v0
	v_mov_b32_e32 v63, v0
	v_mov_b32_e32 v64, v0
	v_mov_b32_e32 v65, v0
	v_mov_b32_e32 v66, v0
	v_mov_b32_e32 v67, v0
	v_mov_b32_e32 v68, v0
	v_mov_b32_e32 v69, v0
	v_mov_b32_e32 v70, v0
	v_mov_b32_e32 v71, v0
	v_mov_b32_e32 v116, v0
	v_mov_b32_e32 v117, v0
	v_mov_b32_e32 v118, v0
	v_mov_b32_e32 v119, v0
	v_mov_b32_e32 v120, v0
	v_mov_b32_e32 v121, v0
	v_mov_b32_e32 v122, v0
	v_mov_b32_e32 v123, v0
	v_mov_b32_e32 v72, v0
	v_mov_b32_e32 v73, v0
	v_mov_b32_e32 v74, v0
	v_mov_b32_e32 v75, v0
	v_mov_b32_e32 v80, v0
	v_mov_b32_e32 v81, v0
	v_mov_b32_e32 v82, v0
	v_mov_b32_e32 v83, v0
	v_mov_b32_e32 v84, v0
	v_mov_b32_e32 v85, v0
	v_mov_b32_e32 v86, v0
	v_mov_b32_e32 v87, v0
	v_mov_b32_e32 v100, v0
	v_mov_b32_e32 v101, v0
	v_mov_b32_e32 v102, v0
	v_mov_b32_e32 v103, v0
	v_mov_b32_e32 v96, v0
	v_mov_b32_e32 v97, v0
	v_mov_b32_e32 v98, v0
	v_mov_b32_e32 v99, v0
	v_mov_b32_e32 v112, v0
	v_mov_b32_e32 v113, v0
	v_mov_b32_e32 v114, v0
	v_mov_b32_e32 v115, v0
	v_mov_b32_e32 v124, v0
	v_mov_b32_e32 v125, v0
	v_mov_b32_e32 v126, v0
	v_mov_b32_e32 v127, v0
	v_mov_b32_e32 v108, v0
	v_mov_b32_e32 v109, v0
	v_mov_b32_e32 v110, v0
	v_mov_b32_e32 v111, v0
	v_mov_b32_e32 v92, v0
	v_mov_b32_e32 v93, v0
	v_mov_b32_e32 v94, v0
	v_mov_b32_e32 v95, v0
	v_mov_b32_e32 v76, v0
	v_mov_b32_e32 v77, v0
	v_mov_b32_e32 v78, v0
	v_mov_b32_e32 v79, v0
	v_mov_b32_e32 v104, v0
	v_mov_b32_e32 v105, v0
	v_mov_b32_e32 v106, v0
	v_mov_b32_e32 v107, v0
	v_mov_b32_e32 v88, v0
	v_mov_b32_e32 v89, v0
	v_mov_b32_e32 v90, v0
	v_mov_b32_e32 v91, v0
	s_branch .LBB0_1064

; #define PG8_STAGE(bufoff, gbase, voff) do { _Pragma("unroll") for (int _i = 0; _i < 2; ++_i) \
;         __builtin_amdgcn_global_load_lds((const unsigned*)((const char*)(gbase) + (voff)[_i]), (LAS unsigned*)(lds + (bufoff) + ldsw + _i * 8192), 16, 0, 0); } while (0)
; #define PG8_LDA(dst, b, h) do { _Pragma("unroll") for (int m = 0; m < 4; ++m) _Pragma("unroll") for (int k = 0; k < 2; ++k) dst[m][k] = *(const LAS bf16x8*)(lds + PG8_SA(b, h) + aoff + m * 2048 + k * 1024); } while (0)
; #define PG8_LDB(dst, b, h) do { _Pragma("unroll") for (int n = 0; n < 2; ++n) _Pragma("unroll") for (int k = 0; k < 2; ++k) dst[n][k] = *(const LAS bf16x8*)(lds + PG8_SB(b, h) + boff + n * 2048 + k * 1024); } while (0)
; #define PG8_MMA(ai, bj, At, Bt) do { __builtin_amdgcn_s_setprio(1); _Pragma("unroll") for (int m = 0; m < 4; ++m) _Pragma("unroll") for (int n = 0; n < 2; ++n) _Pragma("unroll") for (int k = 0; k < 2; ++k) \
;         acc[ai][bj][m][n] = __builtin_amdgcn_mfma_f32_16x16x32_bf16(Bt[n][k], At[m][k], acc[ai][bj][m][n], 0, 0, 0); __builtin_amdgcn_s_setprio(0); } while (0)
; #define PG8_WAIT_L(n) asm volatile("s_waitcnt lgkmcnt(" #n ")" ::: "memory")
; #define PG8_BAR __builtin_amdgcn_s_barrier()
; #define PG8_SCHED __builtin_amdgcn_sched_barrier(0)
; template <class Epi, class Sched>
; __device__ __forceinline__ void gemm_phase(LAS unsigned char* lds, const Gemm g, const Sched& S, const Epi& E) {
;     ...
;             const char* a1 = cA + (size_t)(t + 1) * kstep;
;             const char* a2 = last ? nA : cA + (size_t)(t + 2) * kstep; const char* b2 = last ? nB : cB + (size_t)(t + 2) * kstep;
;             const char* a3 = a2 + kstep; const char* b3 = b2 + kstep;
;             PG8_LDB(B0, 0, 0); PG8_SCHED; PG8_LDA(At, 0, 0); PG8_STAGE(PG8_SA(1, 1), a1 + hstep, voffA);
;             PG8_WAIT_L(8); PG8_BAR; PG8_WAIT_L(0); PG8_MMA(0, 0, At, B0); PG8_BAR; PG8_SCHED;
;             PG8_LDB(B1, 0, 1); PG8_STAGE(PG8_SB(0, 0), b2, voffB);
;             PG8_BAR; PG8_WAIT_L(0); PG8_MMA(0, 1, At, B1); PG8_BAR;
;             PG8_LDA(At, 0, 1); PG8_STAGE(PG8_SA(0, 0), a2, voffA);
;             PG8_BAR; PG8_WAIT_L(0); PG8_MMA(1, 0, At, B0); PG8_BAR; PG8_SCHED;
.LBB0_1159:
	s_add_i32 s8, s26, 2
	s_mov_b32 s9, s81
	s_or_b32 s80, s26, 1
	s_lshl_b64 s[28:29], s[8:9], 7
	s_cmp_lg_u32 s26, s37
	s_cselect_b32 s18, s28, 0
	s_cselect_b32 s9, s29, 0
	s_add_u32 s26, s4, s18
	s_addc_u32 s27, s5, s9
	s_add_i32 s19, 0, 0x10000
	v_add_u32_e32 v142, s19, v132
	ds_read_b128 v[134:137], v142
	ds_read_b128 v[138:141], v142 offset:1024
	ds_read_b128 v[154:157], v142 offset:2048
	ds_read_b128 v[158:161], v142 offset:3072
	s_add_u32 s28, s0, s18
	s_addc_u32 s29, s1, s9
	s_lshl_b64 s[38:39], s[80:81], 7
	s_add_u32 s38, s6, s38
	s_addc_u32 s39, s7, s39
	v_lshl_add_u64 v[142:143], s[38:39], 0, v[144:145]
	s_add_i32 m0, s17, 0xc000
	ds_read_b128 v[162:165], v133
	ds_read_b128 v[166:169], v133 offset:1024
	ds_read_b128 v[170:173], v133 offset:2048
	ds_read_b128 v[174:177], v133 offset:3072
	ds_read_b128 v[178:181], v133 offset:4096
	ds_read_b128 v[182:185], v133 offset:5120
	ds_read_b128 v[208:211], v133 offset:6144
	ds_read_b128 v[212:215], v133 offset:7168
	global_load_lds_dwordx4 v[142:143], off
	v_lshl_add_u64 v[142:143], s[38:39], 0, v[128:129]
	s_add_i32 m0, s17, 0xe000
	s_nop 0
	global_load_lds_dwordx4 v[142:143], off
	s_waitcnt lgkmcnt(8)
	s_barrier
	s_waitcnt lgkmcnt(0)
	s_setprio 1
	v_mfma_f32_16x16x32_bf16 v[124:127], v[134:137], v[162:165], v[124:127]
	v_mfma_f32_16x16x32_bf16 v[120:123], v[154:157], v[162:165], v[120:123]
	v_mfma_f32_16x16x32_bf16 v[116:119], v[134:137], v[170:173], v[116:119]
	v_mfma_f32_16x16x32_bf16 v[112:115], v[154:157], v[170:173], v[112:115]
	v_mfma_f32_16x16x32_bf16 v[104:107], v[134:137], v[178:181], v[104:107]
	v_mfma_f32_16x16x32_bf16 v[96:99], v[154:157], v[178:181], v[96:99]
	v_mfma_f32_16x16x32_bf16 v[88:91], v[134:137], v[208:211], v[88:91]
	v_mfma_f32_16x16x32_bf16 v[80:83], v[154:157], v[208:211], v[80:83]
	v_mfma_f32_16x16x32_bf16 v[124:127], v[138:141], v[166:169], v[124:127]
	v_mfma_f32_16x16x32_bf16 v[120:123], v[158:161], v[166:169], v[120:123]
	v_mfma_f32_16x16x32_bf16 v[116:119], v[138:141], v[174:177], v[116:119]
	v_mfma_f32_16x16x32_bf16 v[112:115], v[158:161], v[174:177], v[112:115]
	v_mfma_f32_16x16x32_bf16 v[104:107], v[138:141], v[182:185], v[104:107]
	v_mfma_f32_16x16x32_bf16 v[96:99], v[158:161], v[182:185], v[96:99]
	v_mfma_f32_16x16x32_bf16 v[88:91], v[138:141], v[212:215], v[88:91]
	v_mfma_f32_16x16x32_bf16 v[80:83], v[158:161], v[212:215], v[80:83]
	s_setprio 0
	s_barrier
	s_add_i32 s9, 0, 0x14000
	v_add_u32_e32 v142, s9, v132
	s_add_i32 s18, s19, s2
	ds_read_b128 v[216:219], v142
	ds_read_b128 v[220:223], v142 offset:1024
	ds_read_b128 v[224:227], v142 offset:2048
	ds_read_b128 v[228:231], v142 offset:3072
	v_lshl_add_u64 v[142:143], s[28:29], 0, v[144:145]
	s_mov_b32 m0, s18
	v_lshl_add_u64 v[186:187], s[28:29], 0, v[128:129]
	global_load_lds_dwordx4 v[142:143], off
	s_add_i32 m0, s18, 0x2000
	s_nop 0
	global_load_lds_dwordx4 v[186:187], off
	s_barrier
	s_waitcnt lgkmcnt(0)
	s_setprio 1
	v_mfma_f32_16x16x32_bf16 v[108:111], v[216:219], v[162:165], v[108:111]
	v_mfma_f32_16x16x32_bf16 v[100:103], v[224:227], v[162:165], v[100:103]
	v_mfma_f32_16x16x32_bf16 v[92:95], v[216:219], v[170:173], v[92:95]
	v_mfma_f32_16x16x32_bf16 v[84:87], v[224:227], v[170:173], v[84:87]
	v_mfma_f32_16x16x32_bf16 v[76:79], v[216:219], v[178:181], v[76:79]
	v_mfma_f32_16x16x32_bf16 v[72:75], v[224:227], v[178:181], v[72:75]
	v_mfma_f32_16x16x32_bf16 v[68:71], v[216:219], v[208:211], v[68:71]
	v_mfma_f32_16x16x32_bf16 v[64:67], v[224:227], v[208:211], v[64:67]
	v_mfma_f32_16x16x32_bf16 v[108:111], v[220:223], v[166:169], v[108:111]
	v_mfma_f32_16x16x32_bf16 v[100:103], v[228:231], v[166:169], v[100:103]
	v_mfma_f32_16x16x32_bf16 v[92:95], v[220:223], v[174:177], v[92:95]
	v_mfma_f32_16x16x32_bf16 v[84:87], v[228:231], v[174:177], v[84:87]
	v_mfma_f32_16x16x32_bf16 v[76:79], v[220:223], v[182:185], v[76:79]
	v_mfma_f32_16x16x32_bf16 v[72:75], v[228:231], v[182:185], v[72:75]
	v_mfma_f32_16x16x32_bf16 v[68:71], v[220:223], v[212:215], v[68:71]
	v_mfma_f32_16x16x32_bf16 v[64:67], v[228:231], v[212:215], v[64:67]
	s_setprio 0
	s_mov_b32 m0, s17
	v_lshl_add_u64 v[192:193], s[26:27], 0, v[144:145]
	s_barrier
	ds_read_b128 v[162:165], v133 offset:16384
	ds_read_b128 v[166:169], v133 offset:17408
	ds_read_b128 v[170:173], v133 offset:18432
	ds_read_b128 v[174:177], v133 offset:19456
	ds_read_b128 v[178:181], v133 offset:20480
	ds_read_b128 v[182:185], v133 offset:21504
	ds_read_b128 v[208:211], v133 offset:22528
	ds_read_b128 v[212:215], v133 offset:23552
	global_load_lds_dwordx4 v[192:193], off
	v_lshl_add_u64 v[232:233], s[26:27], 0, v[128:129]
	s_mov_b32 m0, s30
	s_nop 0
	global_load_lds_dwordx4 v[232:233], off
	s_barrier
	s_waitcnt lgkmcnt(0)
	s_setprio 1
	v_mfma_f32_16x16x32_bf16 v[60:63], v[134:137], v[162:165], v[60:63]
	v_mfma_f32_16x16x32_bf16 v[56:59], v[154:157], v[162:165], v[56:59]
	v_mfma_f32_16x16x32_bf16 v[52:55], v[134:137], v[170:173], v[52:55]
	v_mfma_f32_16x16x32_bf16 v[48:51], v[154:157], v[170:173], v[48:51]
	v_mfma_f32_16x16x32_bf16 v[40:43], v[134:137], v[178:181], v[40:43]
	v_mfma_f32_16x16x32_bf16 v[32:35], v[154:157], v[178:181], v[32:35]
	v_mfma_f32_16x16x32_bf16 v[24:27], v[134:137], v[208:211], v[24:27]
	v_mfma_f32_16x16x32_bf16 v[16:19], v[154:157], v[208:211], v[16:19]
	v_mfma_f32_16x16x32_bf16 v[60:63], v[138:141], v[166:169], v[60:63]
	v_mfma_f32_16x16x32_bf16 v[56:59], v[158:161], v[166:169], v[56:59]
	v_mfma_f32_16x16x32_bf16 v[52:55], v[138:141], v[174:177], v[52:55]
	v_mfma_f32_16x16x32_bf16 v[48:51], v[158:161], v[174:177], v[48:51]
	v_mfma_f32_16x16x32_bf16 v[40:43], v[138:141], v[182:185], v[40:43]
	v_mfma_f32_16x16x32_bf16 v[32:35], v[158:161], v[182:185], v[32:35]
	v_mfma_f32_16x16x32_bf16 v[24:27], v[138:141], v[212:215], v[24:27]
	v_mfma_f32_16x16x32_bf16 v[16:19], v[158:161], v[212:215], v[16:19]
	s_setprio 0
	s_barrier
; #define PG8_STAGE(bufoff, gbase, voff) do { _Pragma("unroll") for (int _i = 0; _i < 2; ++_i) \
;         __builtin_amdgcn_global_load_lds((const unsigned*)((const char*)(gbase) + (voff)[_i]), (LAS unsigned*)(lds + (bufoff) + ldsw + _i * 8192), 16, 0, 0); } while (0)
; #define PG8_LDA(dst, b, h) do { _Pragma("unroll") for (int m = 0; m < 4; ++m) _Pragma("unroll") for (int k = 0; k < 2; ++k) dst[m][k] = *(const LAS bf16x8*)(lds + PG8_SA(b, h) + aoff + m * 2048 + k * 1024); } while (0)
; #define PG8_LDB(dst, b, h) do { _Pragma("unroll") for (int n = 0; n < 2; ++n) _Pragma("unroll") for (int k = 0; k < 2; ++k) dst[n][k] = *(const LAS bf16x8*)(lds + PG8_SB(b, h) + boff + n * 2048 + k * 1024); } while (0)
; #define PG8_MMA(ai, bj, At, Bt) do { __builtin_amdgcn_s_setprio(1); _Pragma("unroll") for (int m = 0; m < 4; ++m) _Pragma("unroll") for (int n = 0; n < 2; ++n) _Pragma("unroll") for (int k = 0; k < 2; ++k) \
;         acc[ai][bj][m][n] = __builtin_amdgcn_mfma_f32_16x16x32_bf16(Bt[n][k], At[m][k], acc[ai][bj][m][n], 0, 0, 0); __builtin_amdgcn_s_setprio(0); } while (0)
; #define PG8_WAIT_V(n) asm volatile("s_waitcnt vmcnt(" #n ")" ::: "memory")
; #define PG8_WAIT_L(n) asm volatile("s_waitcnt lgkmcnt(" #n ")" ::: "memory")
; #define PG8_BAR __builtin_amdgcn_s_barrier()
; #define PG8_SCHED __builtin_amdgcn_sched_barrier(0)
; template <class Epi, class Sched>
; __device__ __forceinline__ void gemm_phase(LAS unsigned char* lds, const Gemm g, const Sched& S, const Epi& E) {
;     ...
;             PG8_STAGE(PG8_SB(0, 1), b2 + hstep, voffB);
;             PG8_WAIT_V(6); PG8_BAR; PG8_MMA(1, 1, At, B1); PG8_BAR;
;             PG8_LDB(B0, 1, 0); PG8_SCHED; PG8_LDA(At, 1, 0); PG8_STAGE(PG8_SA(0, 1), a2 + hstep, voffA);
;             PG8_WAIT_L(8); PG8_BAR; PG8_WAIT_L(0); PG8_MMA(0, 0, At, B0); PG8_BAR; PG8_SCHED;
;             PG8_LDB(B1, 1, 1); PG8_STAGE(PG8_SB(1, 0), b3, voffB);
;             PG8_BAR; PG8_WAIT_L(0); PG8_MMA(0, 1, At, B1); PG8_BAR;
;             PG8_LDA(At, 1, 1); PG8_STAGE(PG8_SA(1, 0), a3, voffA);
;             PG8_BAR; PG8_WAIT_L(0); PG8_MMA(1, 0, At, B0); PG8_BAR; PG8_SCHED;
	s_add_u32 s28, s28, s13
	s_addc_u32 s29, s29, 0
	s_add_i32 s9, s9, s2
	v_lshl_add_u64 v[234:235], s[28:29], 0, v[144:145]
	s_mov_b32 m0, s9
	v_lshl_add_u64 v[236:237], s[28:29], 0, v[128:129]
	global_load_lds_dwordx4 v[234:235], off
	s_add_i32 m0, s9, 0x2000
	s_nop 0
	global_load_lds_dwordx4 v[236:237], off
	s_waitcnt vmcnt(6)
	s_barrier
	s_setprio 1
	v_mfma_f32_16x16x32_bf16 v[44:47], v[216:219], v[162:165], v[44:47]
	v_mfma_f32_16x16x32_bf16 v[36:39], v[224:227], v[162:165], v[36:39]
	v_mfma_f32_16x16x32_bf16 v[28:31], v[216:219], v[170:173], v[28:31]
	v_mfma_f32_16x16x32_bf16 v[20:23], v[224:227], v[170:173], v[20:23]
	v_mfma_f32_16x16x32_bf16 v[12:15], v[216:219], v[178:181], v[12:15]
	v_mfma_f32_16x16x32_bf16 v[8:11], v[224:227], v[178:181], v[8:11]
	v_mfma_f32_16x16x32_bf16 v[4:7], v[216:219], v[208:211], v[4:7]
	v_mfma_f32_16x16x32_bf16 v[0:3], v[224:227], v[208:211], v[0:3]
	v_mfma_f32_16x16x32_bf16 v[44:47], v[220:223], v[166:169], v[44:47]
	v_mfma_f32_16x16x32_bf16 v[36:39], v[228:231], v[166:169], v[36:39]
	v_mfma_f32_16x16x32_bf16 v[28:31], v[220:223], v[174:177], v[28:31]
	v_mfma_f32_16x16x32_bf16 v[20:23], v[228:231], v[174:177], v[20:23]
	v_mfma_f32_16x16x32_bf16 v[12:15], v[220:223], v[182:185], v[12:15]
	v_mfma_f32_16x16x32_bf16 v[8:11], v[228:231], v[182:185], v[8:11]
	v_mfma_f32_16x16x32_bf16 v[4:7], v[220:223], v[212:215], v[4:7]
	v_mfma_f32_16x16x32_bf16 v[0:3], v[228:231], v[212:215], v[0:3]
	s_setprio 0
	s_add_i32 s9, 0, 0x18000
	v_add_u32_e32 v158, s9, v132
	s_barrier
	ds_read_b128 v[134:137], v158
	ds_read_b128 v[138:141], v158 offset:1024
	ds_read_b128 v[154:157], v158 offset:2048
	ds_read_b128 v[158:161], v158 offset:3072
	s_add_u32 s26, s26, s13
	s_addc_u32 s27, s27, 0
	s_mov_b32 m0, s31
	v_lshl_add_u64 v[216:217], s[26:27], 0, v[144:145]
	ds_read_b128 v[162:165], v133 offset:32768
	ds_read_b128 v[166:169], v133 offset:33792
	ds_read_b128 v[170:173], v133 offset:34816
	ds_read_b128 v[174:177], v133 offset:35840
	ds_read_b128 v[178:181], v133 offset:36864
	ds_read_b128 v[182:185], v133 offset:37888
	ds_read_b128 v[208:211], v133 offset:38912
	ds_read_b128 v[212:215], v133 offset:39936
	global_load_lds_dwordx4 v[216:217], off
	v_lshl_add_u64 v[216:217], s[26:27], 0, v[128:129]
	s_mov_b32 m0, s33
	s_nop 0
	global_load_lds_dwordx4 v[216:217], off
	s_waitcnt lgkmcnt(8)
	s_barrier
	s_waitcnt lgkmcnt(0)
	s_setprio 1
	v_mfma_f32_16x16x32_bf16 v[124:127], v[134:137], v[162:165], v[124:127]
	v_mfma_f32_16x16x32_bf16 v[120:123], v[154:157], v[162:165], v[120:123]
	v_mfma_f32_16x16x32_bf16 v[116:119], v[134:137], v[170:173], v[116:119]
	v_mfma_f32_16x16x32_bf16 v[112:115], v[154:157], v[170:173], v[112:115]
	v_mfma_f32_16x16x32_bf16 v[104:107], v[134:137], v[178:181], v[104:107]
	v_mfma_f32_16x16x32_bf16 v[96:99], v[154:157], v[178:181], v[96:99]
	v_mfma_f32_16x16x32_bf16 v[88:91], v[134:137], v[208:211], v[88:91]
	v_mfma_f32_16x16x32_bf16 v[80:83], v[154:157], v[208:211], v[80:83]
	v_mfma_f32_16x16x32_bf16 v[124:127], v[138:141], v[166:169], v[124:127]
	v_mfma_f32_16x16x32_bf16 v[120:123], v[158:161], v[166:169], v[120:123]
	v_mfma_f32_16x16x32_bf16 v[116:119], v[138:141], v[174:177], v[116:119]
	v_mfma_f32_16x16x32_bf16 v[112:115], v[158:161], v[174:177], v[112:115]
	v_mfma_f32_16x16x32_bf16 v[104:107], v[138:141], v[182:185], v[104:107]
	v_mfma_f32_16x16x32_bf16 v[96:99], v[158:161], v[182:185], v[96:99]
	v_mfma_f32_16x16x32_bf16 v[88:91], v[138:141], v[212:215], v[88:91]
	v_mfma_f32_16x16x32_bf16 v[80:83], v[158:161], v[212:215], v[80:83]
	s_setprio 0
	s_barrier
	s_add_i32 s18, 0, 0x1c000
	s_add_i32 s9, s9, s2
	v_add_u32_e32 v228, s18, v132
	v_lshl_add_u64 v[142:143], v[142:143], 0, s[82:83]
	s_mov_b32 m0, s9
	ds_read_b128 v[216:219], v228
	ds_read_b128 v[220:223], v228 offset:1024
	ds_read_b128 v[224:227], v228 offset:2048
	ds_read_b128 v[228:231], v228 offset:3072
	global_load_lds_dwordx4 v[142:143], off
	v_lshl_add_u64 v[142:143], v[186:187], 0, s[82:83]
	s_add_i32 m0, s9, 0x2000
	s_nop 0
	global_load_lds_dwordx4 v[142:143], off
	s_barrier
	s_waitcnt lgkmcnt(0)
	s_setprio 1
	v_mfma_f32_16x16x32_bf16 v[108:111], v[216:219], v[162:165], v[108:111]
	v_mfma_f32_16x16x32_bf16 v[100:103], v[224:227], v[162:165], v[100:103]
	v_mfma_f32_16x16x32_bf16 v[92:95], v[216:219], v[170:173], v[92:95]
	v_mfma_f32_16x16x32_bf16 v[84:87], v[224:227], v[170:173], v[84:87]
	v_mfma_f32_16x16x32_bf16 v[76:79], v[216:219], v[178:181], v[76:79]
	v_mfma_f32_16x16x32_bf16 v[72:75], v[224:227], v[178:181], v[72:75]
	v_mfma_f32_16x16x32_bf16 v[68:71], v[216:219], v[208:211], v[68:71]
	v_mfma_f32_16x16x32_bf16 v[64:67], v[224:227], v[208:211], v[64:67]
	v_mfma_f32_16x16x32_bf16 v[108:111], v[220:223], v[166:169], v[108:111]
	v_mfma_f32_16x16x32_bf16 v[100:103], v[228:231], v[166:169], v[100:103]
	v_mfma_f32_16x16x32_bf16 v[92:95], v[220:223], v[174:177], v[92:95]
	v_mfma_f32_16x16x32_bf16 v[84:87], v[228:231], v[174:177], v[84:87]
	v_mfma_f32_16x16x32_bf16 v[76:79], v[220:223], v[182:185], v[76:79]
	v_mfma_f32_16x16x32_bf16 v[72:75], v[228:231], v[182:185], v[72:75]
	v_mfma_f32_16x16x32_bf16 v[68:71], v[220:223], v[212:215], v[68:71]
	v_mfma_f32_16x16x32_bf16 v[64:67], v[228:231], v[212:215], v[64:67]
	s_setprio 0
	s_mov_b32 m0, s35
	v_lshl_add_u64 v[142:143], v[192:193], 0, s[82:83]
	s_barrier
	ds_read_b128 v[162:165], v133 offset:49152
	ds_read_b128 v[166:169], v133 offset:50176
	ds_read_b128 v[170:173], v133 offset:51200
	ds_read_b128 v[174:177], v133 offset:52224
	ds_read_b128 v[178:181], v133 offset:53248
	ds_read_b128 v[182:185], v133 offset:54272
	ds_read_b128 v[208:211], v133 offset:55296
	ds_read_b128 v[212:215], v133 offset:56320
	global_load_lds_dwordx4 v[142:143], off
	v_lshl_add_u64 v[142:143], v[232:233], 0, s[82:83]
	s_mov_b32 m0, s36
	s_nop 0
	global_load_lds_dwordx4 v[142:143], off
	s_barrier
; #define PG8_STAGE(bufoff, gbase, voff) do { _Pragma("unroll") for (int _i = 0; _i < 2; ++_i) \
;         __builtin_amdgcn_global_load_lds((const unsigned*)((const char*)(gbase) + (voff)[_i]), (LAS unsigned*)(lds + (bufoff) + ldsw + _i * 8192), 16, 0, 0); } while (0)
; #define PG8_MMA(ai, bj, At, Bt) do { __builtin_amdgcn_s_setprio(1); _Pragma("unroll") for (int m = 0; m < 4; ++m) _Pragma("unroll") for (int n = 0; n < 2; ++n) _Pragma("unroll") for (int k = 0; k < 2; ++k) \
;         acc[ai][bj][m][n] = __builtin_amdgcn_mfma_f32_16x16x32_bf16(Bt[n][k], At[m][k], acc[ai][bj][m][n], 0, 0, 0); __builtin_amdgcn_s_setprio(0); } while (0)
; #define PG8_WAIT_V(n) asm volatile("s_waitcnt vmcnt(" #n ")" ::: "memory")
; #define PG8_WAIT_L(n) asm volatile("s_waitcnt lgkmcnt(" #n ")" ::: "memory")
; #define PG8_BAR __builtin_amdgcn_s_barrier()
; #define PG8_SCHED __builtin_amdgcn_sched_barrier(0)
;     __device__ __forceinline__ void operator()(const f32x4 (&acc)[2][2][4][2], const Unit& u, int wr, int wc, int fr, int fq) const {
;         const int row0 = u.pm * BM + wr * 64 + fr, col0 = u.pn * BM + wc * 32 + 4 * fq;
; #pragma unroll
;         for (int ai = 0; ai < 2; ++ai)
; #pragma unroll
;             for (int m = 0; m < 4; ++m) { float* rowp = C + (size_t)(row0 + ai * HALF + m * 16) * ldc + col0;
; #pragma unroll
;                 for (int bj = 0; bj < 2; ++bj)
; #pragma unroll
;                     for (int n = 0; n < 2; ++n) *(f32x4*)(rowp + bj * HALF + n * 16) = acc[ai][bj][m][n]; }
; template <class Epi, class Sched>
; __device__ __forceinline__ void gemm_phase(LAS unsigned char* lds, const Gemm g, const Sched& S, const Epi& E) {
;     ...
;             PG8_BAR; PG8_WAIT_L(0); PG8_MMA(1, 0, At, B0); PG8_BAR; PG8_SCHED;
;             PG8_STAGE(PG8_SB(1, 1), b3 + hstep, voffB);
;             PG8_WAIT_V(6); PG8_BAR; PG8_MMA(1, 1, At, B1); PG8_BAR;
	s_waitcnt lgkmcnt(0)
	s_setprio 1
	v_mfma_f32_16x16x32_bf16 v[60:63], v[134:137], v[162:165], v[60:63]
	v_mfma_f32_16x16x32_bf16 v[56:59], v[154:157], v[162:165], v[56:59]
	v_mfma_f32_16x16x32_bf16 v[52:55], v[134:137], v[170:173], v[52:55]
	v_mfma_f32_16x16x32_bf16 v[48:51], v[154:157], v[170:173], v[48:51]
	v_mfma_f32_16x16x32_bf16 v[40:43], v[134:137], v[178:181], v[40:43]
	v_mfma_f32_16x16x32_bf16 v[32:35], v[154:157], v[178:181], v[32:35]
	v_mfma_f32_16x16x32_bf16 v[24:27], v[134:137], v[208:211], v[24:27]
	v_mfma_f32_16x16x32_bf16 v[16:19], v[154:157], v[208:211], v[16:19]
	v_mfma_f32_16x16x32_bf16 v[60:63], v[138:141], v[166:169], v[60:63]
	v_mfma_f32_16x16x32_bf16 v[56:59], v[158:161], v[166:169], v[56:59]
	v_mfma_f32_16x16x32_bf16 v[52:55], v[138:141], v[174:177], v[52:55]
	v_mfma_f32_16x16x32_bf16 v[48:51], v[158:161], v[174:177], v[48:51]
	v_mfma_f32_16x16x32_bf16 v[40:43], v[138:141], v[182:185], v[40:43]
	v_mfma_f32_16x16x32_bf16 v[32:35], v[158:161], v[182:185], v[32:35]
	v_mfma_f32_16x16x32_bf16 v[24:27], v[138:141], v[212:215], v[24:27]
	v_mfma_f32_16x16x32_bf16 v[16:19], v[158:161], v[212:215], v[16:19]
	s_setprio 0
	s_barrier
	s_add_i32 s9, s18, s2
	v_lshl_add_u64 v[134:135], v[234:235], 0, s[82:83]
	s_mov_b32 m0, s9
	s_nop 0
	global_load_lds_dwordx4 v[134:135], off
	v_lshl_add_u64 v[134:135], v[236:237], 0, s[82:83]
	s_add_i32 m0, s9, 0x2000
	s_nop 0
	global_load_lds_dwordx4 v[134:135], off
	s_waitcnt vmcnt(6)
	s_barrier
	s_setprio 1
	v_mfma_f32_16x16x32_bf16 v[44:47], v[216:219], v[162:165], v[44:47]
	v_mfma_f32_16x16x32_bf16 v[36:39], v[224:227], v[162:165], v[36:39]
	v_mfma_f32_16x16x32_bf16 v[28:31], v[216:219], v[170:173], v[28:31]
	v_mfma_f32_16x16x32_bf16 v[20:23], v[224:227], v[170:173], v[20:23]
	v_mfma_f32_16x16x32_bf16 v[12:15], v[216:219], v[178:181], v[12:15]
	v_mfma_f32_16x16x32_bf16 v[8:11], v[224:227], v[178:181], v[8:11]
	v_mfma_f32_16x16x32_bf16 v[4:7], v[216:219], v[208:211], v[4:7]
	v_mfma_f32_16x16x32_bf16 v[0:3], v[224:227], v[208:211], v[0:3]
	v_mfma_f32_16x16x32_bf16 v[44:47], v[220:223], v[166:169], v[44:47]
	v_mfma_f32_16x16x32_bf16 v[36:39], v[228:231], v[166:169], v[36:39]
	v_mfma_f32_16x16x32_bf16 v[28:31], v[220:223], v[174:177], v[28:31]
	v_mfma_f32_16x16x32_bf16 v[20:23], v[228:231], v[174:177], v[20:23]
	v_mfma_f32_16x16x32_bf16 v[12:15], v[220:223], v[182:185], v[12:15]
	v_mfma_f32_16x16x32_bf16 v[8:11], v[228:231], v[182:185], v[8:11]
	v_mfma_f32_16x16x32_bf16 v[4:7], v[220:223], v[212:215], v[4:7]
	v_mfma_f32_16x16x32_bf16 v[0:3], v[228:231], v[212:215], v[0:3]
	s_setprio 0
	s_cmp_ge_u32 s8, s23
	s_mov_b32 s26, s8
	s_barrier
	s_cbranch_scc0 .LBB0_1159
	v_readlane_b32 s0, v251, 44
	v_readlane_b32 s4, v253, 49
	v_readlane_b32 s2, v251, 46
	v_readlane_b32 s5, v253, 50
	s_add_u32 s0, s4, s0
	v_add_u32_e32 v128, s2, v131
	v_readlane_b32 s2, v251, 48
	s_addc_u32 s1, s5, 0
	s_add_u32 s0, s0, 0x21fb4000
	v_lshl_or_b32 v129, v130, 2, s2
	v_or_b32_e32 v132, s34, v129
	v_ashrrev_i32_e32 v129, 31, v128
	s_addc_u32 s1, s1, 0
	v_lshlrev_b64 v[130:131], 12, v[128:129]
	v_lshl_add_u64 v[130:131], s[0:1], 0, v[130:131]
	v_lshlrev_b32_e32 v144, 2, v132
	v_lshl_add_u64 v[130:131], v[130:131], 0, v[144:145]
	global_store_dwordx4 v[130:131], v[124:127], off
	global_store_dwordx4 v[130:131], v[120:123], off offset:64
	global_store_dwordx4 v[130:131], v[108:111], off offset:512
	global_store_dwordx4 v[130:131], v[100:103], off offset:576
	s_cmpk_lt_u32 s15, 0x100
	s_nop 0
	v_or_b32_e32 v100, 16, v128
	v_ashrrev_i32_e32 v101, 31, v100
	v_lshlrev_b64 v[100:101], 12, v[100:101]
	v_lshl_add_u64 v[100:101], s[0:1], 0, v[100:101]
	v_lshl_add_u64 v[100:101], v[100:101], 0, v[144:145]
	global_store_dwordx4 v[100:101], v[116:119], off
	global_store_dwordx4 v[100:101], v[112:115], off offset:64
	global_store_dwordx4 v[100:101], v[92:95], off offset:512
	global_store_dwordx4 v[100:101], v[84:87], off offset:576
	s_nop 1
	v_or_b32_e32 v84, 32, v128
	v_ashrrev_i32_e32 v85, 31, v84
	v_lshlrev_b64 v[84:85], 12, v[84:85]
	v_lshl_add_u64 v[84:85], s[0:1], 0, v[84:85]
	v_lshl_add_u64 v[84:85], v[84:85], 0, v[144:145]
	global_store_dwordx4 v[84:85], v[104:107], off
	global_store_dwordx4 v[84:85], v[96:99], off offset:64
	global_store_dwordx4 v[84:85], v[76:79], off offset:512
	global_store_dwordx4 v[84:85], v[72:75], off offset:576
	s_nop 1
	v_or_b32_e32 v72, 48, v128
	v_ashrrev_i32_e32 v73, 31, v72
	v_lshlrev_b64 v[72:73], 12, v[72:73]
	v_lshl_add_u64 v[72:73], s[0:1], 0, v[72:73]
	v_lshl_add_u64 v[72:73], v[72:73], 0, v[144:145]
	global_store_dwordx4 v[72:73], v[88:91], off
	global_store_dwordx4 v[72:73], v[80:83], off offset:64
	global_store_dwordx4 v[72:73], v[68:71], off offset:512
	global_store_dwordx4 v[72:73], v[64:67], off offset:576
	s_mov_b64 s[0:1], 0x80000
	s_nop 0
	v_add_co_u32_e32 v66, vcc, s20, v130
	v_lshl_add_u64 v[64:65], v[130:131], 0, s[0:1]
	s_nop 0
	v_addc_co_u32_e32 v67, vcc, 0, v131, vcc
	s_mov_b64 s[0:1], 0x90000
	global_store_dwordx4 v[66:67], v[60:63], off
	global_store_dwordx4 v[64:65], v[56:59], off offset:64
	global_store_dwordx4 v[64:65], v[44:47], off offset:512
	global_store_dwordx4 v[64:65], v[36:39], off offset:576
	s_nop 1
	v_lshl_add_u64 v[36:37], v[130:131], 0, s[0:1]
	s_mov_b32 s0, 0x90000
	v_add_co_u32_e32 v38, vcc, s0, v130
	s_mov_b64 s[0:1], 0xa0000
	s_nop 0
	v_addc_co_u32_e32 v39, vcc, 0, v131, vcc
	global_store_dwordx4 v[38:39], v[52:55], off
	global_store_dwordx4 v[36:37], v[48:51], off offset:64
	global_store_dwordx4 v[36:37], v[28:31], off offset:512
	global_store_dwordx4 v[36:37], v[20:23], off offset:576
	s_nop 1
	v_add_co_u32_e32 v22, vcc, s21, v130
	v_lshl_add_u64 v[20:21], v[130:131], 0, s[0:1]
	s_nop 0
	v_addc_co_u32_e32 v23, vcc, 0, v131, vcc
	global_store_dwordx4 v[22:23], v[40:43], off
	global_store_dwordx4 v[20:21], v[32:35], off offset:64
	global_store_dwordx4 v[20:21], v[12:15], off offset:512
	global_store_dwordx4 v[20:21], v[8:11], off offset:576
	s_mov_b64 s[0:1], 0xb0000
	s_nop 0
	v_add_co_u32_e32 v10, vcc, 0xb0000, v130
	v_lshl_add_u64 v[8:9], v[130:131], 0, s[0:1]
	s_nop 0
	v_addc_co_u32_e32 v11, vcc, 0, v131, vcc
	global_store_dwordx4 v[10:11], v[24:27], off
	global_store_dwordx4 v[8:9], v[16:19], off offset:64
	global_store_dwordx4 v[8:9], v[4:7], off offset:512
	global_store_dwordx4 v[8:9], v[0:3], off offset:576
	s_waitcnt vmcnt(0)
	s_cbranch_scc0 .LBB0_1162
	s_barrier
